# GEMM k-loop LDS fragment read hoist distance tuned to two MFMAs ahead (with the two-group NA QK read hoist)
# baseline (speedup 1.0000x reference)
.LBB0_198:
	s_setprio 1
	ds_read_b128 v[140:143], v103
	ds_read_b128 v[144:147], v104 offset:36864
	ds_read_b128 v[148:151], v104 offset:41472
	ds_read_b128 v[192:195], v103 offset:4608
	s_waitcnt lgkmcnt(2)
	v_mfma_f32_32x32x16_bf16 v[48:63], v[140:143], v[144:147], v[48:63]
	global_load_dwordx4 v[108:111], v168, s[98:99] offset:3840
	global_load_dwordx4 v[112:115], v170, s[98:99] offset:3840
	s_waitcnt vmcnt(9)
	ds_write_b128 v105, v[68:71] offset:18432
	s_waitcnt lgkmcnt(2)
	v_mfma_f32_32x32x16_bf16 v[32:47], v[140:143], v[148:151], v[32:47]
	ds_read_b128 v[196:199], v103 offset:32
	ds_read_b128 v[200:203], v104 offset:36896
	global_load_dwordx4 v[116:119], v172, s[98:99] offset:3840
	global_load_dwordx4 v[120:123], v174, s[98:99] offset:3840
	s_waitcnt lgkmcnt(3)
	v_mfma_f32_32x32x16_bf16 v[16:31], v[192:195], v[144:147], v[16:31]
	ds_read_b128 v[204:207], v104 offset:41504
	global_load_dwordx4 v[124:127], v176, s[98:99] offset:3840
	global_load_dwordx4 v[128:131], v178, s[98:99] offset:3840
	s_waitcnt vmcnt(11)
	ds_write_b128 v105, v[84:87] offset:23040
	v_mfma_f32_32x32x16_bf16 v[0:15], v[192:195], v[148:151], v[0:15]
	ds_read_b128 v[208:211], v103 offset:4640
	global_load_dwordx4 v[132:135], v180, s[98:99] offset:3840
	global_load_dwordx4 v[136:139], v182, s[98:99] offset:3840
	s_waitcnt lgkmcnt(3)
	v_mfma_f32_32x32x16_bf16 v[48:63], v[196:199], v[200:203], v[48:63]
	s_waitcnt vmcnt(12)
	ds_write_b128 v105, v[88:91] offset:27648
	s_waitcnt lgkmcnt(3)
	v_mfma_f32_32x32x16_bf16 v[32:47], v[196:199], v[204:207], v[32:47]
	ds_read_b128 v[212:215], v103 offset:64
	ds_read_b128 v[216:219], v104 offset:36928
	s_waitcnt lgkmcnt(3)
	v_mfma_f32_32x32x16_bf16 v[16:31], v[208:211], v[200:203], v[16:31]
	ds_read_b128 v[220:223], v104 offset:41536
	s_waitcnt vmcnt(11)
	ds_write_b128 v105, v[92:95] offset:32256
	v_mfma_f32_32x32x16_bf16 v[0:15], v[208:211], v[204:207], v[0:15]
	ds_read_b128 v[224:227], v103 offset:4672
	s_waitcnt lgkmcnt(3)
	v_mfma_f32_32x32x16_bf16 v[48:63], v[212:215], v[216:219], v[48:63]
	ds_write_b128 v105, v[64:67] offset:55296
	s_waitcnt lgkmcnt(3)
	v_mfma_f32_32x32x16_bf16 v[32:47], v[212:215], v[220:223], v[32:47]
	ds_read_b128 v[228:231], v103 offset:96
	ds_read_b128 v[140:143], v104 offset:36960
	s_waitcnt lgkmcnt(3)
	v_mfma_f32_32x32x16_bf16 v[16:31], v[224:227], v[216:219], v[16:31]
	ds_read_b128 v[144:147], v104 offset:41568
	s_waitcnt vmcnt(10)
	ds_write_b128 v105, v[72:75] offset:59904
	v_mfma_f32_32x32x16_bf16 v[0:15], v[224:227], v[220:223], v[0:15]
	ds_read_b128 v[148:151], v103 offset:4704
	s_waitcnt lgkmcnt(3)
	v_mfma_f32_32x32x16_bf16 v[48:63], v[228:231], v[140:143], v[48:63]
	s_waitcnt vmcnt(9)
	ds_write_b128 v105, v[76:79] offset:64512
	s_waitcnt lgkmcnt(3)
	v_mfma_f32_32x32x16_bf16 v[32:47], v[228:231], v[144:147], v[32:47]
	s_waitcnt lgkmcnt(1)
	v_mfma_f32_32x32x16_bf16 v[16:31], v[148:151], v[140:143], v[16:31]
	s_waitcnt vmcnt(8)
	ds_write_b128 v106, v[80:83] offset:13824
	v_mfma_f32_32x32x16_bf16 v[0:15], v[148:151], v[144:147], v[0:15]
	s_setprio 0
	s_waitcnt lgkmcnt(0)
	s_barrier
	s_setprio 1
	ds_read_b128 v[140:143], v103 offset:18432
	ds_read_b128 v[144:147], v104 offset:55296
	ds_read_b128 v[148:151], v104 offset:59904
	ds_read_b128 v[192:195], v103 offset:23040
	s_waitcnt lgkmcnt(2)
	v_mfma_f32_32x32x16_bf16 v[48:63], v[140:143], v[144:147], v[48:63]
	global_load_dwordx4 v[68:71], v168, s[98:99] offset:3968
	global_load_dwordx4 v[84:87], v170, s[98:99] offset:3968
	s_waitcnt vmcnt(9)
	ds_write_b128 v105, v[108:111]
	s_waitcnt lgkmcnt(2)
	v_mfma_f32_32x32x16_bf16 v[32:47], v[140:143], v[148:151], v[32:47]
	ds_read_b128 v[196:199], v103 offset:18464
	ds_read_b128 v[200:203], v104 offset:55328
	global_load_dwordx4 v[88:91], v172, s[98:99] offset:3968
	global_load_dwordx4 v[92:95], v174, s[98:99] offset:3968
	s_waitcnt lgkmcnt(3)
	v_mfma_f32_32x32x16_bf16 v[16:31], v[192:195], v[144:147], v[16:31]
	ds_read_b128 v[204:207], v104 offset:59936
	global_load_dwordx4 v[64:67], v176, s[98:99] offset:3968
	global_load_dwordx4 v[72:75], v178, s[98:99] offset:3968
	s_waitcnt vmcnt(12)
	ds_write_b128 v105, v[112:115] offset:4608
	v_mfma_f32_32x32x16_bf16 v[0:15], v[192:195], v[148:151], v[0:15]
	ds_read_b128 v[208:211], v103 offset:23072
	global_load_dwordx4 v[76:79], v180, s[98:99] offset:3968
	global_load_dwordx4 v[80:83], v182, s[98:99] offset:3968
	s_waitcnt lgkmcnt(3)
	v_mfma_f32_32x32x16_bf16 v[48:63], v[196:199], v[200:203], v[48:63]
	s_add_u32 s98, s98, 0x100
	s_addc_u32 s99, s99, 0
	s_add_i32 s6, s6, 2
	s_cmp_lt_u32 s6, 11
	s_waitcnt vmcnt(13)
	ds_write_b128 v105, v[116:119] offset:9216
	s_waitcnt lgkmcnt(3)
	v_mfma_f32_32x32x16_bf16 v[32:47], v[196:199], v[204:207], v[32:47]
	ds_read_b128 v[212:215], v103 offset:18496
	ds_read_b128 v[216:219], v104 offset:55360
	s_waitcnt lgkmcnt(3)
	v_mfma_f32_32x32x16_bf16 v[16:31], v[208:211], v[200:203], v[16:31]
	ds_read_b128 v[220:223], v104 offset:59968
	s_waitcnt vmcnt(12)
	ds_write_b128 v105, v[120:123] offset:13824
	v_mfma_f32_32x32x16_bf16 v[0:15], v[208:211], v[204:207], v[0:15]
	ds_read_b128 v[224:227], v103 offset:23104
	s_waitcnt lgkmcnt(3)
	v_mfma_f32_32x32x16_bf16 v[48:63], v[212:215], v[216:219], v[48:63]
	s_waitcnt vmcnt(11)
	ds_write_b128 v105, v[124:127] offset:36864
	s_waitcnt lgkmcnt(3)
	v_mfma_f32_32x32x16_bf16 v[32:47], v[212:215], v[220:223], v[32:47]
	ds_read_b128 v[228:231], v103 offset:18528
	ds_read_b128 v[140:143], v104 offset:55392
	s_waitcnt lgkmcnt(3)
	v_mfma_f32_32x32x16_bf16 v[16:31], v[224:227], v[216:219], v[16:31]
	ds_read_b128 v[144:147], v104 offset:60000
	s_waitcnt vmcnt(10)
	ds_write_b128 v105, v[128:131] offset:41472
	v_mfma_f32_32x32x16_bf16 v[0:15], v[224:227], v[220:223], v[0:15]
	ds_read_b128 v[148:151], v103 offset:23136
	s_waitcnt lgkmcnt(3)
	v_mfma_f32_32x32x16_bf16 v[48:63], v[228:231], v[140:143], v[48:63]
	s_waitcnt vmcnt(9)
	ds_write_b128 v105, v[132:135] offset:46080
	s_waitcnt lgkmcnt(3)
	v_mfma_f32_32x32x16_bf16 v[32:47], v[228:231], v[144:147], v[32:47]
	s_waitcnt lgkmcnt(1)
	v_mfma_f32_32x32x16_bf16 v[16:31], v[148:151], v[140:143], v[16:31]
	s_waitcnt vmcnt(8)
	ds_write_b128 v105, v[136:139] offset:50688
	v_mfma_f32_32x32x16_bf16 v[0:15], v[148:151], v[144:147], v[0:15]
	s_setprio 0
	s_waitcnt lgkmcnt(0)
	s_barrier
	s_cbranch_scc1 .LBB0_198
	s_setprio 1
	ds_read_b128 v[98:101], v103
	ds_read_b128 v[108:111], v104 offset:36864
	ds_read_b128 v[112:115], v104 offset:41472
	ds_read_b128 v[192:195], v103 offset:4608
	s_waitcnt lgkmcnt(2)
	v_mfma_f32_32x32x16_bf16 v[48:63], v[98:101], v[108:111], v[48:63]
	s_waitcnt vmcnt(7)
	ds_write_b128 v105, v[68:71] offset:18432
	s_waitcnt lgkmcnt(2)
	v_mfma_f32_32x32x16_bf16 v[32:47], v[98:101], v[112:115], v[32:47]
	ds_read_b128 v[196:199], v103 offset:32
	ds_read_b128 v[200:203], v104 offset:36896
	s_waitcnt lgkmcnt(3)
	v_mfma_f32_32x32x16_bf16 v[16:31], v[192:195], v[108:111], v[16:31]
	ds_read_b128 v[204:207], v104 offset:41504
	s_waitcnt vmcnt(6)
	ds_write_b128 v105, v[84:87] offset:23040
	v_mfma_f32_32x32x16_bf16 v[0:15], v[192:195], v[112:115], v[0:15]
	ds_read_b128 v[208:211], v103 offset:4640
	s_waitcnt lgkmcnt(3)
	v_mfma_f32_32x32x16_bf16 v[48:63], v[196:199], v[200:203], v[48:63]
	s_waitcnt vmcnt(5)
	ds_write_b128 v105, v[88:91] offset:27648
	s_waitcnt lgkmcnt(3)
	v_mfma_f32_32x32x16_bf16 v[32:47], v[196:199], v[204:207], v[32:47]
	ds_read_b128 v[212:215], v103 offset:64
	ds_read_b128 v[216:219], v104 offset:36928
	s_waitcnt lgkmcnt(3)
	v_mfma_f32_32x32x16_bf16 v[16:31], v[208:211], v[200:203], v[16:31]
	ds_read_b128 v[220:223], v104 offset:41536
	s_waitcnt vmcnt(4)
	ds_write_b128 v105, v[92:95] offset:32256
	v_mfma_f32_32x32x16_bf16 v[0:15], v[208:211], v[204:207], v[0:15]
	ds_read_b128 v[224:227], v103 offset:4672
	s_waitcnt lgkmcnt(3)
	v_mfma_f32_32x32x16_bf16 v[48:63], v[212:215], v[216:219], v[48:63]
	s_waitcnt vmcnt(3)
	ds_write_b128 v105, v[64:67] offset:55296
	s_waitcnt lgkmcnt(3)
	v_mfma_f32_32x32x16_bf16 v[32:47], v[212:215], v[220:223], v[32:47]
	ds_read_b128 v[228:231], v103 offset:96
	ds_read_b128 v[98:101], v104 offset:36960
	s_waitcnt lgkmcnt(3)
	v_mfma_f32_32x32x16_bf16 v[16:31], v[224:227], v[216:219], v[16:31]
	ds_read_b128 v[108:111], v104 offset:41568
	s_waitcnt vmcnt(2)
	ds_write_b128 v105, v[72:75] offset:59904
	v_mfma_f32_32x32x16_bf16 v[0:15], v[224:227], v[220:223], v[0:15]
	ds_read_b128 v[112:115], v103 offset:4704
	s_waitcnt lgkmcnt(3)
	v_mfma_f32_32x32x16_bf16 v[48:63], v[228:231], v[98:101], v[48:63]
	s_waitcnt vmcnt(1)
	ds_write_b128 v105, v[76:79] offset:64512
	s_waitcnt lgkmcnt(3)
	v_mfma_f32_32x32x16_bf16 v[32:47], v[228:231], v[108:111], v[32:47]
	s_waitcnt lgkmcnt(1)
	v_mfma_f32_32x32x16_bf16 v[16:31], v[112:115], v[98:101], v[16:31]
	s_waitcnt vmcnt(0)
	ds_write_b128 v106, v[80:83] offset:13824
	v_mfma_f32_32x32x16_bf16 v[0:15], v[112:115], v[108:111], v[0:15]
	s_setprio 0
	s_waitcnt lgkmcnt(0)
	s_barrier
	s_setprio 1
	ds_read_b128 v[64:67], v103 offset:18432
	ds_read_b128 v[68:71], v104 offset:55296
	ds_read_b128 v[72:75], v104 offset:59904
	ds_read_b128 v[192:195], v103 offset:23040
	s_waitcnt lgkmcnt(2)
	v_mfma_f32_32x32x16_bf16 v[48:63], v[64:67], v[68:71], v[48:63]
	s_waitcnt lgkmcnt(1)
	v_mfma_f32_32x32x16_bf16 v[32:47], v[64:67], v[72:75], v[32:47]
	ds_read_b128 v[196:199], v103 offset:18464
	ds_read_b128 v[200:203], v104 offset:55328
	s_waitcnt lgkmcnt(2)
	v_mfma_f32_32x32x16_bf16 v[16:31], v[192:195], v[68:71], v[16:31]
	ds_read_b128 v[204:207], v104 offset:59936
	v_mfma_f32_32x32x16_bf16 v[0:15], v[192:195], v[72:75], v[0:15]
	ds_read_b128 v[208:211], v103 offset:23072
	s_waitcnt lgkmcnt(2)
	v_mfma_f32_32x32x16_bf16 v[48:63], v[196:199], v[200:203], v[48:63]
	s_waitcnt lgkmcnt(1)
	v_mfma_f32_32x32x16_bf16 v[32:47], v[196:199], v[204:207], v[32:47]
	ds_read_b128 v[212:215], v103 offset:18496
	ds_read_b128 v[216:219], v104 offset:55360
	s_waitcnt lgkmcnt(2)
	v_mfma_f32_32x32x16_bf16 v[16:31], v[208:211], v[200:203], v[16:31]
	ds_read_b128 v[220:223], v104 offset:59968
	v_mfma_f32_32x32x16_bf16 v[0:15], v[208:211], v[204:207], v[0:15]
	ds_read_b128 v[224:227], v103 offset:23104
	s_waitcnt lgkmcnt(2)
	v_mfma_f32_32x32x16_bf16 v[48:63], v[212:215], v[216:219], v[48:63]
	s_waitcnt lgkmcnt(1)
	v_mfma_f32_32x32x16_bf16 v[32:47], v[212:215], v[220:223], v[32:47]
	ds_read_b128 v[228:231], v103 offset:18528
	ds_read_b128 v[64:67], v104 offset:55392
	s_waitcnt lgkmcnt(2)
	v_mfma_f32_32x32x16_bf16 v[16:31], v[224:227], v[216:219], v[16:31]
	ds_read_b128 v[68:71], v104 offset:60000
	v_mfma_f32_32x32x16_bf16 v[0:15], v[224:227], v[220:223], v[0:15]
	ds_read_b128 v[72:75], v103 offset:23136
	s_waitcnt lgkmcnt(2)
	v_mfma_f32_32x32x16_bf16 v[48:63], v[228:231], v[64:67], v[48:63]
	s_waitcnt lgkmcnt(1)
	v_mfma_f32_32x32x16_bf16 v[32:47], v[228:231], v[68:71], v[32:47]
	s_waitcnt lgkmcnt(0)
	v_mfma_f32_32x32x16_bf16 v[16:31], v[72:75], v[64:67], v[16:31]
	v_mfma_f32_32x32x16_bf16 v[0:15], v[72:75], v[68:71], v[0:15]
	s_setprio 0
	s_cmpk_gt_u32 s24, 0xfff
	s_cselect_b64 s[12:13], -1, 0
	s_cmpk_lt_u32 s24, 0x1000
	s_cselect_b64 s[48:49], -1, 0
	s_ashr_i32 s76, s2, 2
	s_cmp_lt_i32 s76, 7
	s_barrier
	s_cbranch_scc1 .LBB0_201
	s_cmp_lg_u32 s76, 7
	s_cselect_b64 s[6:7], -1, 0
	s_cbranch_execz .LBB0_202
	s_branch .LBB0_203

.LBB0_1745:
	s_setprio 1
	ds_read_b128 v[148:151], v144
	ds_read_b128 v[152:155], v145 offset:36864
	ds_read_b128 v[156:159], v145 offset:41472
	ds_read_b128 v[192:195], v144 offset:4608
	s_waitcnt lgkmcnt(2)
	v_mfma_f32_32x32x16_bf16 v[48:63], v[148:151], v[152:155], v[48:63]
	global_load_dwordx4 v[96:99], v160, s[98:99] offset:256
	global_load_dwordx4 v[100:103], v164, s[98:99] offset:256
	s_waitcnt vmcnt(9)
	ds_write_b128 v146, v[64:67] offset:18432
	s_waitcnt lgkmcnt(2)
	v_mfma_f32_32x32x16_bf16 v[32:47], v[148:151], v[156:159], v[32:47]
	ds_read_b128 v[196:199], v144 offset:32
	ds_read_b128 v[200:203], v145 offset:36896
	global_load_dwordx4 v[104:107], v166, s[98:99] offset:256
	global_load_dwordx4 v[108:111], v168, s[98:99] offset:256
	s_waitcnt lgkmcnt(3)
	v_mfma_f32_32x32x16_bf16 v[16:31], v[192:195], v[152:155], v[16:31]
	ds_read_b128 v[204:207], v145 offset:41504
	global_load_dwordx4 v[112:115], v162, s[98:99]
	global_load_dwordx4 v[116:119], v130, s[98:99]
	s_waitcnt vmcnt(12)
	ds_write_b128 v146, v[68:71] offset:23040
	v_mfma_f32_32x32x16_bf16 v[0:15], v[192:195], v[156:159], v[0:15]
	ds_read_b128 v[208:211], v144 offset:4640
	global_load_dwordx4 v[120:123], v170, s[98:99]
	global_load_dwordx4 v[124:127], v172, s[98:99] offset:-128
	s_waitcnt lgkmcnt(3)
	v_mfma_f32_32x32x16_bf16 v[48:63], v[196:199], v[200:203], v[48:63]
	s_waitcnt vmcnt(13)
	ds_write_b128 v146, v[72:75] offset:27648
	s_waitcnt lgkmcnt(3)
	v_mfma_f32_32x32x16_bf16 v[32:47], v[196:199], v[204:207], v[32:47]
	ds_read_b128 v[212:215], v144 offset:64
	ds_read_b128 v[216:219], v145 offset:36928
	s_waitcnt lgkmcnt(3)
	v_mfma_f32_32x32x16_bf16 v[16:31], v[208:211], v[200:203], v[16:31]
	ds_read_b128 v[220:223], v145 offset:41536
	s_waitcnt vmcnt(12)
	ds_write_b128 v146, v[76:79] offset:32256
	v_mfma_f32_32x32x16_bf16 v[0:15], v[208:211], v[204:207], v[0:15]
	ds_read_b128 v[224:227], v144 offset:4672
	s_waitcnt lgkmcnt(3)
	v_mfma_f32_32x32x16_bf16 v[48:63], v[212:215], v[216:219], v[48:63]
	s_waitcnt vmcnt(11)
	ds_write_b128 v146, v[80:83] offset:55296
	s_waitcnt lgkmcnt(3)
	v_mfma_f32_32x32x16_bf16 v[32:47], v[212:215], v[220:223], v[32:47]
	ds_read_b128 v[228:231], v144 offset:96
	ds_read_b128 v[148:151], v145 offset:36960
	s_waitcnt lgkmcnt(3)
	v_mfma_f32_32x32x16_bf16 v[16:31], v[224:227], v[216:219], v[16:31]
	ds_read_b128 v[152:155], v145 offset:41568
	s_waitcnt vmcnt(10)
	ds_write_b128 v146, v[84:87] offset:59904
	v_mfma_f32_32x32x16_bf16 v[0:15], v[224:227], v[220:223], v[0:15]
	ds_read_b128 v[156:159], v144 offset:4704
	s_waitcnt lgkmcnt(3)
	v_mfma_f32_32x32x16_bf16 v[48:63], v[228:231], v[148:151], v[48:63]
	s_waitcnt vmcnt(9)
	ds_write_b128 v146, v[88:91] offset:64512
	s_waitcnt lgkmcnt(3)
	v_mfma_f32_32x32x16_bf16 v[32:47], v[228:231], v[152:155], v[32:47]
	s_waitcnt lgkmcnt(1)
	v_mfma_f32_32x32x16_bf16 v[16:31], v[156:159], v[148:151], v[16:31]
	s_waitcnt vmcnt(8)
	ds_write_b128 v147, v[92:95] offset:13824
	v_mfma_f32_32x32x16_bf16 v[0:15], v[156:159], v[152:155], v[0:15]
	s_setprio 0
	s_waitcnt lgkmcnt(0)
	s_barrier
	s_setprio 1
	ds_read_b128 v[148:151], v144 offset:18432
	ds_read_b128 v[152:155], v145 offset:55296
	ds_read_b128 v[156:159], v145 offset:59904
	ds_read_b128 v[192:195], v144 offset:23040
	s_waitcnt lgkmcnt(2)
	v_mfma_f32_32x32x16_bf16 v[48:63], v[148:151], v[152:155], v[48:63]
	global_load_dwordx4 v[64:67], v160, s[98:99] offset:384
	global_load_dwordx4 v[68:71], v164, s[98:99] offset:384
	s_waitcnt vmcnt(9)
	ds_write_b128 v146, v[96:99]
	s_waitcnt lgkmcnt(2)
	v_mfma_f32_32x32x16_bf16 v[32:47], v[148:151], v[156:159], v[32:47]
	ds_read_b128 v[196:199], v144 offset:18464
	ds_read_b128 v[200:203], v145 offset:55328
	global_load_dwordx4 v[72:75], v166, s[98:99] offset:384
	global_load_dwordx4 v[76:79], v168, s[98:99] offset:384
	s_waitcnt lgkmcnt(3)
	v_mfma_f32_32x32x16_bf16 v[16:31], v[192:195], v[152:155], v[16:31]
	ds_read_b128 v[204:207], v145 offset:59936
	global_load_dwordx4 v[80:83], v162, s[98:99] offset:128
	global_load_dwordx4 v[84:87], v131, s[98:99]
	s_waitcnt vmcnt(12)
	ds_write_b128 v146, v[100:103] offset:4608
	v_mfma_f32_32x32x16_bf16 v[0:15], v[192:195], v[156:159], v[0:15]
	ds_read_b128 v[208:211], v144 offset:23072
	global_load_dwordx4 v[88:91], v170, s[98:99] offset:128
	global_load_dwordx4 v[92:95], v172, s[98:99]
	s_waitcnt lgkmcnt(3)
	v_mfma_f32_32x32x16_bf16 v[48:63], v[196:199], v[200:203], v[48:63]
	s_add_u32 s98, s98, 0x100
	s_addc_u32 s99, s99, 0
	s_add_i32 s0, s0, 2
	s_cmp_lt_u32 s0, 3
	s_waitcnt vmcnt(13)
	ds_write_b128 v146, v[104:107] offset:9216
	s_waitcnt lgkmcnt(3)
	v_mfma_f32_32x32x16_bf16 v[32:47], v[196:199], v[204:207], v[32:47]
	ds_read_b128 v[212:215], v144 offset:18496
	ds_read_b128 v[216:219], v145 offset:55360
	s_waitcnt lgkmcnt(3)
	v_mfma_f32_32x32x16_bf16 v[16:31], v[208:211], v[200:203], v[16:31]
	ds_read_b128 v[220:223], v145 offset:59968
	s_waitcnt vmcnt(12)
	ds_write_b128 v146, v[108:111] offset:13824
	v_mfma_f32_32x32x16_bf16 v[0:15], v[208:211], v[204:207], v[0:15]
	ds_read_b128 v[224:227], v144 offset:23104
	s_waitcnt lgkmcnt(3)
	v_mfma_f32_32x32x16_bf16 v[48:63], v[212:215], v[216:219], v[48:63]
	s_waitcnt vmcnt(11)
	ds_write_b128 v146, v[112:115] offset:36864
	s_waitcnt lgkmcnt(3)
	v_mfma_f32_32x32x16_bf16 v[32:47], v[212:215], v[220:223], v[32:47]
	ds_read_b128 v[228:231], v144 offset:18528
	ds_read_b128 v[148:151], v145 offset:55392
	s_waitcnt lgkmcnt(3)
	v_mfma_f32_32x32x16_bf16 v[16:31], v[224:227], v[216:219], v[16:31]
	ds_read_b128 v[152:155], v145 offset:60000
	s_waitcnt vmcnt(10)
	ds_write_b128 v146, v[116:119] offset:41472
	v_mfma_f32_32x32x16_bf16 v[0:15], v[224:227], v[220:223], v[0:15]
	ds_read_b128 v[156:159], v144 offset:23136
	s_waitcnt lgkmcnt(3)
	v_mfma_f32_32x32x16_bf16 v[48:63], v[228:231], v[148:151], v[48:63]
	s_waitcnt vmcnt(9)
	ds_write_b128 v146, v[120:123] offset:46080
	s_waitcnt lgkmcnt(3)
	v_mfma_f32_32x32x16_bf16 v[32:47], v[228:231], v[152:155], v[32:47]
	s_waitcnt lgkmcnt(1)
	v_mfma_f32_32x32x16_bf16 v[16:31], v[156:159], v[148:151], v[16:31]
	s_waitcnt vmcnt(8)
	ds_write_b128 v146, v[124:127] offset:50688
	v_mfma_f32_32x32x16_bf16 v[0:15], v[156:159], v[152:155], v[0:15]
	s_setprio 0
	s_waitcnt lgkmcnt(0)
	s_barrier
	s_cbranch_scc1 .LBB0_1745
	s_setprio 1
	ds_read_b128 v[96:99], v144
	ds_read_b128 v[100:103], v145 offset:36864
	ds_read_b128 v[104:107], v145 offset:41472
	ds_read_b128 v[192:195], v144 offset:4608
	s_waitcnt lgkmcnt(2)
	v_mfma_f32_32x32x16_bf16 v[48:63], v[96:99], v[100:103], v[48:63]
	s_waitcnt vmcnt(7)
	ds_write_b128 v146, v[64:67] offset:18432
	s_waitcnt lgkmcnt(2)
	v_mfma_f32_32x32x16_bf16 v[32:47], v[96:99], v[104:107], v[32:47]
	ds_read_b128 v[196:199], v144 offset:32
	ds_read_b128 v[200:203], v145 offset:36896
	s_waitcnt lgkmcnt(3)
	v_mfma_f32_32x32x16_bf16 v[16:31], v[192:195], v[100:103], v[16:31]
	ds_read_b128 v[204:207], v145 offset:41504
	s_waitcnt vmcnt(6)
	ds_write_b128 v146, v[68:71] offset:23040
	v_mfma_f32_32x32x16_bf16 v[0:15], v[192:195], v[104:107], v[0:15]
	ds_read_b128 v[208:211], v144 offset:4640
	s_waitcnt lgkmcnt(3)
	v_mfma_f32_32x32x16_bf16 v[48:63], v[196:199], v[200:203], v[48:63]
	s_waitcnt vmcnt(5)
	ds_write_b128 v146, v[72:75] offset:27648
	s_waitcnt lgkmcnt(3)
	v_mfma_f32_32x32x16_bf16 v[32:47], v[196:199], v[204:207], v[32:47]
	ds_read_b128 v[212:215], v144 offset:64
	ds_read_b128 v[216:219], v145 offset:36928
	s_waitcnt lgkmcnt(3)
	v_mfma_f32_32x32x16_bf16 v[16:31], v[208:211], v[200:203], v[16:31]
	ds_read_b128 v[220:223], v145 offset:41536
	s_waitcnt vmcnt(4)
	ds_write_b128 v146, v[76:79] offset:32256
	v_mfma_f32_32x32x16_bf16 v[0:15], v[208:211], v[204:207], v[0:15]
	ds_read_b128 v[224:227], v144 offset:4672
	s_waitcnt lgkmcnt(3)
	v_mfma_f32_32x32x16_bf16 v[48:63], v[212:215], v[216:219], v[48:63]
	s_waitcnt vmcnt(3)
	ds_write_b128 v146, v[80:83] offset:55296
	s_waitcnt lgkmcnt(3)
	v_mfma_f32_32x32x16_bf16 v[32:47], v[212:215], v[220:223], v[32:47]
	ds_read_b128 v[228:231], v144 offset:96
	ds_read_b128 v[96:99], v145 offset:36960
	s_waitcnt lgkmcnt(3)
	v_mfma_f32_32x32x16_bf16 v[16:31], v[224:227], v[216:219], v[16:31]
	ds_read_b128 v[100:103], v145 offset:41568
	s_waitcnt vmcnt(2)
	ds_write_b128 v146, v[84:87] offset:59904
	v_mfma_f32_32x32x16_bf16 v[0:15], v[224:227], v[220:223], v[0:15]
	ds_read_b128 v[104:107], v144 offset:4704
	s_waitcnt lgkmcnt(3)
	v_mfma_f32_32x32x16_bf16 v[48:63], v[228:231], v[96:99], v[48:63]
	s_waitcnt vmcnt(1)
	ds_write_b128 v146, v[88:91] offset:64512
	s_waitcnt lgkmcnt(3)
	v_mfma_f32_32x32x16_bf16 v[32:47], v[228:231], v[100:103], v[32:47]
	s_waitcnt lgkmcnt(1)
	v_mfma_f32_32x32x16_bf16 v[16:31], v[104:107], v[96:99], v[16:31]
	s_waitcnt vmcnt(0)
	ds_write_b128 v147, v[92:95] offset:13824
	v_mfma_f32_32x32x16_bf16 v[0:15], v[104:107], v[100:103], v[0:15]
	s_setprio 0
	s_waitcnt lgkmcnt(0)
	s_barrier
	s_setprio 1
	ds_read_b128 v[64:67], v144 offset:18432
	ds_read_b128 v[68:71], v145 offset:55296
	ds_read_b128 v[72:75], v145 offset:59904
	ds_read_b128 v[192:195], v144 offset:23040
	s_waitcnt lgkmcnt(2)
	v_mfma_f32_32x32x16_bf16 v[48:63], v[64:67], v[68:71], v[48:63]
	s_waitcnt lgkmcnt(1)
	v_mfma_f32_32x32x16_bf16 v[32:47], v[64:67], v[72:75], v[32:47]
	ds_read_b128 v[196:199], v144 offset:18464
	ds_read_b128 v[200:203], v145 offset:55328
	s_waitcnt lgkmcnt(2)
	v_mfma_f32_32x32x16_bf16 v[16:31], v[192:195], v[68:71], v[16:31]
	ds_read_b128 v[204:207], v145 offset:59936
	v_mfma_f32_32x32x16_bf16 v[0:15], v[192:195], v[72:75], v[0:15]
	ds_read_b128 v[208:211], v144 offset:23072
	s_waitcnt lgkmcnt(2)
	v_mfma_f32_32x32x16_bf16 v[48:63], v[196:199], v[200:203], v[48:63]
	s_waitcnt lgkmcnt(1)
	v_mfma_f32_32x32x16_bf16 v[32:47], v[196:199], v[204:207], v[32:47]
	ds_read_b128 v[212:215], v144 offset:18496
	ds_read_b128 v[216:219], v145 offset:55360
	s_waitcnt lgkmcnt(2)
	v_mfma_f32_32x32x16_bf16 v[16:31], v[208:211], v[200:203], v[16:31]
	ds_read_b128 v[220:223], v145 offset:59968
	v_mfma_f32_32x32x16_bf16 v[0:15], v[208:211], v[204:207], v[0:15]
	ds_read_b128 v[224:227], v144 offset:23104
	s_waitcnt lgkmcnt(2)
	v_mfma_f32_32x32x16_bf16 v[48:63], v[212:215], v[216:219], v[48:63]
	s_waitcnt lgkmcnt(1)
	v_mfma_f32_32x32x16_bf16 v[32:47], v[212:215], v[220:223], v[32:47]
	ds_read_b128 v[228:231], v144 offset:18528
	ds_read_b128 v[64:67], v145 offset:55392
	s_waitcnt lgkmcnt(2)
	v_mfma_f32_32x32x16_bf16 v[16:31], v[224:227], v[216:219], v[16:31]
	ds_read_b128 v[68:71], v145 offset:60000
	v_mfma_f32_32x32x16_bf16 v[0:15], v[224:227], v[220:223], v[0:15]
	ds_read_b128 v[72:75], v144 offset:23136
	s_waitcnt lgkmcnt(2)
	v_mfma_f32_32x32x16_bf16 v[48:63], v[228:231], v[64:67], v[48:63]
	s_waitcnt lgkmcnt(1)
	v_mfma_f32_32x32x16_bf16 v[32:47], v[228:231], v[68:71], v[32:47]
	s_waitcnt lgkmcnt(0)
	v_mfma_f32_32x32x16_bf16 v[16:31], v[72:75], v[64:67], v[16:31]
	v_mfma_f32_32x32x16_bf16 v[0:15], v[72:75], v[68:71], v[0:15]
	s_setprio 0
	s_nop 6
	v_cvt_pk_bf16_f32 v32, v32, s0
	s_nop 2
	v_cvt_pk_bf16_f32 v0, v0, s0
	s_barrier
	ds_write_b16 v143, v32 offset:64
	v_cvt_pk_bf16_f32 v32, v49, s0
	ds_write_b16 v143, v0 offset:8768
	v_cvt_pk_bf16_f32 v0, v17, s0
	ds_write_b16 v143, v32 offset:272
	v_cvt_pk_bf16_f32 v32, v33, s0
	ds_write_b16 v143, v0 offset:8976
	v_cvt_pk_bf16_f32 v0, v1, s0
	ds_write_b16 v143, v32 offset:336
	v_cvt_pk_bf16_f32 v32, v50, s0
	ds_write_b16 v143, v0 offset:9040
	v_cvt_pk_bf16_f32 v0, v18, s0
	ds_write_b16 v143, v32 offset:544
	v_cvt_pk_bf16_f32 v32, v34, s0
	ds_write_b16 v143, v0 offset:9248
	v_cvt_pk_bf16_f32 v0, v2, s0
	ds_write_b16 v143, v32 offset:608
	v_cvt_pk_bf16_f32 v32, v51, s0
	ds_write_b16 v143, v0 offset:9312
	v_cvt_pk_bf16_f32 v0, v19, s0
	ds_write_b16 v143, v32 offset:816
	v_cvt_pk_bf16_f32 v32, v35, s0
	ds_write_b16 v143, v0 offset:9520
	v_cvt_pk_bf16_f32 v0, v3, s0
	ds_write_b16 v143, v32 offset:880
	v_cvt_pk_bf16_f32 v32, v52, s0
	ds_write_b16 v143, v0 offset:9584
	v_cvt_pk_bf16_f32 v0, v20, s0
	ds_write_b16 v143, v32 offset:2176
	v_cvt_pk_bf16_f32 v32, v36, s0
	ds_write_b16 v143, v0 offset:10880
	v_cvt_pk_bf16_f32 v0, v4, s0
	ds_write_b16 v143, v32 offset:2240
	v_cvt_pk_bf16_f32 v32, v53, s0
	ds_write_b16 v143, v0 offset:10944
	v_cvt_pk_bf16_f32 v0, v21, s0
	ds_write_b16 v143, v32 offset:2448
	v_cvt_pk_bf16_f32 v32, v37, s0
	ds_write_b16 v143, v0 offset:11152
	v_cvt_pk_bf16_f32 v0, v5, s0
	ds_write_b16 v143, v32 offset:2512
	v_cvt_pk_bf16_f32 v32, v54, s0
	ds_write_b16 v143, v0 offset:11216
	v_cvt_pk_bf16_f32 v0, v22, s0
	ds_write_b16 v143, v32 offset:2720
	v_cvt_pk_bf16_f32 v32, v38, s0
	ds_write_b16 v143, v0 offset:11424
	v_cvt_pk_bf16_f32 v0, v6, s0
	ds_write_b16 v143, v32 offset:2784
	v_cvt_pk_bf16_f32 v32, v55, s0
	ds_write_b16 v143, v0 offset:11488
	v_cvt_pk_bf16_f32 v0, v23, s0
	ds_write_b16 v143, v32 offset:2992
	v_cvt_pk_bf16_f32 v32, v39, s0
	ds_write_b16 v143, v0 offset:11696
	v_cvt_pk_bf16_f32 v0, v7, s0
	ds_write_b16 v143, v32 offset:3056
	v_cvt_pk_bf16_f32 v32, v56, s0
	ds_write_b16 v143, v0 offset:11760
	v_cvt_pk_bf16_f32 v0, v24, s0
	ds_write_b16 v143, v32 offset:4352
	v_cvt_pk_bf16_f32 v32, v40, s0
	ds_write_b16 v143, v0 offset:13056
	v_cvt_pk_bf16_f32 v0, v8, s0
	ds_write_b16 v143, v32 offset:4416
	v_cvt_pk_bf16_f32 v32, v57, s0
	ds_write_b16 v143, v0 offset:13120
	v_cvt_pk_bf16_f32 v0, v25, s0
	ds_write_b16 v143, v32 offset:4624
	v_cvt_pk_bf16_f32 v32, v41, s0
	ds_write_b16 v143, v0 offset:13328
	v_cvt_pk_bf16_f32 v0, v9, s0
	ds_write_b16 v143, v32 offset:4688
	v_cvt_pk_bf16_f32 v32, v58, s0
	ds_write_b16 v143, v0 offset:13392
	v_cvt_pk_bf16_f32 v0, v26, s0
	ds_write_b16 v143, v32 offset:4896
	v_cvt_pk_bf16_f32 v32, v42, s0
	ds_write_b16 v143, v0 offset:13600
	v_cvt_pk_bf16_f32 v0, v10, s0
	ds_write_b16 v143, v32 offset:4960
	v_cvt_pk_bf16_f32 v32, v59, s0
	ds_write_b16 v143, v0 offset:13664
	v_cvt_pk_bf16_f32 v0, v27, s0
	ds_write_b16 v143, v32 offset:5168
	v_cvt_pk_bf16_f32 v32, v43, s0
	ds_write_b16 v143, v0 offset:13872
	v_cvt_pk_bf16_f32 v0, v11, s0
	ds_write_b16 v143, v32 offset:5232
	v_cvt_pk_bf16_f32 v32, v60, s0
	ds_write_b16 v143, v0 offset:13936
	v_cvt_pk_bf16_f32 v0, v28, s0
	ds_write_b16 v143, v32 offset:6528
	v_cvt_pk_bf16_f32 v32, v44, s0
	ds_write_b16 v143, v0 offset:15232
	v_cvt_pk_bf16_f32 v0, v12, s0
	ds_write_b16 v143, v32 offset:6592
	v_cvt_pk_bf16_f32 v32, v61, s0
	ds_write_b16 v143, v0 offset:15296
	v_cvt_pk_bf16_f32 v0, v29, s0
	ds_write_b16 v143, v32 offset:6800
	v_cvt_pk_bf16_f32 v32, v45, s0
	ds_write_b16 v143, v0 offset:15504
	v_cvt_pk_bf16_f32 v0, v13, s0
	ds_write_b16 v143, v32 offset:6864
	v_cvt_pk_bf16_f32 v32, v62, s0
	ds_write_b16 v143, v0 offset:15568
	v_cvt_pk_bf16_f32 v0, v30, s0
	ds_write_b16 v143, v32 offset:7072
	v_cvt_pk_bf16_f32 v32, v46, s0
	ds_write_b16 v143, v0 offset:15776
	v_cvt_pk_bf16_f32 v0, v14, s0
	ds_write_b16 v143, v32 offset:7136
	v_cvt_pk_bf16_f32 v32, v63, s0
	ds_write_b16 v143, v0 offset:15840
	v_cvt_pk_bf16_f32 v0, v31, s0
	v_cvt_pk_bf16_f32 v48, v48, s0
	ds_write_b16 v143, v32 offset:7344
	v_cvt_pk_bf16_f32 v32, v47, s0
	v_cvt_pk_bf16_f32 v16, v16, s0
	ds_write_b16 v143, v0 offset:16048
	v_cvt_pk_bf16_f32 v0, v15, s0
	v_mov_b32_e32 v15, v142
	ds_write_b16 v143, v48
	ds_write_b16 v143, v32 offset:7408
	ds_write_b16 v143, v16 offset:8704
	ds_write_b16 v143, v0 offset:16112
	s_waitcnt lgkmcnt(0)
	s_barrier
	v_mov_b64_e32 v[2:3], s[4:5]
	v_lshlrev_b32_e32 v0, 3, v15
	v_and_b32_e32 v0, 0x78, v0
	v_ashrrev_i32_e32 v1, 4, v15
	v_lshlrev_b32_e32 v128, 1, v0
	v_add_u32_e32 v0, s69, v1
	s_lshl_b32 s16, s26, 10
	v_mad_i64_i32 v[2:3], s[0:1], v0, s66, v[2:3]
	v_lshl_add_u64 v[2:3], s[16:17], 1, v[2:3]
	v_lshl_add_u64 v[2:3], s[22:23], 1, v[2:3]
	v_lshl_add_u64 v[2:3], v[2:3], 0, v[128:129]
	global_load_dwordx4 v[6:9], v[2:3], off
	v_add_co_u32_e32 v80, vcc, 0x18000, v2
	s_nop 1
	v_addc_co_u32_e32 v81, vcc, 0, v3, vcc
	global_load_dwordx4 v[24:27], v[80:81], off
	v_add_co_u32_e32 v80, vcc, 0x30000, v2
	s_nop 1
	v_addc_co_u32_e32 v81, vcc, 0, v3, vcc
	global_load_dwordx4 v[28:31], v[80:81], off
	v_add_co_u32_e32 v80, vcc, 0x48000, v2
	s_nop 1
	v_addc_co_u32_e32 v81, vcc, 0, v3, vcc
	global_load_dwordx4 v[32:35], v[80:81], off
	v_add_co_u32_e32 v80, vcc, 0x60000, v2
	s_nop 1
	v_addc_co_u32_e32 v81, vcc, 0, v3, vcc
	global_load_dwordx4 v[36:39], v[80:81], off
	v_add_co_u32_e32 v80, vcc, 0x78000, v2
	s_nop 1
	v_addc_co_u32_e32 v81, vcc, 0, v3, vcc
	global_load_dwordx4 v[40:43], v[80:81], off
	v_add_co_u32_e32 v80, vcc, 0x90000, v2
	s_nop 1
	v_addc_co_u32_e32 v81, vcc, 0, v3, vcc
	global_load_dwordx4 v[44:47], v[80:81], off
	v_add_co_u32_e32 v80, vcc, 0xa8000, v2
	s_nop 1
	v_addc_co_u32_e32 v81, vcc, 0, v3, vcc
	global_load_dwordx4 v[48:51], v[80:81], off
	v_add_u32_e32 v14, 32, v128
	v_mad_u64_u32 v[2:3], s[0:1], v1, s60, v[14:15]
	ds_read_b128 v[2:5], v2
	v_ashrrev_i32_e32 v1, 31, v0
	v_lshlrev_b64 v[0:1], 11, v[0:1]
	v_lshl_add_u64 v[0:1], s[24:25], 0, v[0:1]
	v_lshl_add_u64 v[16:17], v[0:1], 0, v[128:129]
	v_cndmask_b32_e64 v1, 0, 1, s[50:51]
	v_mov_b32_e32 v0, 0
	v_cmp_ne_u32_e64 s[0:1], 1, v1
	s_andn2_b64 vcc, exec, s[50:51]
	v_mov_b32_e32 v10, 0
	v_mov_b32_e32 v11, 0
	v_mov_b32_e32 v12, 0
	v_mov_b32_e32 v13, 0
	s_cbranch_vccnz .LBB0_1748
	global_load_dwordx4 v[10:13], v[16:17], off
	v_add_co_u32_e32 v80, vcc, 0x8000, v16
	s_nop 1
	v_addc_co_u32_e32 v81, vcc, 0, v17, vcc
	global_load_dwordx4 v[52:55], v[80:81], off
	v_add_co_u32_e32 v80, vcc, 0x10000, v16
	s_nop 1
	v_addc_co_u32_e32 v81, vcc, 0, v17, vcc
	global_load_dwordx4 v[56:59], v[80:81], off
	v_add_co_u32_e32 v80, vcc, 0x18000, v16
	s_nop 1
	v_addc_co_u32_e32 v81, vcc, 0, v17, vcc
	global_load_dwordx4 v[60:63], v[80:81], off
	v_add_co_u32_e32 v80, vcc, 0x20000, v16
	s_nop 1
	v_addc_co_u32_e32 v81, vcc, 0, v17, vcc
	global_load_dwordx4 v[64:67], v[80:81], off
	v_add_co_u32_e32 v80, vcc, 0x28000, v16
	s_nop 1
	v_addc_co_u32_e32 v81, vcc, 0, v17, vcc
	global_load_dwordx4 v[68:71], v[80:81], off
	v_add_co_u32_e32 v80, vcc, 0x30000, v16
	s_nop 1
	v_addc_co_u32_e32 v81, vcc, 0, v17, vcc
	global_load_dwordx4 v[72:75], v[80:81], off
	v_add_co_u32_e32 v80, vcc, 0x38000, v16
	s_nop 1
	v_addc_co_u32_e32 v81, vcc, 0, v17, vcc
	global_load_dwordx4 v[76:79], v[80:81], off

.LBB0_1817:
	s_setprio 1
	ds_read_b128 v[140:143], v103
	ds_read_b128 v[144:147], v104 offset:36864
	ds_read_b128 v[148:151], v104 offset:41472
	ds_read_b128 v[192:195], v103 offset:4608
	s_waitcnt lgkmcnt(2)
	v_mfma_f32_32x32x16_bf16 v[48:63], v[140:143], v[144:147], v[48:63]
	global_load_dwordx4 v[108:111], v168, s[98:99] offset:3840
	global_load_dwordx4 v[112:115], v170, s[98:99] offset:3840
	s_waitcnt vmcnt(9)
	ds_write_b128 v105, v[68:71] offset:18432
	s_waitcnt lgkmcnt(2)
	v_mfma_f32_32x32x16_bf16 v[32:47], v[140:143], v[148:151], v[32:47]
	ds_read_b128 v[196:199], v103 offset:32
	ds_read_b128 v[200:203], v104 offset:36896
	global_load_dwordx4 v[116:119], v172, s[98:99] offset:3840
	global_load_dwordx4 v[120:123], v174, s[98:99] offset:3840
	s_waitcnt lgkmcnt(3)
	v_mfma_f32_32x32x16_bf16 v[16:31], v[192:195], v[144:147], v[16:31]
	ds_read_b128 v[204:207], v104 offset:41504
	global_load_dwordx4 v[124:127], v176, s[98:99] offset:3840
	global_load_dwordx4 v[128:131], v178, s[98:99] offset:3840
	s_waitcnt vmcnt(11)
	ds_write_b128 v105, v[84:87] offset:23040
	v_mfma_f32_32x32x16_bf16 v[0:15], v[192:195], v[148:151], v[0:15]
	ds_read_b128 v[208:211], v103 offset:4640
	global_load_dwordx4 v[132:135], v180, s[98:99] offset:3840
	global_load_dwordx4 v[136:139], v182, s[98:99] offset:3840
	s_waitcnt lgkmcnt(3)
	v_mfma_f32_32x32x16_bf16 v[48:63], v[196:199], v[200:203], v[48:63]
	s_waitcnt vmcnt(12)
	ds_write_b128 v105, v[88:91] offset:27648
	s_waitcnt lgkmcnt(3)
	v_mfma_f32_32x32x16_bf16 v[32:47], v[196:199], v[204:207], v[32:47]
	ds_read_b128 v[212:215], v103 offset:64
	ds_read_b128 v[216:219], v104 offset:36928
	s_waitcnt lgkmcnt(3)
	v_mfma_f32_32x32x16_bf16 v[16:31], v[208:211], v[200:203], v[16:31]
	ds_read_b128 v[220:223], v104 offset:41536
	s_waitcnt vmcnt(11)
	ds_write_b128 v105, v[92:95] offset:32256
	v_mfma_f32_32x32x16_bf16 v[0:15], v[208:211], v[204:207], v[0:15]
	ds_read_b128 v[224:227], v103 offset:4672
	s_waitcnt lgkmcnt(3)
	v_mfma_f32_32x32x16_bf16 v[48:63], v[212:215], v[216:219], v[48:63]
	ds_write_b128 v105, v[64:67] offset:55296
	s_waitcnt lgkmcnt(3)
	v_mfma_f32_32x32x16_bf16 v[32:47], v[212:215], v[220:223], v[32:47]
	ds_read_b128 v[228:231], v103 offset:96
	ds_read_b128 v[140:143], v104 offset:36960
	s_waitcnt lgkmcnt(3)
	v_mfma_f32_32x32x16_bf16 v[16:31], v[224:227], v[216:219], v[16:31]
	ds_read_b128 v[144:147], v104 offset:41568
	s_waitcnt vmcnt(10)
	ds_write_b128 v105, v[72:75] offset:59904
	v_mfma_f32_32x32x16_bf16 v[0:15], v[224:227], v[220:223], v[0:15]
	ds_read_b128 v[148:151], v103 offset:4704
	s_waitcnt lgkmcnt(3)
	v_mfma_f32_32x32x16_bf16 v[48:63], v[228:231], v[140:143], v[48:63]
	s_waitcnt vmcnt(9)
	ds_write_b128 v105, v[76:79] offset:64512
	s_waitcnt lgkmcnt(3)
	v_mfma_f32_32x32x16_bf16 v[32:47], v[228:231], v[144:147], v[32:47]
	s_waitcnt lgkmcnt(1)
	v_mfma_f32_32x32x16_bf16 v[16:31], v[148:151], v[140:143], v[16:31]
	s_waitcnt vmcnt(8)
	ds_write_b128 v106, v[80:83] offset:13824
	v_mfma_f32_32x32x16_bf16 v[0:15], v[148:151], v[144:147], v[0:15]
	s_setprio 0
	s_waitcnt lgkmcnt(0)
	s_barrier
	s_setprio 1
	ds_read_b128 v[140:143], v103 offset:18432
	ds_read_b128 v[144:147], v104 offset:55296
	ds_read_b128 v[148:151], v104 offset:59904
	ds_read_b128 v[192:195], v103 offset:23040
	s_waitcnt lgkmcnt(2)
	v_mfma_f32_32x32x16_bf16 v[48:63], v[140:143], v[144:147], v[48:63]
	global_load_dwordx4 v[68:71], v168, s[98:99] offset:3968
	global_load_dwordx4 v[84:87], v170, s[98:99] offset:3968
	s_waitcnt vmcnt(9)
	ds_write_b128 v105, v[108:111]
	s_waitcnt lgkmcnt(2)
	v_mfma_f32_32x32x16_bf16 v[32:47], v[140:143], v[148:151], v[32:47]
	ds_read_b128 v[196:199], v103 offset:18464
	ds_read_b128 v[200:203], v104 offset:55328
	global_load_dwordx4 v[88:91], v172, s[98:99] offset:3968
	global_load_dwordx4 v[92:95], v174, s[98:99] offset:3968
	s_waitcnt lgkmcnt(3)
	v_mfma_f32_32x32x16_bf16 v[16:31], v[192:195], v[144:147], v[16:31]
	ds_read_b128 v[204:207], v104 offset:59936
	global_load_dwordx4 v[64:67], v176, s[98:99] offset:3968
	global_load_dwordx4 v[72:75], v178, s[98:99] offset:3968
	s_waitcnt vmcnt(12)
	ds_write_b128 v105, v[112:115] offset:4608
	v_mfma_f32_32x32x16_bf16 v[0:15], v[192:195], v[148:151], v[0:15]
	ds_read_b128 v[208:211], v103 offset:23072
	global_load_dwordx4 v[76:79], v180, s[98:99] offset:3968
	global_load_dwordx4 v[80:83], v182, s[98:99] offset:3968
	s_waitcnt lgkmcnt(3)
	v_mfma_f32_32x32x16_bf16 v[48:63], v[196:199], v[200:203], v[48:63]
	s_add_u32 s98, s98, 0x100
	s_addc_u32 s99, s99, 0
	s_add_i32 s10, s10, 2
	s_cmp_lt_u32 s10, 11
	s_waitcnt vmcnt(13)
	ds_write_b128 v105, v[116:119] offset:9216
	s_waitcnt lgkmcnt(3)
	v_mfma_f32_32x32x16_bf16 v[32:47], v[196:199], v[204:207], v[32:47]
	ds_read_b128 v[212:215], v103 offset:18496
	ds_read_b128 v[216:219], v104 offset:55360
	s_waitcnt lgkmcnt(3)
	v_mfma_f32_32x32x16_bf16 v[16:31], v[208:211], v[200:203], v[16:31]
	ds_read_b128 v[220:223], v104 offset:59968
	s_waitcnt vmcnt(12)
	ds_write_b128 v105, v[120:123] offset:13824
	v_mfma_f32_32x32x16_bf16 v[0:15], v[208:211], v[204:207], v[0:15]
	ds_read_b128 v[224:227], v103 offset:23104
	s_waitcnt lgkmcnt(3)
	v_mfma_f32_32x32x16_bf16 v[48:63], v[212:215], v[216:219], v[48:63]
	s_waitcnt vmcnt(11)
	ds_write_b128 v105, v[124:127] offset:36864
	s_waitcnt lgkmcnt(3)
	v_mfma_f32_32x32x16_bf16 v[32:47], v[212:215], v[220:223], v[32:47]
	ds_read_b128 v[228:231], v103 offset:18528
	ds_read_b128 v[140:143], v104 offset:55392
	s_waitcnt lgkmcnt(3)
	v_mfma_f32_32x32x16_bf16 v[16:31], v[224:227], v[216:219], v[16:31]
	ds_read_b128 v[144:147], v104 offset:60000
	s_waitcnt vmcnt(10)
	ds_write_b128 v105, v[128:131] offset:41472
	v_mfma_f32_32x32x16_bf16 v[0:15], v[224:227], v[220:223], v[0:15]
	ds_read_b128 v[148:151], v103 offset:23136
	s_waitcnt lgkmcnt(3)
	v_mfma_f32_32x32x16_bf16 v[48:63], v[228:231], v[140:143], v[48:63]
	s_waitcnt vmcnt(9)
	ds_write_b128 v105, v[132:135] offset:46080
	s_waitcnt lgkmcnt(3)
	v_mfma_f32_32x32x16_bf16 v[32:47], v[228:231], v[144:147], v[32:47]
	s_waitcnt lgkmcnt(1)
	v_mfma_f32_32x32x16_bf16 v[16:31], v[148:151], v[140:143], v[16:31]
	s_waitcnt vmcnt(8)
	ds_write_b128 v105, v[136:139] offset:50688
	v_mfma_f32_32x32x16_bf16 v[0:15], v[148:151], v[144:147], v[0:15]
	s_setprio 0
	s_waitcnt lgkmcnt(0)
	s_barrier
	s_cbranch_scc1 .LBB0_1817
	s_setprio 1
	ds_read_b128 v[98:101], v103
	ds_read_b128 v[108:111], v104 offset:36864
	ds_read_b128 v[112:115], v104 offset:41472
	ds_read_b128 v[192:195], v103 offset:4608
	s_waitcnt lgkmcnt(2)
	v_mfma_f32_32x32x16_bf16 v[48:63], v[98:101], v[108:111], v[48:63]
	s_waitcnt vmcnt(7)
	ds_write_b128 v105, v[68:71] offset:18432
	s_waitcnt lgkmcnt(2)
	v_mfma_f32_32x32x16_bf16 v[32:47], v[98:101], v[112:115], v[32:47]
	ds_read_b128 v[196:199], v103 offset:32
	ds_read_b128 v[200:203], v104 offset:36896
	s_waitcnt lgkmcnt(3)
	v_mfma_f32_32x32x16_bf16 v[16:31], v[192:195], v[108:111], v[16:31]
	ds_read_b128 v[204:207], v104 offset:41504
	s_waitcnt vmcnt(6)
	ds_write_b128 v105, v[84:87] offset:23040
	v_mfma_f32_32x32x16_bf16 v[0:15], v[192:195], v[112:115], v[0:15]
	ds_read_b128 v[208:211], v103 offset:4640
	s_waitcnt lgkmcnt(3)
	v_mfma_f32_32x32x16_bf16 v[48:63], v[196:199], v[200:203], v[48:63]
	s_waitcnt vmcnt(5)
	ds_write_b128 v105, v[88:91] offset:27648
	s_waitcnt lgkmcnt(3)
	v_mfma_f32_32x32x16_bf16 v[32:47], v[196:199], v[204:207], v[32:47]
	ds_read_b128 v[212:215], v103 offset:64
	ds_read_b128 v[216:219], v104 offset:36928
	s_waitcnt lgkmcnt(3)
	v_mfma_f32_32x32x16_bf16 v[16:31], v[208:211], v[200:203], v[16:31]
	ds_read_b128 v[220:223], v104 offset:41536
	s_waitcnt vmcnt(4)
	ds_write_b128 v105, v[92:95] offset:32256
	v_mfma_f32_32x32x16_bf16 v[0:15], v[208:211], v[204:207], v[0:15]
	ds_read_b128 v[224:227], v103 offset:4672
	s_waitcnt lgkmcnt(3)
	v_mfma_f32_32x32x16_bf16 v[48:63], v[212:215], v[216:219], v[48:63]
	s_waitcnt vmcnt(3)
	ds_write_b128 v105, v[64:67] offset:55296
	s_waitcnt lgkmcnt(3)
	v_mfma_f32_32x32x16_bf16 v[32:47], v[212:215], v[220:223], v[32:47]
	ds_read_b128 v[228:231], v104 offset:36960
	ds_read_b128 v[98:101], v103 offset:4704
	s_waitcnt lgkmcnt(3)
	v_mfma_f32_32x32x16_bf16 v[16:31], v[224:227], v[216:219], v[16:31]
	ds_read_b128 v[108:111], v104 offset:41568
	s_waitcnt vmcnt(2)
	ds_write_b128 v105, v[72:75] offset:59904
	v_mfma_f32_32x32x16_bf16 v[0:15], v[224:227], v[220:223], v[0:15]
	ds_read_b128 v[112:115], v103 offset:96
	s_waitcnt lgkmcnt(3)
	v_mfma_f32_32x32x16_bf16 v[16:31], v[98:101], v[228:231], v[16:31]
	s_waitcnt vmcnt(1)
	ds_write_b128 v105, v[76:79] offset:64512
	s_waitcnt lgkmcnt(3)
	v_mfma_f32_32x32x16_bf16 v[0:15], v[98:101], v[108:111], v[0:15]
	s_waitcnt lgkmcnt(1)
	v_mfma_f32_32x32x16_bf16 v[48:63], v[112:115], v[228:231], v[48:63]
	s_waitcnt vmcnt(0)
	ds_write_b128 v106, v[80:83] offset:13824
	v_mfma_f32_32x32x16_bf16 v[32:47], v[112:115], v[108:111], v[32:47]
	s_setprio 0
	s_waitcnt lgkmcnt(0)
	s_barrier
	s_setprio 1
	ds_read_b128 v[64:67], v103 offset:18432
	ds_read_b128 v[68:71], v104 offset:55296
	ds_read_b128 v[72:75], v104 offset:59904
	ds_read_b128 v[192:195], v103 offset:23040
	s_waitcnt lgkmcnt(2)
	v_mfma_f32_32x32x16_bf16 v[48:63], v[64:67], v[68:71], v[48:63]
	s_waitcnt lgkmcnt(1)
	v_mfma_f32_32x32x16_bf16 v[32:47], v[64:67], v[72:75], v[32:47]
	ds_read_b128 v[196:199], v103 offset:18464
	ds_read_b128 v[200:203], v104 offset:55328
	s_waitcnt lgkmcnt(2)
	v_mfma_f32_32x32x16_bf16 v[16:31], v[192:195], v[68:71], v[16:31]
	ds_read_b128 v[204:207], v104 offset:59936
	v_mfma_f32_32x32x16_bf16 v[0:15], v[192:195], v[72:75], v[0:15]
	ds_read_b128 v[208:211], v103 offset:23072
	s_waitcnt lgkmcnt(2)
	v_mfma_f32_32x32x16_bf16 v[48:63], v[196:199], v[200:203], v[48:63]
	s_waitcnt lgkmcnt(1)
	v_mfma_f32_32x32x16_bf16 v[32:47], v[196:199], v[204:207], v[32:47]
	ds_read_b128 v[212:215], v103 offset:18496
	ds_read_b128 v[216:219], v104 offset:55360
	s_waitcnt lgkmcnt(2)
	v_mfma_f32_32x32x16_bf16 v[16:31], v[208:211], v[200:203], v[16:31]
	ds_read_b128 v[220:223], v104 offset:59968
	v_mfma_f32_32x32x16_bf16 v[0:15], v[208:211], v[204:207], v[0:15]
	ds_read_b128 v[224:227], v103 offset:23104
	s_waitcnt lgkmcnt(2)
	v_mfma_f32_32x32x16_bf16 v[48:63], v[212:215], v[216:219], v[48:63]
	s_waitcnt lgkmcnt(1)
	v_mfma_f32_32x32x16_bf16 v[32:47], v[212:215], v[220:223], v[32:47]
	ds_read_b128 v[228:231], v104 offset:55392
	ds_read_b128 v[64:67], v103 offset:23136
	s_waitcnt lgkmcnt(2)
	v_mfma_f32_32x32x16_bf16 v[16:31], v[224:227], v[216:219], v[16:31]
	ds_read_b128 v[68:71], v104 offset:60000
	v_mfma_f32_32x32x16_bf16 v[0:15], v[224:227], v[220:223], v[0:15]
	ds_read_b128 v[72:75], v103 offset:18528
	s_waitcnt lgkmcnt(2)
	v_mfma_f32_32x32x16_bf16 v[16:31], v[64:67], v[228:231], v[16:31]
	s_waitcnt lgkmcnt(1)
	v_mfma_f32_32x32x16_bf16 v[0:15], v[64:67], v[68:71], v[0:15]
	s_waitcnt lgkmcnt(0)
	v_mfma_f32_32x32x16_bf16 v[48:63], v[72:75], v[228:231], v[48:63]
	v_mfma_f32_32x32x16_bf16 v[32:47], v[72:75], v[68:71], v[32:47]
	s_setprio 0
	s_addk_i32 s0, 0xf000
	s_lshr_b32 s10, s0, 10
	s_mulk_i32 s10, 0x1800
	s_addk_i32 s10, 0x1800
	s_and_b64 s[22:23], s[8:9], exec
	s_cselect_b32 s10, 0, s10
	v_mov_b32_e32 v68, v234
	s_barrier
	s_lshl_b64 s[22:23], s[10:11], 2
	s_add_u32 s22, s30, s22
	v_and_b32_e32 v69, 0x5f, v68
	v_or_b32_e32 v64, s21, v69
	s_addc_u32 s23, s31, s23
	v_ashrrev_i32_e32 v65, 31, v64
	v_lshl_add_u64 v[64:65], v[64:65], 2, s[22:23]
	v_lshl_add_u64 v[66:67], v[64:65], 0, s[14:15]
	v_add_co_u32_e32 v64, vcc, s54, v64
	v_lshlrev_b32_e32 v69, 2, v69
	s_nop 0
	v_addc_co_u32_e32 v65, vcc, 0, v65, vcc
	global_load_dword v64, v[64:65], off
	s_nop 0
	global_load_dword v65, v[66:67], off offset:128
	v_lshrrev_b32_e32 v67, 3, v68
	v_lshrrev_b32_e32 v66, 1, v68
	v_and_b32_e32 v67, 4, v67
	v_and_or_b32 v66, v66, s45, v67
	v_mul_lo_u32 v66, v66, s55
	v_add3_u32 v66, 32, v69, v66
	v_add_u32_e32 v67, 0x400, v66
	v_add_u32_e32 v69, 0x1000, v66
	v_add_u32_e32 v70, 0x1400, v66
	v_add_u32_e32 v71, 0x2000, v66
	v_add_u32_e32 v72, 0x2400, v66
	v_add_u32_e32 v73, 0x3000, v66
	v_add_u32_e32 v74, 0x3200, v66
	v_add_u32_e32 v75, 0x3400, v66
	v_add_u32_e32 v76, 0x3600, v66
	v_add_u32_e32 v77, 0x4000, v66
	v_readlane_b32 s80, v251, 39
	v_readlane_b32 s81, v251, 40
	s_lshl_b32 s1, s1, 19
	v_readlane_b32 s82, v251, 41
	v_readlane_b32 s83, v251, 42
	s_mov_b64 s[36:37], s[80:81]
	s_add_u32 s10, s36, s1
	s_mov_b32 s1, s11
	s_mov_b64 s[38:39], s[82:83]
	s_addc_u32 s21, s37, 0
	s_lshl_b64 s[0:1], s[0:1], 12
	s_add_u32 s22, s38, s0
	s_addc_u32 s23, s39, s1
	s_and_b64 s[0:1], s[8:9], exec
	s_cselect_b32 s23, s21, s23
	s_cselect_b32 s22, s10, s22
	s_add_i32 s10, s20, s27
	v_readlane_b32 s84, v251, 43
	v_readlane_b32 s85, v251, 44
	v_readlane_b32 s86, v251, 45
	v_readlane_b32 s87, v251, 46
	v_readlane_b32 s88, v251, 47
	v_readlane_b32 s89, v251, 48
	v_readlane_b32 s90, v251, 49
	v_readlane_b32 s91, v251, 50
	v_readlane_b32 s92, v251, 51
	v_readlane_b32 s93, v251, 52
	v_readlane_b32 s94, v251, 53
	v_readlane_b32 s95, v251, 54
	s_waitcnt vmcnt(1)
	v_mul_f32_e32 v48, v48, v64
	s_waitcnt vmcnt(0)
	v_mul_f32_e32 v32, v32, v65
	v_mul_f32_e32 v16, v16, v64
	v_mul_f32_e32 v0, v0, v65
	v_mul_f32_e32 v49, v49, v64
	v_mul_f32_e32 v33, v33, v65
	v_mul_f32_e32 v50, v50, v64
	v_mul_f32_e32 v34, v34, v65
	v_mul_f32_e32 v51, v51, v64
	v_mul_f32_e32 v35, v35, v65
	v_mul_f32_e32 v52, v52, v64
	v_mul_f32_e32 v36, v36, v65
	v_mul_f32_e32 v53, v53, v64
	v_mul_f32_e32 v37, v37, v65
	v_mul_f32_e32 v54, v54, v64
	v_mul_f32_e32 v38, v38, v65
	v_mul_f32_e32 v55, v55, v64
	v_mul_f32_e32 v39, v39, v65
	v_mul_f32_e32 v56, v56, v64
	v_mul_f32_e32 v40, v40, v65
	v_mul_f32_e32 v57, v57, v64
	v_mul_f32_e32 v41, v41, v65
	v_mul_f32_e32 v58, v58, v64
	v_mul_f32_e32 v42, v42, v65
	v_mul_f32_e32 v59, v59, v64
	v_mul_f32_e32 v43, v43, v65
	v_mul_f32_e32 v60, v60, v64
	v_mul_f32_e32 v44, v44, v65
	v_mul_f32_e32 v61, v61, v64
	v_mul_f32_e32 v45, v45, v65
	v_mul_f32_e32 v62, v62, v64
	v_mul_f32_e32 v46, v46, v65
	v_mul_f32_e32 v63, v63, v64
	v_mul_f32_e32 v47, v47, v65
	ds_write2_b32 v66, v48, v32 offset1:32
	ds_write2_b32 v66, v49, v33 offset0:132 offset1:164
	ds_write2_b32 v67, v50, v34 offset0:8 offset1:40
	ds_write2_b32 v67, v51, v35 offset0:140 offset1:172
	ds_write2_b32 v69, v52, v36 offset0:32 offset1:64
	ds_write2_b32 v69, v53, v37 offset0:164 offset1:196
	ds_write2_b32 v70, v54, v38 offset0:40 offset1:72
	ds_write2_b32 v70, v55, v39 offset0:172 offset1:204
	ds_write2_b32 v71, v56, v40 offset0:64 offset1:96
	ds_write2_b32 v71, v57, v41 offset0:196 offset1:228
	ds_write2_b32 v72, v58, v42 offset0:72 offset1:104
	ds_write2_b32 v72, v59, v43 offset0:204 offset1:236
	ds_write2_b32 v73, v60, v44 offset0:96 offset1:128
	ds_write2_b32 v74, v61, v45 offset0:100 offset1:132
	ds_write2_b32 v75, v62, v46 offset0:104 offset1:136
	ds_write2_b32 v76, v63, v47 offset0:108 offset1:140
	ds_write2_b32 v77, v16, v0 offset0:128 offset1:160
	v_mul_f32_e32 v0, v17, v64
	v_mul_f32_e32 v1, v1, v65
	v_add_u32_e32 v16, 0x4400, v66
	ds_write2_b32 v16, v0, v1 offset0:4 offset1:36
	v_mul_f32_e32 v0, v18, v64
	v_mul_f32_e32 v1, v2, v65
	ds_write2_b32 v16, v0, v1 offset0:136 offset1:168
	v_mul_f32_e32 v0, v19, v64
	v_mul_f32_e32 v1, v3, v65
	v_add_u32_e32 v2, 0x4800, v66
	ds_write2_b32 v2, v0, v1 offset0:12 offset1:44
	v_mul_f32_e32 v0, v20, v64
	v_mul_f32_e32 v1, v4, v65
	v_add_u32_e32 v2, 0x5000, v66
	ds_write2_b32 v2, v0, v1 offset0:160 offset1:192
	v_mul_f32_e32 v0, v21, v64
	v_mul_f32_e32 v1, v5, v65
	v_add_u32_e32 v2, 0x5400, v66
	ds_write2_b32 v2, v0, v1 offset0:36 offset1:68
	v_mul_f32_e32 v0, v22, v64
	v_mul_f32_e32 v1, v6, v65
	ds_write2_b32 v2, v0, v1 offset0:168 offset1:200
	v_mul_f32_e32 v0, v23, v64
	v_mul_f32_e32 v1, v7, v65
	v_add_u32_e32 v2, 0x5800, v66
	ds_write2_b32 v2, v0, v1 offset0:44 offset1:76
	v_mul_f32_e32 v0, v24, v64
	v_mul_f32_e32 v1, v8, v65
	v_add_u32_e32 v2, 0x6000, v66
	ds_write2_b32 v2, v0, v1 offset0:192 offset1:224
	v_mul_f32_e32 v0, v25, v64
	v_mul_f32_e32 v1, v9, v65
	v_add_u32_e32 v2, 0x6400, v66
	ds_write2_b32 v2, v0, v1 offset0:68 offset1:100
	v_mul_f32_e32 v0, v26, v64
	v_mul_f32_e32 v1, v10, v65
	ds_write2_b32 v2, v0, v1 offset0:200 offset1:232
	v_mul_f32_e32 v0, v27, v64
	v_mul_f32_e32 v1, v11, v65
	v_add_u32_e32 v2, 0x6800, v66
	ds_write2_b32 v2, v0, v1 offset0:76 offset1:108
	v_mul_f32_e32 v0, v28, v64
	v_mul_f32_e32 v1, v12, v65
	v_add_u32_e32 v2, 0x7200, v66
	ds_write2_b32 v2, v0, v1 offset0:96 offset1:128
	v_mul_f32_e32 v0, v29, v64
	v_mul_f32_e32 v1, v13, v65
	v_add_u32_e32 v2, 0x7400, v66
	ds_write2_b32 v2, v0, v1 offset0:100 offset1:132
	v_mul_f32_e32 v0, v30, v64
	v_mul_f32_e32 v1, v14, v65
	v_add_u32_e32 v2, 0x7600, v66
	ds_write2_b32 v2, v0, v1 offset0:104 offset1:136
	v_mul_f32_e32 v0, v31, v64
	v_mul_f32_e32 v1, v15, v65
	v_add_u32_e32 v2, 0x7800, v66
	ds_write2_b32 v2, v0, v1 offset0:108 offset1:140
	v_and_b32_e32 v0, 64, v102
	v_add_u32_e32 v0, 64, v0
	v_xor_b32_e32 v1, 1, v102
	v_cmp_lt_i32_e32 vcc, v1, v0
	v_and_b32_e32 v4, 31, v68
	v_lshl_add_u32 v2, v4, 2, s18
	v_cndmask_b32_e32 v1, v102, v1, vcc
	v_lshlrev_b32_e32 v20, 2, v1
	v_xor_b32_e32 v1, 2, v102
	v_cmp_lt_i32_e32 vcc, v1, v0
	v_ashrrev_i32_e32 v14, 5, v68
	v_ashrrev_i32_e32 v3, 31, v2
	v_cndmask_b32_e32 v1, v102, v1, vcc
	v_lshlrev_b32_e32 v21, 2, v1
	v_xor_b32_e32 v1, 4, v102
	v_cmp_lt_i32_e32 vcc, v1, v0
	v_cmp_eq_u32_e64 s[0:1], 0, v4
	v_lshlrev_b64 v[16:17], 2, v[2:3]
	v_cndmask_b32_e32 v1, v102, v1, vcc
	v_lshlrev_b32_e32 v22, 2, v1
	v_xor_b32_e32 v1, 8, v102
	v_cmp_lt_i32_e32 vcc, v1, v0
	v_lshlrev_b32_e32 v3, 4, v4
	v_add_u32_e32 v4, s10, v14
	v_cndmask_b32_e32 v1, v102, v1, vcc
	v_lshlrev_b32_e32 v23, 2, v1
	v_xor_b32_e32 v1, 16, v102
	s_add_i32 s10, s20, s33
	s_add_i32 s20, s20, s34
	v_cmp_lt_i32_e32 vcc, v1, v0
	v_add_u32_e32 v8, s10, v14
	v_add_u32_e32 v12, s20, v14
	v_add_u32_e32 v18, s19, v14
	v_cndmask_b32_e32 v0, v102, v1, vcc
	v_ashrrev_i32_e32 v15, 31, v14
	v_mul_lo_u32 v2, v14, s55
	v_ashrrev_i32_e32 v5, 31, v4
	v_ashrrev_i32_e32 v9, 31, v8
	v_ashrrev_i32_e32 v13, 31, v12
	v_ashrrev_i32_e32 v19, 31, v18
	v_lshlrev_b32_e32 v24, 2, v0
	v_lshlrev_b64 v[0:1], 12, v[14:15]
	v_add3_u32 v25, v2, v3, 32
	v_lshlrev_b32_e32 v2, 1, v4
	v_lshlrev_b64 v[4:5], 12, v[4:5]
	v_lshlrev_b32_e32 v6, 1, v8
	v_lshlrev_b64 v[8:9], 12, v[8:9]
	v_lshlrev_b32_e32 v10, 1, v12
	v_lshlrev_b64 v[12:13], 12, v[12:13]
	v_lshlrev_b64 v[14:15], 12, v[18:19]
	v_lshl_add_u64 v[0:1], v[0:1], 0, v[16:17]
	v_lshl_add_u64 v[4:5], v[4:5], 0, v[16:17]
	v_lshl_add_u64 v[8:9], v[8:9], 0, v[16:17]
	v_lshl_add_u64 v[12:13], v[12:13], 0, v[16:17]
	v_lshl_add_u64 v[14:15], v[14:15], 0, v[16:17]
	v_lshlrev_b32_e32 v16, 1, v18
	v_ashrrev_i32_e32 v3, 31, v2
	v_ashrrev_i32_e32 v7, 31, v6
	v_ashrrev_i32_e32 v11, 31, v10
	v_ashrrev_i32_e32 v17, 31, v16
	v_lshl_add_u64 v[0:1], s[22:23], 0, v[0:1]
	v_lshlrev_b64 v[2:3], 2, v[2:3]
	v_lshl_add_u64 v[4:5], s[30:31], 0, v[4:5]
	v_lshlrev_b64 v[6:7], 2, v[6:7]
	v_lshl_add_u64 v[8:9], s[30:31], 0, v[8:9]
	v_lshlrev_b64 v[10:11], 2, v[10:11]
	v_lshl_add_u64 v[12:13], s[30:31], 0, v[12:13]
	v_lshl_add_u64 v[14:15], s[30:31], 0, v[14:15]
	v_lshlrev_b64 v[16:17], 2, v[16:17]
	s_mov_b64 s[18:19], 0
	s_mov_b64 s[20:21], s[30:31]
	s_waitcnt lgkmcnt(0)
	s_barrier
	s_branch .LBB0_1820

.LBB0_1940:
	s_setprio 1
	ds_read_b128 v[140:143], v103
	ds_read_b128 v[144:147], v104 offset:36864
	ds_read_b128 v[148:151], v104 offset:41472
	ds_read_b128 v[192:195], v103 offset:4608
	s_waitcnt lgkmcnt(2)
	v_mfma_f32_32x32x16_bf16 v[48:63], v[140:143], v[144:147], v[48:63]
	global_load_dwordx4 v[108:111], v168, s[98:99] offset:3840
	global_load_dwordx4 v[112:115], v170, s[98:99] offset:3840
	s_waitcnt vmcnt(9)
	ds_write_b128 v105, v[68:71] offset:18432
	s_waitcnt lgkmcnt(2)
	v_mfma_f32_32x32x16_bf16 v[32:47], v[140:143], v[148:151], v[32:47]
	ds_read_b128 v[196:199], v103 offset:32
	ds_read_b128 v[200:203], v104 offset:36896
	global_load_dwordx4 v[116:119], v172, s[98:99] offset:3840
	global_load_dwordx4 v[120:123], v174, s[98:99] offset:3840
	s_waitcnt lgkmcnt(3)
	v_mfma_f32_32x32x16_bf16 v[16:31], v[192:195], v[144:147], v[16:31]
	ds_read_b128 v[204:207], v104 offset:41504
	global_load_dwordx4 v[124:127], v176, s[98:99] offset:3840
	global_load_dwordx4 v[128:131], v178, s[98:99] offset:3840
	s_waitcnt vmcnt(11)
	ds_write_b128 v105, v[84:87] offset:23040
	v_mfma_f32_32x32x16_bf16 v[0:15], v[192:195], v[148:151], v[0:15]
	ds_read_b128 v[208:211], v103 offset:4640
	global_load_dwordx4 v[132:135], v180, s[98:99] offset:3840
	global_load_dwordx4 v[136:139], v182, s[98:99] offset:3840
	s_waitcnt lgkmcnt(3)
	v_mfma_f32_32x32x16_bf16 v[48:63], v[196:199], v[200:203], v[48:63]
	s_waitcnt vmcnt(12)
	ds_write_b128 v105, v[88:91] offset:27648
	s_waitcnt lgkmcnt(3)
	v_mfma_f32_32x32x16_bf16 v[32:47], v[196:199], v[204:207], v[32:47]
	ds_read_b128 v[212:215], v103 offset:64
	ds_read_b128 v[216:219], v104 offset:36928
	s_waitcnt lgkmcnt(3)
	v_mfma_f32_32x32x16_bf16 v[16:31], v[208:211], v[200:203], v[16:31]
	ds_read_b128 v[220:223], v104 offset:41536
	s_waitcnt vmcnt(11)
	ds_write_b128 v105, v[92:95] offset:32256
	v_mfma_f32_32x32x16_bf16 v[0:15], v[208:211], v[204:207], v[0:15]
	ds_read_b128 v[224:227], v103 offset:4672
	s_waitcnt lgkmcnt(3)
	v_mfma_f32_32x32x16_bf16 v[48:63], v[212:215], v[216:219], v[48:63]
	ds_write_b128 v105, v[64:67] offset:55296
	s_waitcnt lgkmcnt(3)
	v_mfma_f32_32x32x16_bf16 v[32:47], v[212:215], v[220:223], v[32:47]
	ds_read_b128 v[228:231], v103 offset:96
	ds_read_b128 v[140:143], v104 offset:36960
	s_waitcnt lgkmcnt(3)
	v_mfma_f32_32x32x16_bf16 v[16:31], v[224:227], v[216:219], v[16:31]
	ds_read_b128 v[144:147], v104 offset:41568
	s_waitcnt vmcnt(10)
	ds_write_b128 v105, v[72:75] offset:59904
	v_mfma_f32_32x32x16_bf16 v[0:15], v[224:227], v[220:223], v[0:15]
	ds_read_b128 v[148:151], v103 offset:4704
	s_waitcnt lgkmcnt(3)
	v_mfma_f32_32x32x16_bf16 v[48:63], v[228:231], v[140:143], v[48:63]
	s_waitcnt vmcnt(9)
	ds_write_b128 v105, v[76:79] offset:64512
	s_waitcnt lgkmcnt(3)
	v_mfma_f32_32x32x16_bf16 v[32:47], v[228:231], v[144:147], v[32:47]
	s_waitcnt lgkmcnt(1)
	v_mfma_f32_32x32x16_bf16 v[16:31], v[148:151], v[140:143], v[16:31]
	s_waitcnt vmcnt(8)
	ds_write_b128 v106, v[80:83] offset:13824
	v_mfma_f32_32x32x16_bf16 v[0:15], v[148:151], v[144:147], v[0:15]
	s_setprio 0
	s_waitcnt lgkmcnt(0)
	s_barrier
	s_setprio 1
	ds_read_b128 v[140:143], v103 offset:18432
	ds_read_b128 v[144:147], v104 offset:55296
	ds_read_b128 v[148:151], v104 offset:59904
	ds_read_b128 v[192:195], v103 offset:23040
	s_waitcnt lgkmcnt(2)
	v_mfma_f32_32x32x16_bf16 v[48:63], v[140:143], v[144:147], v[48:63]
	global_load_dwordx4 v[68:71], v168, s[98:99] offset:3968
	global_load_dwordx4 v[84:87], v170, s[98:99] offset:3968
	s_waitcnt vmcnt(9)
	ds_write_b128 v105, v[108:111]
	s_waitcnt lgkmcnt(2)
	v_mfma_f32_32x32x16_bf16 v[32:47], v[140:143], v[148:151], v[32:47]
	ds_read_b128 v[196:199], v103 offset:18464
	ds_read_b128 v[200:203], v104 offset:55328
	global_load_dwordx4 v[88:91], v172, s[98:99] offset:3968
	global_load_dwordx4 v[92:95], v174, s[98:99] offset:3968
	s_waitcnt lgkmcnt(3)
	v_mfma_f32_32x32x16_bf16 v[16:31], v[192:195], v[144:147], v[16:31]
	ds_read_b128 v[204:207], v104 offset:59936
	global_load_dwordx4 v[64:67], v176, s[98:99] offset:3968
	global_load_dwordx4 v[72:75], v178, s[98:99] offset:3968
	s_waitcnt vmcnt(12)
	ds_write_b128 v105, v[112:115] offset:4608
	v_mfma_f32_32x32x16_bf16 v[0:15], v[192:195], v[148:151], v[0:15]
	ds_read_b128 v[208:211], v103 offset:23072
	global_load_dwordx4 v[76:79], v180, s[98:99] offset:3968
	global_load_dwordx4 v[80:83], v182, s[98:99] offset:3968
	s_waitcnt lgkmcnt(3)
	v_mfma_f32_32x32x16_bf16 v[48:63], v[196:199], v[200:203], v[48:63]
	s_add_u32 s98, s98, 0x100
	s_addc_u32 s99, s99, 0
	s_add_i32 s41, s41, 2
	s_cmp_lt_u32 s41, 11
	s_waitcnt vmcnt(13)
	ds_write_b128 v105, v[116:119] offset:9216
	s_waitcnt lgkmcnt(3)
	v_mfma_f32_32x32x16_bf16 v[32:47], v[196:199], v[204:207], v[32:47]
	ds_read_b128 v[212:215], v103 offset:18496
	ds_read_b128 v[216:219], v104 offset:55360
	s_waitcnt lgkmcnt(3)
	v_mfma_f32_32x32x16_bf16 v[16:31], v[208:211], v[200:203], v[16:31]
	ds_read_b128 v[220:223], v104 offset:59968
	s_waitcnt vmcnt(12)
	ds_write_b128 v105, v[120:123] offset:13824
	v_mfma_f32_32x32x16_bf16 v[0:15], v[208:211], v[204:207], v[0:15]
	ds_read_b128 v[224:227], v103 offset:23104
	s_waitcnt lgkmcnt(3)
	v_mfma_f32_32x32x16_bf16 v[48:63], v[212:215], v[216:219], v[48:63]
	s_waitcnt vmcnt(11)
	ds_write_b128 v105, v[124:127] offset:36864
	s_waitcnt lgkmcnt(3)
	v_mfma_f32_32x32x16_bf16 v[32:47], v[212:215], v[220:223], v[32:47]
	ds_read_b128 v[228:231], v103 offset:18528
	ds_read_b128 v[140:143], v104 offset:55392
	s_waitcnt lgkmcnt(3)
	v_mfma_f32_32x32x16_bf16 v[16:31], v[224:227], v[216:219], v[16:31]
	ds_read_b128 v[144:147], v104 offset:60000
	s_waitcnt vmcnt(10)
	ds_write_b128 v105, v[128:131] offset:41472
	v_mfma_f32_32x32x16_bf16 v[0:15], v[224:227], v[220:223], v[0:15]
	ds_read_b128 v[148:151], v103 offset:23136
	s_waitcnt lgkmcnt(3)
	v_mfma_f32_32x32x16_bf16 v[48:63], v[228:231], v[140:143], v[48:63]
	s_waitcnt vmcnt(9)
	ds_write_b128 v105, v[132:135] offset:46080
	s_waitcnt lgkmcnt(3)
	v_mfma_f32_32x32x16_bf16 v[32:47], v[228:231], v[144:147], v[32:47]
	s_waitcnt lgkmcnt(1)
	v_mfma_f32_32x32x16_bf16 v[16:31], v[148:151], v[140:143], v[16:31]
	s_waitcnt vmcnt(8)
	ds_write_b128 v105, v[136:139] offset:50688
	v_mfma_f32_32x32x16_bf16 v[0:15], v[148:151], v[144:147], v[0:15]
	s_setprio 0
	s_waitcnt lgkmcnt(0)
	s_barrier
	s_cbranch_scc1 .LBB0_1940
	s_setprio 1
	ds_read_b128 v[98:101], v103
	ds_read_b128 v[108:111], v104 offset:36864
	ds_read_b128 v[112:115], v104 offset:41472
	ds_read_b128 v[192:195], v103 offset:4608
	s_waitcnt lgkmcnt(2)
	v_mfma_f32_32x32x16_bf16 v[48:63], v[98:101], v[108:111], v[48:63]
	s_waitcnt vmcnt(7)
	ds_write_b128 v105, v[68:71] offset:18432
	s_waitcnt lgkmcnt(2)
	v_mfma_f32_32x32x16_bf16 v[32:47], v[98:101], v[112:115], v[32:47]
	ds_read_b128 v[196:199], v103 offset:32
	ds_read_b128 v[200:203], v104 offset:36896
	s_waitcnt lgkmcnt(3)
	v_mfma_f32_32x32x16_bf16 v[16:31], v[192:195], v[108:111], v[16:31]
	ds_read_b128 v[204:207], v104 offset:41504
	s_waitcnt vmcnt(6)
	ds_write_b128 v105, v[84:87] offset:23040
	v_mfma_f32_32x32x16_bf16 v[0:15], v[192:195], v[112:115], v[0:15]
	ds_read_b128 v[208:211], v103 offset:4640
	s_waitcnt lgkmcnt(3)
	v_mfma_f32_32x32x16_bf16 v[48:63], v[196:199], v[200:203], v[48:63]
	s_waitcnt vmcnt(5)
	ds_write_b128 v105, v[88:91] offset:27648
	s_waitcnt lgkmcnt(3)
	v_mfma_f32_32x32x16_bf16 v[32:47], v[196:199], v[204:207], v[32:47]
	ds_read_b128 v[212:215], v103 offset:64
	ds_read_b128 v[216:219], v104 offset:36928
	s_waitcnt lgkmcnt(3)
	v_mfma_f32_32x32x16_bf16 v[16:31], v[208:211], v[200:203], v[16:31]
	ds_read_b128 v[220:223], v104 offset:41536
	s_waitcnt vmcnt(4)
	ds_write_b128 v105, v[92:95] offset:32256
	v_mfma_f32_32x32x16_bf16 v[0:15], v[208:211], v[204:207], v[0:15]
	ds_read_b128 v[224:227], v103 offset:4672
	s_waitcnt lgkmcnt(3)
	v_mfma_f32_32x32x16_bf16 v[48:63], v[212:215], v[216:219], v[48:63]
	s_waitcnt vmcnt(3)
	ds_write_b128 v105, v[64:67] offset:55296
	s_waitcnt lgkmcnt(3)
	v_mfma_f32_32x32x16_bf16 v[32:47], v[212:215], v[220:223], v[32:47]
	ds_read_b128 v[228:231], v103 offset:96
	ds_read_b128 v[98:101], v104 offset:36960
	s_waitcnt lgkmcnt(3)
	v_mfma_f32_32x32x16_bf16 v[16:31], v[224:227], v[216:219], v[16:31]
	ds_read_b128 v[108:111], v104 offset:41568
	s_waitcnt vmcnt(2)
	ds_write_b128 v105, v[72:75] offset:59904
	v_mfma_f32_32x32x16_bf16 v[0:15], v[224:227], v[220:223], v[0:15]
	ds_read_b128 v[112:115], v103 offset:4704
	s_waitcnt lgkmcnt(3)
	v_mfma_f32_32x32x16_bf16 v[48:63], v[228:231], v[98:101], v[48:63]
	s_waitcnt vmcnt(1)
	ds_write_b128 v105, v[76:79] offset:64512
	s_waitcnt lgkmcnt(3)
	v_mfma_f32_32x32x16_bf16 v[32:47], v[228:231], v[108:111], v[32:47]
	s_waitcnt lgkmcnt(1)
	v_mfma_f32_32x32x16_bf16 v[16:31], v[112:115], v[98:101], v[16:31]
	s_waitcnt vmcnt(0)
	ds_write_b128 v106, v[80:83] offset:13824
	v_mfma_f32_32x32x16_bf16 v[0:15], v[112:115], v[108:111], v[0:15]
	s_setprio 0
	s_waitcnt lgkmcnt(0)
	s_barrier
	s_setprio 1
	ds_read_b128 v[64:67], v103 offset:18432
	ds_read_b128 v[68:71], v104 offset:55296
	ds_read_b128 v[72:75], v104 offset:59904
	ds_read_b128 v[192:195], v103 offset:23040
	s_waitcnt lgkmcnt(2)
	v_mfma_f32_32x32x16_bf16 v[48:63], v[64:67], v[68:71], v[48:63]
	s_waitcnt lgkmcnt(1)
	v_mfma_f32_32x32x16_bf16 v[32:47], v[64:67], v[72:75], v[32:47]
	ds_read_b128 v[196:199], v103 offset:18464
	ds_read_b128 v[200:203], v104 offset:55328
	s_waitcnt lgkmcnt(2)
	v_mfma_f32_32x32x16_bf16 v[16:31], v[192:195], v[68:71], v[16:31]
	ds_read_b128 v[204:207], v104 offset:59936
	v_mfma_f32_32x32x16_bf16 v[0:15], v[192:195], v[72:75], v[0:15]
	ds_read_b128 v[208:211], v103 offset:23072
	s_waitcnt lgkmcnt(2)
	v_mfma_f32_32x32x16_bf16 v[48:63], v[196:199], v[200:203], v[48:63]
	s_waitcnt lgkmcnt(1)
	v_mfma_f32_32x32x16_bf16 v[32:47], v[196:199], v[204:207], v[32:47]
	ds_read_b128 v[212:215], v103 offset:18496
	ds_read_b128 v[216:219], v104 offset:55360
	s_waitcnt lgkmcnt(2)
	v_mfma_f32_32x32x16_bf16 v[16:31], v[208:211], v[200:203], v[16:31]
	ds_read_b128 v[220:223], v104 offset:59968
	v_mfma_f32_32x32x16_bf16 v[0:15], v[208:211], v[204:207], v[0:15]
	ds_read_b128 v[224:227], v103 offset:23104
	s_waitcnt lgkmcnt(2)
	v_mfma_f32_32x32x16_bf16 v[48:63], v[212:215], v[216:219], v[48:63]
	s_waitcnt lgkmcnt(1)
	v_mfma_f32_32x32x16_bf16 v[32:47], v[212:215], v[220:223], v[32:47]
	ds_read_b128 v[228:231], v103 offset:18528
	ds_read_b128 v[64:67], v104 offset:55392
	s_waitcnt lgkmcnt(2)
	v_mfma_f32_32x32x16_bf16 v[16:31], v[224:227], v[216:219], v[16:31]
	ds_read_b128 v[68:71], v104 offset:60000
	v_mfma_f32_32x32x16_bf16 v[0:15], v[224:227], v[220:223], v[0:15]
	ds_read_b128 v[72:75], v103 offset:23136
	s_waitcnt lgkmcnt(2)
	v_mfma_f32_32x32x16_bf16 v[48:63], v[228:231], v[64:67], v[48:63]
	s_waitcnt lgkmcnt(1)
	v_mfma_f32_32x32x16_bf16 v[32:47], v[228:231], v[68:71], v[32:47]
	s_waitcnt lgkmcnt(0)
	v_mfma_f32_32x32x16_bf16 v[16:31], v[72:75], v[64:67], v[16:31]
	v_mfma_f32_32x32x16_bf16 v[0:15], v[72:75], v[68:71], v[0:15]
	s_setprio 0
	v_lshrrev_b32_e32 v65, 3, v102
	v_lshrrev_b32_e32 v64, 1, v102
	v_and_b32_e32 v65, 4, v65
	v_and_or_b32 v64, v64, s22, v65
	v_and_b32_e32 v65, 0x5f, v102
	v_lshlrev_b32_e32 v65, 1, v65
	v_mul_lo_u32 v64, v64, s36
	v_add3_u32 v64, 32, v65, v64
	s_nop 2
	v_cvt_pk_bf16_f32 v0, v0, s0
	s_barrier
	ds_write_b16 v64, v0 offset:8768
	v_cvt_pk_bf16_f32 v0, v17, s0
	ds_write_b16 v64, v0 offset:8976
	v_cvt_pk_bf16_f32 v0, v1, s0
	ds_write_b16 v64, v0 offset:9040
	v_cvt_pk_bf16_f32 v0, v18, s0
	v_cvt_pk_bf16_f32 v32, v32, s0
	ds_write_b16 v64, v0 offset:9248
	v_cvt_pk_bf16_f32 v0, v2, s0
	ds_write_b16 v64, v32 offset:64
	v_cvt_pk_bf16_f32 v32, v49, s0
	ds_write_b16 v64, v0 offset:9312
	v_cvt_pk_bf16_f32 v0, v19, s0
	ds_write_b16 v64, v32 offset:272
	v_cvt_pk_bf16_f32 v32, v33, s0
	ds_write_b16 v64, v0 offset:9520
	v_cvt_pk_bf16_f32 v0, v3, s0
	ds_write_b16 v64, v32 offset:336
	v_cvt_pk_bf16_f32 v32, v50, s0
	ds_write_b16 v64, v0 offset:9584
	v_cvt_pk_bf16_f32 v0, v20, s0
	ds_write_b16 v64, v32 offset:544
	v_cvt_pk_bf16_f32 v32, v34, s0
	ds_write_b16 v64, v0 offset:10880
	v_cvt_pk_bf16_f32 v0, v4, s0
	ds_write_b16 v64, v32 offset:608
	v_cvt_pk_bf16_f32 v32, v51, s0
	ds_write_b16 v64, v0 offset:10944
	v_cvt_pk_bf16_f32 v0, v21, s0
	ds_write_b16 v64, v32 offset:816
	v_cvt_pk_bf16_f32 v32, v35, s0
	ds_write_b16 v64, v0 offset:11152
	v_cvt_pk_bf16_f32 v0, v5, s0
	ds_write_b16 v64, v32 offset:880
	v_cvt_pk_bf16_f32 v32, v52, s0
	ds_write_b16 v64, v0 offset:11216
	v_cvt_pk_bf16_f32 v0, v22, s0
	ds_write_b16 v64, v32 offset:2176
	v_cvt_pk_bf16_f32 v32, v36, s0
	ds_write_b16 v64, v0 offset:11424
	v_cvt_pk_bf16_f32 v0, v6, s0
	ds_write_b16 v64, v32 offset:2240
	v_cvt_pk_bf16_f32 v32, v53, s0
	ds_write_b16 v64, v0 offset:11488
	v_cvt_pk_bf16_f32 v0, v23, s0
	ds_write_b16 v64, v32 offset:2448
	v_cvt_pk_bf16_f32 v32, v37, s0
	ds_write_b16 v64, v0 offset:11696
	v_cvt_pk_bf16_f32 v0, v7, s0
	ds_write_b16 v64, v32 offset:2512
	v_cvt_pk_bf16_f32 v32, v54, s0
	ds_write_b16 v64, v0 offset:11760
	v_cvt_pk_bf16_f32 v0, v24, s0
	ds_write_b16 v64, v32 offset:2720
	v_cvt_pk_bf16_f32 v32, v38, s0
	ds_write_b16 v64, v0 offset:13056
	v_cvt_pk_bf16_f32 v0, v8, s0
	ds_write_b16 v64, v32 offset:2784
	v_cvt_pk_bf16_f32 v32, v55, s0
	ds_write_b16 v64, v0 offset:13120
	v_cvt_pk_bf16_f32 v0, v25, s0
	ds_write_b16 v64, v32 offset:2992
	v_cvt_pk_bf16_f32 v32, v39, s0
	ds_write_b16 v64, v0 offset:13328
	v_cvt_pk_bf16_f32 v0, v9, s0
	ds_write_b16 v64, v32 offset:3056
	v_cvt_pk_bf16_f32 v32, v56, s0
	ds_write_b16 v64, v0 offset:13392
	v_cvt_pk_bf16_f32 v0, v26, s0
	ds_write_b16 v64, v32 offset:4352
	v_cvt_pk_bf16_f32 v32, v40, s0
	ds_write_b16 v64, v0 offset:13600
	v_cvt_pk_bf16_f32 v0, v10, s0
	ds_write_b16 v64, v32 offset:4416
	v_cvt_pk_bf16_f32 v32, v57, s0
	ds_write_b16 v64, v0 offset:13664
	v_cvt_pk_bf16_f32 v0, v27, s0
	ds_write_b16 v64, v32 offset:4624
	v_cvt_pk_bf16_f32 v32, v41, s0
	ds_write_b16 v64, v0 offset:13872
	v_cvt_pk_bf16_f32 v0, v11, s0
	ds_write_b16 v64, v32 offset:4688
	v_cvt_pk_bf16_f32 v32, v58, s0
	ds_write_b16 v64, v0 offset:13936
	v_cvt_pk_bf16_f32 v0, v28, s0
	ds_write_b16 v64, v32 offset:4896
	v_cvt_pk_bf16_f32 v32, v42, s0
	ds_write_b16 v64, v0 offset:15232
	v_cvt_pk_bf16_f32 v0, v12, s0
	ds_write_b16 v64, v32 offset:4960
	v_cvt_pk_bf16_f32 v32, v59, s0
	ds_write_b16 v64, v0 offset:15296
	v_cvt_pk_bf16_f32 v0, v29, s0
	ds_write_b16 v64, v32 offset:5168
	v_cvt_pk_bf16_f32 v32, v43, s0
	ds_write_b16 v64, v0 offset:15504
	v_cvt_pk_bf16_f32 v0, v13, s0
	ds_write_b16 v64, v32 offset:5232
	v_cvt_pk_bf16_f32 v32, v60, s0
	ds_write_b16 v64, v0 offset:15568
	v_cvt_pk_bf16_f32 v0, v30, s0
	ds_write_b16 v64, v32 offset:6528
	v_cvt_pk_bf16_f32 v32, v44, s0
	ds_write_b16 v64, v0 offset:15776
	v_cvt_pk_bf16_f32 v0, v14, s0
	s_mul_i32 s11, s11, 0x160000
	ds_write_b16 v64, v32 offset:6592
	v_cvt_pk_bf16_f32 v32, v61, s0
	ds_write_b16 v64, v0 offset:15840
	v_cvt_pk_bf16_f32 v0, v31, s0
	s_add_u32 s41, s13, s11
	ds_write_b16 v64, v32 offset:6800
	v_cvt_pk_bf16_f32 v32, v45, s0
	ds_write_b16 v64, v0 offset:16048
	v_cvt_pk_bf16_f32 v0, v15, s0
	s_addc_u32 s44, s14, 0
	s_ashr_i32 s11, s10, 31
	ds_write_b16 v64, v32 offset:6864
	v_cvt_pk_bf16_f32 v32, v62, s0
	ds_write_b16 v64, v0 offset:16112
	s_lshl_b64 s[10:11], s[10:11], 1
	v_lshlrev_b32_e32 v0, 4, v102
	ds_write_b16 v64, v32 offset:7072
	v_cvt_pk_bf16_f32 v32, v46, s0
	s_add_u32 s10, s41, s10
	v_and_b32_e32 v96, 0xf0, v0
	ds_write_b16 v64, v32 offset:7136
	v_cvt_pk_bf16_f32 v32, v63, s0
	s_addc_u32 s11, s44, s11
	v_add_u32_e32 v8, 32, v96
	v_ashrrev_i32_e32 v9, 4, v102
	v_add_u32_e32 v4, 0x100, v102
	v_cvt_pk_bf16_f32 v48, v48, s0
	ds_write_b16 v64, v32 offset:7344
	v_cvt_pk_bf16_f32 v32, v47, s0
	v_cvt_pk_bf16_f32 v16, v16, s0
	v_lshl_add_u64 v[10:11], s[10:11], 0, v[96:97]
	v_mad_u64_u32 v[0:1], s[10:11], v9, s36, v[8:9]
	v_ashrrev_i32_e32 v14, 4, v4
	ds_write_b16 v64, v48
	ds_write_b16 v64, v32 offset:7408
	ds_write_b16 v64, v16 offset:8704
	s_waitcnt lgkmcnt(0)
	s_barrier
	ds_read_b128 v[0:3], v0
	v_mad_u64_u32 v[4:5], s[10:11], v14, s36, v[8:9]
	ds_read_b128 v[4:7], v4
	v_mad_i64_i32 v[12:13], s[10:11], v9, s37, v[10:11]
	s_waitcnt lgkmcnt(1)
	global_store_dwordx4 v[12:13], v[0:3], off
	s_nop 1
	v_mad_i64_i32 v[0:1], s[10:11], v14, s37, v[10:11]
	s_waitcnt lgkmcnt(0)
	global_store_dwordx4 v[0:1], v[4:7], off
	v_add_u32_e32 v0, 0x200, v102
	v_ashrrev_i32_e32 v9, 4, v0
	v_add_u32_e32 v4, 0x300, v102
	v_mad_u64_u32 v[0:1], s[10:11], v9, s36, v[8:9]
	v_ashrrev_i32_e32 v14, 4, v4
	ds_read_b128 v[0:3], v0
	v_mad_u64_u32 v[4:5], s[10:11], v14, s36, v[8:9]
	ds_read_b128 v[4:7], v4
	v_mad_i64_i32 v[12:13], s[10:11], v9, s37, v[10:11]
	s_waitcnt lgkmcnt(1)
	global_store_dwordx4 v[12:13], v[0:3], off
	s_nop 1
	v_mad_i64_i32 v[0:1], s[10:11], v14, s37, v[10:11]
	s_waitcnt lgkmcnt(0)
	global_store_dwordx4 v[0:1], v[4:7], off
	v_add_u32_e32 v0, 0x400, v102
	v_ashrrev_i32_e32 v9, 4, v0
	v_add_u32_e32 v4, 0x500, v102
	v_mad_u64_u32 v[0:1], s[10:11], v9, s36, v[8:9]
	v_ashrrev_i32_e32 v14, 4, v4
	ds_read_b128 v[0:3], v0
	v_mad_u64_u32 v[4:5], s[10:11], v14, s36, v[8:9]
	ds_read_b128 v[4:7], v4
	v_mad_i64_i32 v[12:13], s[10:11], v9, s37, v[10:11]
	s_waitcnt lgkmcnt(1)
	global_store_dwordx4 v[12:13], v[0:3], off
	s_nop 1
	v_mad_i64_i32 v[0:1], s[10:11], v14, s37, v[10:11]
	s_waitcnt lgkmcnt(0)
	global_store_dwordx4 v[0:1], v[4:7], off
	v_add_u32_e32 v0, 0x600, v102
	v_ashrrev_i32_e32 v9, 4, v0
	v_add_u32_e32 v4, 0x700, v102
	v_mad_u64_u32 v[0:1], s[10:11], v9, s36, v[8:9]
	v_ashrrev_i32_e32 v12, 4, v4
	ds_read_b128 v[0:3], v0
	v_mad_u64_u32 v[4:5], s[10:11], v12, s36, v[8:9]
	ds_read_b128 v[4:7], v4
	v_mad_i64_i32 v[8:9], s[10:11], v9, s37, v[10:11]
	s_waitcnt lgkmcnt(1)
	global_store_dwordx4 v[8:9], v[0:3], off
	s_nop 1
	v_mad_i64_i32 v[0:1], s[10:11], v12, s37, v[10:11]
	s_waitcnt lgkmcnt(0)
	global_store_dwordx4 v[0:1], v[4:7], off
	s_branch .LBB0_1937

.LBB0_2062:
	s_setprio 1
	ds_read_b128 v[146:149], v109
	ds_read_b128 v[150:153], v110 offset:36864
	ds_read_b128 v[154:157], v110 offset:41472
	ds_read_b128 v[192:195], v109 offset:4608
	s_waitcnt lgkmcnt(2)
	v_mfma_f32_32x32x16_bf16 v[32:47], v[146:149], v[150:153], v[32:47]
	global_load_dwordx4 v[114:117], v174, s[98:99] offset:3840
	global_load_dwordx4 v[118:121], v176, s[98:99] offset:3840
	s_waitcnt vmcnt(9)
	ds_write_b128 v111, v[68:71] offset:18432
	s_waitcnt lgkmcnt(2)
	v_mfma_f32_32x32x16_bf16 v[48:63], v[146:149], v[154:157], v[48:63]
	ds_read_b128 v[196:199], v109 offset:32
	ds_read_b128 v[200:203], v110 offset:36896
	global_load_dwordx4 v[122:125], v178, s[98:99] offset:3840
	global_load_dwordx4 v[126:129], v180, s[98:99] offset:3840
	s_waitcnt lgkmcnt(3)
	v_mfma_f32_32x32x16_bf16 v[16:31], v[192:195], v[150:153], v[16:31]
	ds_read_b128 v[204:207], v110 offset:41504
	global_load_dwordx4 v[130:133], v182, s[98:99] offset:3840
	global_load_dwordx4 v[134:137], v184, s[98:99] offset:3840
	s_waitcnt vmcnt(11)
	ds_write_b128 v111, v[84:87] offset:23040
	v_mfma_f32_32x32x16_bf16 v[0:15], v[192:195], v[154:157], v[0:15]
	ds_read_b128 v[208:211], v109 offset:4640
	global_load_dwordx4 v[138:141], v186, s[98:99] offset:3840
	global_load_dwordx4 v[142:145], v188, s[98:99] offset:3840
	s_waitcnt lgkmcnt(3)
	v_mfma_f32_32x32x16_bf16 v[32:47], v[196:199], v[200:203], v[32:47]
	s_waitcnt vmcnt(12)
	ds_write_b128 v111, v[88:91] offset:27648
	s_waitcnt lgkmcnt(3)
	v_mfma_f32_32x32x16_bf16 v[48:63], v[196:199], v[204:207], v[48:63]
	ds_read_b128 v[212:215], v109 offset:64
	ds_read_b128 v[216:219], v110 offset:36928
	s_waitcnt lgkmcnt(3)
	v_mfma_f32_32x32x16_bf16 v[16:31], v[208:211], v[200:203], v[16:31]
	ds_read_b128 v[220:223], v110 offset:41536
	s_waitcnt vmcnt(11)
	ds_write_b128 v111, v[92:95] offset:32256
	v_mfma_f32_32x32x16_bf16 v[0:15], v[208:211], v[204:207], v[0:15]
	ds_read_b128 v[224:227], v109 offset:4672
	s_waitcnt lgkmcnt(3)
	v_mfma_f32_32x32x16_bf16 v[32:47], v[212:215], v[216:219], v[32:47]
	ds_write_b128 v111, v[64:67] offset:55296
	s_waitcnt lgkmcnt(3)
	v_mfma_f32_32x32x16_bf16 v[48:63], v[212:215], v[220:223], v[48:63]
	ds_read_b128 v[228:231], v109 offset:96
	ds_read_b128 v[146:149], v110 offset:36960
	s_waitcnt lgkmcnt(3)
	v_mfma_f32_32x32x16_bf16 v[16:31], v[224:227], v[216:219], v[16:31]
	ds_read_b128 v[150:153], v110 offset:41568
	s_waitcnt vmcnt(10)
	ds_write_b128 v111, v[72:75] offset:59904
	v_mfma_f32_32x32x16_bf16 v[0:15], v[224:227], v[220:223], v[0:15]
	ds_read_b128 v[154:157], v109 offset:4704
	s_waitcnt lgkmcnt(3)
	v_mfma_f32_32x32x16_bf16 v[32:47], v[228:231], v[146:149], v[32:47]
	s_waitcnt vmcnt(9)
	ds_write_b128 v111, v[76:79] offset:64512
	s_waitcnt lgkmcnt(3)
	v_mfma_f32_32x32x16_bf16 v[48:63], v[228:231], v[150:153], v[48:63]
	s_waitcnt lgkmcnt(1)
	v_mfma_f32_32x32x16_bf16 v[16:31], v[154:157], v[146:149], v[16:31]
	s_waitcnt vmcnt(8)
	ds_write_b128 v112, v[80:83] offset:13824
	v_mfma_f32_32x32x16_bf16 v[0:15], v[154:157], v[150:153], v[0:15]
	s_setprio 0
	s_waitcnt lgkmcnt(0)
	s_barrier
	s_setprio 1
	ds_read_b128 v[146:149], v109 offset:18432
	ds_read_b128 v[150:153], v110 offset:55296
	ds_read_b128 v[154:157], v110 offset:59904
	ds_read_b128 v[192:195], v109 offset:23040
	s_waitcnt lgkmcnt(2)
	v_mfma_f32_32x32x16_bf16 v[32:47], v[146:149], v[150:153], v[32:47]
	global_load_dwordx4 v[68:71], v174, s[98:99] offset:3968
	global_load_dwordx4 v[84:87], v176, s[98:99] offset:3968
	s_waitcnt vmcnt(9)
	ds_write_b128 v111, v[114:117]
	s_waitcnt lgkmcnt(2)
	v_mfma_f32_32x32x16_bf16 v[48:63], v[146:149], v[154:157], v[48:63]
	ds_read_b128 v[196:199], v109 offset:18464
	ds_read_b128 v[200:203], v110 offset:55328
	global_load_dwordx4 v[88:91], v178, s[98:99] offset:3968
	global_load_dwordx4 v[92:95], v180, s[98:99] offset:3968
	s_waitcnt lgkmcnt(3)
	v_mfma_f32_32x32x16_bf16 v[16:31], v[192:195], v[150:153], v[16:31]
	ds_read_b128 v[204:207], v110 offset:59936
	global_load_dwordx4 v[64:67], v182, s[98:99] offset:3968
	global_load_dwordx4 v[72:75], v184, s[98:99] offset:3968
	s_waitcnt vmcnt(12)
	ds_write_b128 v111, v[118:121] offset:4608
	v_mfma_f32_32x32x16_bf16 v[0:15], v[192:195], v[154:157], v[0:15]
	ds_read_b128 v[208:211], v109 offset:23072
	global_load_dwordx4 v[76:79], v186, s[98:99] offset:3968
	global_load_dwordx4 v[80:83], v188, s[98:99] offset:3968
	s_waitcnt lgkmcnt(3)
	v_mfma_f32_32x32x16_bf16 v[32:47], v[196:199], v[200:203], v[32:47]
	s_add_u32 s98, s98, 0x100
	s_addc_u32 s99, s99, 0
	s_add_i32 s8, s8, 2
	s_cmp_lt_u32 s8, 39
	s_waitcnt vmcnt(13)
	ds_write_b128 v111, v[122:125] offset:9216
	s_waitcnt lgkmcnt(3)
	v_mfma_f32_32x32x16_bf16 v[48:63], v[196:199], v[204:207], v[48:63]
	ds_read_b128 v[212:215], v109 offset:18496
	ds_read_b128 v[216:219], v110 offset:55360
	s_waitcnt lgkmcnt(3)
	v_mfma_f32_32x32x16_bf16 v[16:31], v[208:211], v[200:203], v[16:31]
	ds_read_b128 v[220:223], v110 offset:59968
	s_waitcnt vmcnt(12)
	ds_write_b128 v111, v[126:129] offset:13824
	v_mfma_f32_32x32x16_bf16 v[0:15], v[208:211], v[204:207], v[0:15]
	ds_read_b128 v[224:227], v109 offset:23104
	s_waitcnt lgkmcnt(3)
	v_mfma_f32_32x32x16_bf16 v[32:47], v[212:215], v[216:219], v[32:47]
	s_waitcnt vmcnt(11)
	ds_write_b128 v111, v[130:133] offset:36864
	s_waitcnt lgkmcnt(3)
	v_mfma_f32_32x32x16_bf16 v[48:63], v[212:215], v[220:223], v[48:63]
	ds_read_b128 v[228:231], v109 offset:18528
	ds_read_b128 v[146:149], v110 offset:55392
	s_waitcnt lgkmcnt(3)
	v_mfma_f32_32x32x16_bf16 v[16:31], v[224:227], v[216:219], v[16:31]
	ds_read_b128 v[150:153], v110 offset:60000
	s_waitcnt vmcnt(10)
	ds_write_b128 v111, v[134:137] offset:41472
	v_mfma_f32_32x32x16_bf16 v[0:15], v[224:227], v[220:223], v[0:15]
	ds_read_b128 v[154:157], v109 offset:23136
	s_waitcnt lgkmcnt(3)
	v_mfma_f32_32x32x16_bf16 v[32:47], v[228:231], v[146:149], v[32:47]
	s_waitcnt vmcnt(9)
	ds_write_b128 v111, v[138:141] offset:46080
	s_waitcnt lgkmcnt(3)
	v_mfma_f32_32x32x16_bf16 v[48:63], v[228:231], v[150:153], v[48:63]
	s_waitcnt lgkmcnt(1)
	v_mfma_f32_32x32x16_bf16 v[16:31], v[154:157], v[146:149], v[16:31]
	s_waitcnt vmcnt(8)
	ds_write_b128 v111, v[142:145] offset:50688
	v_mfma_f32_32x32x16_bf16 v[0:15], v[154:157], v[150:153], v[0:15]
	s_setprio 0
	s_waitcnt lgkmcnt(0)
	s_barrier
	s_cbranch_scc1 .LBB0_2062
	s_setprio 1
	ds_read_b128 v[104:107], v109
	ds_read_b128 v[114:117], v110 offset:36864
	ds_read_b128 v[118:121], v110 offset:41472
	ds_read_b128 v[192:195], v109 offset:4608
	s_waitcnt lgkmcnt(2)
	v_mfma_f32_32x32x16_bf16 v[32:47], v[104:107], v[114:117], v[32:47]
	s_waitcnt vmcnt(7)
	ds_write_b128 v111, v[68:71] offset:18432
	s_waitcnt lgkmcnt(2)
	v_mfma_f32_32x32x16_bf16 v[48:63], v[104:107], v[118:121], v[48:63]
	ds_read_b128 v[196:199], v109 offset:32
	ds_read_b128 v[200:203], v110 offset:36896
	s_waitcnt lgkmcnt(3)
	v_mfma_f32_32x32x16_bf16 v[16:31], v[192:195], v[114:117], v[16:31]
	ds_read_b128 v[204:207], v110 offset:41504
	s_waitcnt vmcnt(6)
	ds_write_b128 v111, v[84:87] offset:23040
	v_mfma_f32_32x32x16_bf16 v[0:15], v[192:195], v[118:121], v[0:15]
	ds_read_b128 v[208:211], v109 offset:4640
	s_waitcnt lgkmcnt(3)
	v_mfma_f32_32x32x16_bf16 v[32:47], v[196:199], v[200:203], v[32:47]
	s_waitcnt vmcnt(5)
	ds_write_b128 v111, v[88:91] offset:27648
	s_waitcnt lgkmcnt(3)
	v_mfma_f32_32x32x16_bf16 v[48:63], v[196:199], v[204:207], v[48:63]
	ds_read_b128 v[212:215], v109 offset:64
	ds_read_b128 v[216:219], v110 offset:36928
	s_waitcnt lgkmcnt(3)
	v_mfma_f32_32x32x16_bf16 v[16:31], v[208:211], v[200:203], v[16:31]
	ds_read_b128 v[220:223], v110 offset:41536
	s_waitcnt vmcnt(4)
	ds_write_b128 v111, v[92:95] offset:32256
	v_mfma_f32_32x32x16_bf16 v[0:15], v[208:211], v[204:207], v[0:15]
	ds_read_b128 v[224:227], v109 offset:4672
	s_waitcnt lgkmcnt(3)
	v_mfma_f32_32x32x16_bf16 v[32:47], v[212:215], v[216:219], v[32:47]
	s_waitcnt vmcnt(3)
	ds_write_b128 v111, v[64:67] offset:55296
	s_waitcnt lgkmcnt(3)
	v_mfma_f32_32x32x16_bf16 v[48:63], v[212:215], v[220:223], v[48:63]
	ds_read_b128 v[228:231], v109 offset:96
	ds_read_b128 v[104:107], v110 offset:36960
	s_waitcnt lgkmcnt(3)
	v_mfma_f32_32x32x16_bf16 v[16:31], v[224:227], v[216:219], v[16:31]
	ds_read_b128 v[114:117], v109 offset:4704
	s_waitcnt vmcnt(2)
	ds_write_b128 v111, v[72:75] offset:59904
	v_mfma_f32_32x32x16_bf16 v[0:15], v[224:227], v[220:223], v[0:15]
	ds_read_b128 v[118:121], v110 offset:41568
	s_waitcnt lgkmcnt(3)
	v_mfma_f32_32x32x16_bf16 v[32:47], v[228:231], v[104:107], v[32:47]
	s_waitcnt vmcnt(1)
	ds_write_b128 v111, v[76:79] offset:64512
	s_waitcnt lgkmcnt(3)
	v_mfma_f32_32x32x16_bf16 v[16:31], v[114:117], v[104:107], v[16:31]
	s_waitcnt lgkmcnt(1)
	v_mfma_f32_32x32x16_bf16 v[0:15], v[114:117], v[118:121], v[0:15]
	s_waitcnt vmcnt(0)
	ds_write_b128 v112, v[80:83] offset:13824
	v_mfma_f32_32x32x16_bf16 v[48:63], v[228:231], v[118:121], v[48:63]
	s_setprio 0
	s_waitcnt lgkmcnt(0)
	s_barrier
	s_setprio 1
	ds_read_b128 v[64:67], v109 offset:18432
	ds_read_b128 v[68:71], v110 offset:55296
	ds_read_b128 v[72:75], v110 offset:59904
	ds_read_b128 v[192:195], v109 offset:23040
	s_waitcnt lgkmcnt(2)
	v_mfma_f32_32x32x16_bf16 v[32:47], v[64:67], v[68:71], v[32:47]
	s_waitcnt lgkmcnt(1)
	v_mfma_f32_32x32x16_bf16 v[48:63], v[64:67], v[72:75], v[48:63]
	ds_read_b128 v[196:199], v109 offset:18464
	ds_read_b128 v[200:203], v110 offset:55328
	s_waitcnt lgkmcnt(2)
	v_mfma_f32_32x32x16_bf16 v[16:31], v[192:195], v[68:71], v[16:31]
	ds_read_b128 v[204:207], v110 offset:59936
	v_mfma_f32_32x32x16_bf16 v[0:15], v[192:195], v[72:75], v[0:15]
	ds_read_b128 v[208:211], v109 offset:23072
	s_waitcnt lgkmcnt(2)
	v_mfma_f32_32x32x16_bf16 v[32:47], v[196:199], v[200:203], v[32:47]
	s_waitcnt lgkmcnt(1)
	v_mfma_f32_32x32x16_bf16 v[48:63], v[196:199], v[204:207], v[48:63]
	ds_read_b128 v[212:215], v109 offset:18496
	ds_read_b128 v[216:219], v110 offset:55360
	s_waitcnt lgkmcnt(2)
	v_mfma_f32_32x32x16_bf16 v[16:31], v[208:211], v[200:203], v[16:31]
	ds_read_b128 v[220:223], v110 offset:59968
	v_mfma_f32_32x32x16_bf16 v[0:15], v[208:211], v[204:207], v[0:15]
	ds_read_b128 v[224:227], v109 offset:23104
	s_waitcnt lgkmcnt(2)
	v_mfma_f32_32x32x16_bf16 v[32:47], v[212:215], v[216:219], v[32:47]
	s_waitcnt lgkmcnt(1)
	v_mfma_f32_32x32x16_bf16 v[48:63], v[212:215], v[220:223], v[48:63]
	ds_read_b128 v[228:231], v109 offset:18528
	ds_read_b128 v[64:67], v110 offset:55392
	s_waitcnt lgkmcnt(2)
	v_mfma_f32_32x32x16_bf16 v[16:31], v[224:227], v[216:219], v[16:31]
	ds_read_b128 v[68:71], v109 offset:23136
	v_mfma_f32_32x32x16_bf16 v[0:15], v[224:227], v[220:223], v[0:15]
	ds_read_b128 v[72:75], v110 offset:60000
	s_waitcnt lgkmcnt(2)
	v_mfma_f32_32x32x16_bf16 v[32:47], v[228:231], v[64:67], v[32:47]
	s_waitcnt lgkmcnt(1)
	v_mfma_f32_32x32x16_bf16 v[16:31], v[68:71], v[64:67], v[16:31]
	s_waitcnt lgkmcnt(0)
	v_mfma_f32_32x32x16_bf16 v[0:15], v[68:71], v[72:75], v[0:15]
	v_mfma_f32_32x32x16_bf16 v[48:63], v[228:231], v[72:75], v[48:63]
	s_setprio 0
	s_addk_i32 s0, 0xf000
	s_lshr_b32 s8, s0, 10
	s_mulk_i32 s8, 0x1800
	s_addk_i32 s8, 0x1800
	s_and_b64 s[58:59], s[4:5], exec
	s_cselect_b32 s8, 0, s8
	v_mov_b32_e32 v68, v234
	s_barrier
	s_lshl_b64 s[58:59], s[8:9], 2
	s_add_u32 s58, s30, s58
	v_and_b32_e32 v69, 0x5f, v68
	v_or_b32_e32 v64, s23, v69
	s_addc_u32 s59, s31, s59
	v_ashrrev_i32_e32 v65, 31, v64
	v_lshl_add_u64 v[64:65], v[64:65], 2, s[58:59]
	v_lshl_add_u64 v[66:67], v[64:65], 0, s[12:13]
	v_add_co_u32_e32 v64, vcc, s51, v64
	global_load_dword v66, v[66:67], off offset:128
	s_nop 0
	v_addc_co_u32_e32 v65, vcc, 0, v65, vcc
	global_load_dword v64, v[64:65], off
	v_lshrrev_b32_e32 v67, 3, v68
	v_lshrrev_b32_e32 v65, 1, v68
	v_and_b32_e32 v67, 4, v67
	v_and_or_b32 v65, v65, s45, v67
	v_lshlrev_b32_e32 v69, 2, v69
	v_mul_lo_u32 v65, v65, s52
	v_add3_u32 v65, 32, v69, v65
	v_add_u32_e32 v67, 0x400, v65
	v_add_u32_e32 v69, 0x1000, v65
	v_add_u32_e32 v70, 0x1400, v65
	v_add_u32_e32 v71, 0x2000, v65
	v_add_u32_e32 v72, 0x2400, v65
	v_add_u32_e32 v73, 0x3000, v65
	v_add_u32_e32 v74, 0x3200, v65
	v_add_u32_e32 v75, 0x3400, v65
	v_add_u32_e32 v76, 0x3600, v65
	v_add_u32_e32 v77, 0x4000, v65
	v_readlane_b32 s80, v250, 6
	v_readlane_b32 s81, v250, 7
	v_readlane_b32 s82, v250, 8
	v_readlane_b32 s83, v250, 9
	s_lshl_b32 s1, s1, 19
	s_add_u32 s8, s15, s1
	s_mov_b32 s1, s9
	v_readlane_b32 s84, v250, 10
	v_readlane_b32 s85, v250, 11
	v_readlane_b32 s86, v250, 12
	v_readlane_b32 s87, v250, 13
	v_readlane_b32 s88, v250, 14
	v_readlane_b32 s89, v250, 15
	v_readlane_b32 s90, v250, 16
	v_readlane_b32 s91, v250, 17
	v_readlane_b32 s92, v250, 18
	v_readlane_b32 s93, v250, 19
	v_readlane_b32 s94, v250, 20
	v_readlane_b32 s95, v250, 21
	s_waitcnt vmcnt(1)
	v_mul_f32_e32 v48, v48, v66
	v_mul_f32_e32 v0, v0, v66
	v_mul_f32_e32 v49, v49, v66
	s_waitcnt vmcnt(0)
	v_mul_f32_e32 v32, v32, v64
	v_mul_f32_e32 v50, v50, v66
	v_mul_f32_e32 v51, v51, v66
	v_mul_f32_e32 v52, v52, v66
	v_mul_f32_e32 v53, v53, v66
	v_mul_f32_e32 v54, v54, v66
	v_mul_f32_e32 v55, v55, v66
	v_mul_f32_e32 v56, v56, v66
	v_mul_f32_e32 v57, v57, v66
	v_mul_f32_e32 v58, v58, v66
	v_mul_f32_e32 v59, v59, v66
	v_mul_f32_e32 v60, v60, v66
	v_mul_f32_e32 v61, v61, v66
	v_mul_f32_e32 v62, v62, v66
	v_mul_f32_e32 v63, v63, v66
	v_mul_f32_e32 v33, v33, v64
	v_mul_f32_e32 v34, v34, v64
	v_mul_f32_e32 v35, v35, v64
	v_mul_f32_e32 v36, v36, v64
	v_mul_f32_e32 v37, v37, v64
	v_mul_f32_e32 v38, v38, v64
	v_mul_f32_e32 v39, v39, v64
	v_mul_f32_e32 v40, v40, v64
	v_mul_f32_e32 v41, v41, v64
	v_mul_f32_e32 v42, v42, v64
	v_mul_f32_e32 v43, v43, v64
	v_mul_f32_e32 v44, v44, v64
	v_mul_f32_e32 v45, v45, v64
	v_mul_f32_e32 v46, v46, v64
	v_mul_f32_e32 v47, v47, v64
	v_mul_f32_e32 v16, v16, v64
	v_mul_f32_e32 v17, v17, v64
	ds_write2_b32 v65, v32, v48 offset1:32
	ds_write2_b32 v65, v33, v49 offset0:132 offset1:164
	ds_write2_b32 v67, v34, v50 offset0:8 offset1:40
	ds_write2_b32 v67, v35, v51 offset0:140 offset1:172
	ds_write2_b32 v69, v36, v52 offset0:32 offset1:64
	ds_write2_b32 v69, v37, v53 offset0:164 offset1:196
	ds_write2_b32 v70, v38, v54 offset0:40 offset1:72
	ds_write2_b32 v70, v39, v55 offset0:172 offset1:204
	ds_write2_b32 v71, v40, v56 offset0:64 offset1:96
	ds_write2_b32 v71, v41, v57 offset0:196 offset1:228
	ds_write2_b32 v72, v42, v58 offset0:72 offset1:104
	ds_write2_b32 v72, v43, v59 offset0:204 offset1:236
	ds_write2_b32 v73, v44, v60 offset0:96 offset1:128
	ds_write2_b32 v74, v45, v61 offset0:100 offset1:132
	ds_write2_b32 v75, v46, v62 offset0:104 offset1:136
	ds_write2_b32 v76, v47, v63 offset0:108 offset1:140
	ds_write2_b32 v77, v16, v0 offset0:128 offset1:160
	v_mul_f32_e32 v0, v1, v66
	v_add_u32_e32 v1, 0x4400, v65
	ds_write2_b32 v1, v17, v0 offset0:4 offset1:36
	v_mul_f32_e32 v0, v18, v64
	v_mul_f32_e32 v2, v2, v66
	ds_write2_b32 v1, v0, v2 offset0:136 offset1:168
	v_mul_f32_e32 v0, v19, v64
	v_mul_f32_e32 v1, v3, v66
	v_add_u32_e32 v2, 0x4800, v65
	ds_write2_b32 v2, v0, v1 offset0:12 offset1:44
	v_mul_f32_e32 v0, v20, v64
	v_mul_f32_e32 v1, v4, v66
	v_add_u32_e32 v2, 0x5000, v65
	ds_write2_b32 v2, v0, v1 offset0:160 offset1:192
	v_mul_f32_e32 v0, v21, v64
	v_mul_f32_e32 v1, v5, v66
	v_add_u32_e32 v2, 0x5400, v65
	ds_write2_b32 v2, v0, v1 offset0:36 offset1:68
	v_mul_f32_e32 v0, v22, v64
	v_mul_f32_e32 v1, v6, v66
	ds_write2_b32 v2, v0, v1 offset0:168 offset1:200
	v_mul_f32_e32 v0, v23, v64
	v_mul_f32_e32 v1, v7, v66
	v_add_u32_e32 v2, 0x5800, v65
	ds_write2_b32 v2, v0, v1 offset0:44 offset1:76
	v_mul_f32_e32 v0, v24, v64
	v_mul_f32_e32 v1, v8, v66
	v_add_u32_e32 v2, 0x6000, v65
	ds_write2_b32 v2, v0, v1 offset0:192 offset1:224
	v_mul_f32_e32 v0, v25, v64
	v_mul_f32_e32 v1, v9, v66
	v_add_u32_e32 v2, 0x6400, v65
	ds_write2_b32 v2, v0, v1 offset0:68 offset1:100
	v_mul_f32_e32 v0, v26, v64
	v_mul_f32_e32 v1, v10, v66
	ds_write2_b32 v2, v0, v1 offset0:200 offset1:232
	v_mul_f32_e32 v0, v27, v64
	v_mul_f32_e32 v1, v11, v66
	v_add_u32_e32 v2, 0x6800, v65
	ds_write2_b32 v2, v0, v1 offset0:76 offset1:108
	v_mul_f32_e32 v0, v28, v64
	v_mul_f32_e32 v1, v12, v66
	v_add_u32_e32 v2, 0x7200, v65
	ds_write2_b32 v2, v0, v1 offset0:96 offset1:128
	v_mul_f32_e32 v0, v29, v64
	v_mul_f32_e32 v1, v13, v66
	v_add_u32_e32 v2, 0x7400, v65
	ds_write2_b32 v2, v0, v1 offset0:100 offset1:132
	v_mul_f32_e32 v0, v30, v64
	v_mul_f32_e32 v1, v14, v66
	v_add_u32_e32 v2, 0x7600, v65
	v_and_b32_e32 v12, 31, v68
	ds_write2_b32 v2, v0, v1 offset0:104 offset1:136
	v_mul_f32_e32 v0, v31, v64
	v_mul_f32_e32 v1, v15, v66
	v_add_u32_e32 v2, 0x7800, v65
	v_lshlrev_b32_e32 v8, 2, v12
	ds_write2_b32 v2, v0, v1 offset0:108 offset1:140
	v_or_b32_e32 v0, s23, v8
	v_ashrrev_i32_e32 v1, 31, v0
	v_lshlrev_b64 v[0:1], 2, v[0:1]
	v_lshl_add_u64 v[2:3], s[80:81], 0, v[0:1]
	v_lshl_add_u64 v[4:5], s[82:83], 0, v[0:1]
	s_waitcnt lgkmcnt(0)
	s_barrier
	global_load_dwordx4 v[0:3], v[2:3], off
	s_nop 0
	global_load_dwordx4 v[4:7], v[4:5], off
	v_and_b32_e32 v9, 64, v108
	v_add_u32_e32 v9, 64, v9
	v_xor_b32_e32 v10, 1, v108
	v_cmp_lt_i32_e32 vcc, v10, v9
	s_addc_u32 s23, s17, 0
	s_lshl_b64 s[0:1], s[0:1], 12
	v_cndmask_b32_e32 v10, v108, v10, vcc
	v_lshlrev_b32_e32 v32, 2, v10
	v_xor_b32_e32 v10, 2, v108
	v_cmp_lt_i32_e32 vcc, v10, v9
	s_add_u32 s58, s24, s0
	s_addc_u32 s59, s25, s1
	v_cndmask_b32_e32 v10, v108, v10, vcc
	v_lshlrev_b32_e32 v33, 2, v10
	v_xor_b32_e32 v10, 4, v108
	v_cmp_lt_i32_e32 vcc, v10, v9
	s_and_b64 s[0:1], s[4:5], exec
	v_ashrrev_i32_e32 v22, 5, v68
	v_cndmask_b32_e32 v10, v108, v10, vcc
	v_lshlrev_b32_e32 v34, 2, v10
	v_xor_b32_e32 v10, 8, v108
	s_cselect_b32 s59, s23, s59
	s_cselect_b32 s58, s8, s58
	v_cmp_lt_i32_e32 vcc, v10, v9
	s_add_i32 s8, s22, s35
	v_add_u32_e32 v16, s8, v22
	v_cndmask_b32_e32 v10, v108, v10, vcc
	s_add_i32 s8, s22, s36
	s_add_i32 s22, s22, s37
	v_lshlrev_b32_e32 v35, 2, v10
	v_xor_b32_e32 v10, 16, v108
	v_add_u32_e32 v20, s8, v22
	v_add_u32_e32 v24, s22, v22
	v_cmp_eq_u32_e64 s[0:1], 0, v12
	v_cmp_lt_i32_e32 vcc, v10, v9
	v_ashrrev_i32_e32 v23, 31, v22
	v_mul_lo_u32 v13, v22, s52
	v_lshlrev_b32_e32 v12, 4, v12
	v_add_u32_e32 v26, s21, v22
	v_ashrrev_i32_e32 v17, 31, v16
	v_ashrrev_i32_e32 v21, 31, v20
	v_ashrrev_i32_e32 v25, 31, v24
	v_cndmask_b32_e32 v9, v108, v10, vcc
	v_add_u32_e32 v8, s20, v8
	v_lshlrev_b64 v[10:11], 12, v[22:23]
	v_add3_u32 v37, v13, v12, 32
	v_lshlrev_b32_e32 v12, 1, v26
	v_lshlrev_b64 v[14:15], 12, v[16:17]
	v_lshlrev_b32_e32 v16, 1, v16
	v_lshlrev_b64 v[18:19], 12, v[20:21]
	v_lshlrev_b32_e32 v20, 1, v20
	v_lshlrev_b64 v[22:23], 12, v[24:25]
	v_lshlrev_b32_e32 v24, 1, v24
	v_ashrrev_i32_e32 v27, 31, v26
	v_lshlrev_b32_e32 v36, 2, v9
	v_ashrrev_i32_e32 v9, 31, v8
	v_ashrrev_i32_e32 v13, 31, v12
	v_ashrrev_i32_e32 v17, 31, v16
	v_ashrrev_i32_e32 v21, 31, v20
	v_ashrrev_i32_e32 v25, 31, v24
	v_lshlrev_b64 v[26:27], 12, v[26:27]
	v_lshlrev_b64 v[8:9], 2, v[8:9]
	v_lshl_add_u64 v[10:11], s[58:59], 0, v[10:11]
	v_lshl_add_u64 v[12:13], v[12:13], 2, s[30:31]
	v_lshl_add_u64 v[14:15], s[28:29], 0, v[14:15]
	v_lshl_add_u64 v[16:17], v[16:17], 2, s[30:31]
	v_lshl_add_u64 v[18:19], s[28:29], 0, v[18:19]
	v_lshl_add_u64 v[20:21], v[20:21], 2, s[30:31]
	v_lshl_add_u64 v[22:23], s[28:29], 0, v[22:23]
	v_lshl_add_u64 v[24:25], v[24:25], 2, s[30:31]
	v_lshl_add_u64 v[26:27], s[6:7], 0, v[26:27]
	s_mov_b64 s[20:21], 0
	s_branch .LBB0_2065

.LBB0_2186:
	s_setprio 1
	ds_read_b128 v[140:143], v103
	ds_read_b128 v[144:147], v104 offset:36864
	ds_read_b128 v[148:151], v104 offset:41472
	ds_read_b128 v[192:195], v103 offset:4608
	s_waitcnt lgkmcnt(2)
	v_mfma_f32_32x32x16_bf16 v[48:63], v[140:143], v[144:147], v[48:63]
	global_load_dwordx4 v[108:111], v168, s[98:99] offset:3840
	global_load_dwordx4 v[112:115], v170, s[98:99] offset:3840
	s_waitcnt vmcnt(9)
	ds_write_b128 v105, v[68:71] offset:18432
	s_waitcnt lgkmcnt(2)
	v_mfma_f32_32x32x16_bf16 v[32:47], v[140:143], v[148:151], v[32:47]
	ds_read_b128 v[196:199], v103 offset:32
	ds_read_b128 v[200:203], v104 offset:36896
	global_load_dwordx4 v[116:119], v172, s[98:99] offset:3840
	global_load_dwordx4 v[120:123], v174, s[98:99] offset:3840
	s_waitcnt lgkmcnt(3)
	v_mfma_f32_32x32x16_bf16 v[16:31], v[192:195], v[144:147], v[16:31]
	ds_read_b128 v[204:207], v104 offset:41504
	global_load_dwordx4 v[124:127], v176, s[98:99] offset:3840
	global_load_dwordx4 v[128:131], v178, s[98:99] offset:3840
	s_waitcnt vmcnt(11)
	ds_write_b128 v105, v[84:87] offset:23040
	v_mfma_f32_32x32x16_bf16 v[0:15], v[192:195], v[148:151], v[0:15]
	ds_read_b128 v[208:211], v103 offset:4640
	global_load_dwordx4 v[132:135], v180, s[98:99] offset:3840
	global_load_dwordx4 v[136:139], v182, s[98:99] offset:3840
	s_waitcnt lgkmcnt(3)
	v_mfma_f32_32x32x16_bf16 v[48:63], v[196:199], v[200:203], v[48:63]
	s_waitcnt vmcnt(12)
	ds_write_b128 v105, v[88:91] offset:27648
	s_waitcnt lgkmcnt(3)
	v_mfma_f32_32x32x16_bf16 v[32:47], v[196:199], v[204:207], v[32:47]
	ds_read_b128 v[212:215], v103 offset:64
	ds_read_b128 v[216:219], v104 offset:36928
	s_waitcnt lgkmcnt(3)
	v_mfma_f32_32x32x16_bf16 v[16:31], v[208:211], v[200:203], v[16:31]
	ds_read_b128 v[220:223], v104 offset:41536
	s_waitcnt vmcnt(11)
	ds_write_b128 v105, v[92:95] offset:32256
	v_mfma_f32_32x32x16_bf16 v[0:15], v[208:211], v[204:207], v[0:15]
	ds_read_b128 v[224:227], v103 offset:4672
	s_waitcnt lgkmcnt(3)
	v_mfma_f32_32x32x16_bf16 v[48:63], v[212:215], v[216:219], v[48:63]
	ds_write_b128 v105, v[64:67] offset:55296
	s_waitcnt lgkmcnt(3)
	v_mfma_f32_32x32x16_bf16 v[32:47], v[212:215], v[220:223], v[32:47]
	ds_read_b128 v[228:231], v103 offset:96
	ds_read_b128 v[140:143], v104 offset:36960
	s_waitcnt lgkmcnt(3)
	v_mfma_f32_32x32x16_bf16 v[16:31], v[224:227], v[216:219], v[16:31]
	ds_read_b128 v[144:147], v104 offset:41568
	s_waitcnt vmcnt(10)
	ds_write_b128 v105, v[72:75] offset:59904
	v_mfma_f32_32x32x16_bf16 v[0:15], v[224:227], v[220:223], v[0:15]
	ds_read_b128 v[148:151], v103 offset:4704
	s_waitcnt lgkmcnt(3)
	v_mfma_f32_32x32x16_bf16 v[48:63], v[228:231], v[140:143], v[48:63]
	s_waitcnt vmcnt(9)
	ds_write_b128 v105, v[76:79] offset:64512
	s_waitcnt lgkmcnt(3)
	v_mfma_f32_32x32x16_bf16 v[32:47], v[228:231], v[144:147], v[32:47]
	s_waitcnt lgkmcnt(1)
	v_mfma_f32_32x32x16_bf16 v[16:31], v[148:151], v[140:143], v[16:31]
	s_waitcnt vmcnt(8)
	ds_write_b128 v106, v[80:83] offset:13824
	v_mfma_f32_32x32x16_bf16 v[0:15], v[148:151], v[144:147], v[0:15]
	s_setprio 0
	s_waitcnt lgkmcnt(0)
	s_barrier
	s_setprio 1
	ds_read_b128 v[140:143], v103 offset:18432
	ds_read_b128 v[144:147], v104 offset:55296
	ds_read_b128 v[148:151], v104 offset:59904
	ds_read_b128 v[192:195], v103 offset:23040
	s_waitcnt lgkmcnt(2)
	v_mfma_f32_32x32x16_bf16 v[48:63], v[140:143], v[144:147], v[48:63]
	global_load_dwordx4 v[68:71], v168, s[98:99] offset:3968
	global_load_dwordx4 v[84:87], v170, s[98:99] offset:3968
	s_waitcnt vmcnt(9)
	ds_write_b128 v105, v[108:111]
	s_waitcnt lgkmcnt(2)
	v_mfma_f32_32x32x16_bf16 v[32:47], v[140:143], v[148:151], v[32:47]
	ds_read_b128 v[196:199], v103 offset:18464
	ds_read_b128 v[200:203], v104 offset:55328
	global_load_dwordx4 v[88:91], v172, s[98:99] offset:3968
	global_load_dwordx4 v[92:95], v174, s[98:99] offset:3968
	s_waitcnt lgkmcnt(3)
	v_mfma_f32_32x32x16_bf16 v[16:31], v[192:195], v[144:147], v[16:31]
	ds_read_b128 v[204:207], v104 offset:59936
	global_load_dwordx4 v[64:67], v176, s[98:99] offset:3968
	global_load_dwordx4 v[72:75], v178, s[98:99] offset:3968
	s_waitcnt vmcnt(12)
	ds_write_b128 v105, v[112:115] offset:4608
	v_mfma_f32_32x32x16_bf16 v[0:15], v[192:195], v[148:151], v[0:15]
	ds_read_b128 v[208:211], v103 offset:23072
	global_load_dwordx4 v[76:79], v180, s[98:99] offset:3968
	global_load_dwordx4 v[80:83], v182, s[98:99] offset:3968
	s_waitcnt lgkmcnt(3)
	v_mfma_f32_32x32x16_bf16 v[48:63], v[196:199], v[200:203], v[48:63]
	s_add_u32 s98, s98, 0x100
	s_addc_u32 s99, s99, 0
	s_add_i32 s4, s4, 2
	s_cmp_lt_u32 s4, 11
	s_waitcnt vmcnt(13)
	ds_write_b128 v105, v[116:119] offset:9216
	s_waitcnt lgkmcnt(3)
	v_mfma_f32_32x32x16_bf16 v[32:47], v[196:199], v[204:207], v[32:47]
	ds_read_b128 v[212:215], v103 offset:18496
	ds_read_b128 v[216:219], v104 offset:55360
	s_waitcnt lgkmcnt(3)
	v_mfma_f32_32x32x16_bf16 v[16:31], v[208:211], v[200:203], v[16:31]
	ds_read_b128 v[220:223], v104 offset:59968
	s_waitcnt vmcnt(12)
	ds_write_b128 v105, v[120:123] offset:13824
	v_mfma_f32_32x32x16_bf16 v[0:15], v[208:211], v[204:207], v[0:15]
	ds_read_b128 v[224:227], v103 offset:23104
	s_waitcnt lgkmcnt(3)
	v_mfma_f32_32x32x16_bf16 v[48:63], v[212:215], v[216:219], v[48:63]
	s_waitcnt vmcnt(11)
	ds_write_b128 v105, v[124:127] offset:36864
	s_waitcnt lgkmcnt(3)
	v_mfma_f32_32x32x16_bf16 v[32:47], v[212:215], v[220:223], v[32:47]
	ds_read_b128 v[228:231], v103 offset:18528
	ds_read_b128 v[140:143], v104 offset:55392
	s_waitcnt lgkmcnt(3)
	v_mfma_f32_32x32x16_bf16 v[16:31], v[224:227], v[216:219], v[16:31]
	ds_read_b128 v[144:147], v104 offset:60000
	s_waitcnt vmcnt(10)
	ds_write_b128 v105, v[128:131] offset:41472
	v_mfma_f32_32x32x16_bf16 v[0:15], v[224:227], v[220:223], v[0:15]
	ds_read_b128 v[148:151], v103 offset:23136
	s_waitcnt lgkmcnt(3)
	v_mfma_f32_32x32x16_bf16 v[48:63], v[228:231], v[140:143], v[48:63]
	s_waitcnt vmcnt(9)
	ds_write_b128 v105, v[132:135] offset:46080
	s_waitcnt lgkmcnt(3)
	v_mfma_f32_32x32x16_bf16 v[32:47], v[228:231], v[144:147], v[32:47]
	s_waitcnt lgkmcnt(1)
	v_mfma_f32_32x32x16_bf16 v[16:31], v[148:151], v[140:143], v[16:31]
	s_waitcnt vmcnt(8)
	ds_write_b128 v105, v[136:139] offset:50688
	v_mfma_f32_32x32x16_bf16 v[0:15], v[148:151], v[144:147], v[0:15]
	s_setprio 0
	s_waitcnt lgkmcnt(0)
	s_barrier
	s_cbranch_scc1 .LBB0_2186
	s_setprio 1
	ds_read_b128 v[98:101], v103
	ds_read_b128 v[108:111], v104 offset:36864
	ds_read_b128 v[112:115], v104 offset:41472
	ds_read_b128 v[192:195], v103 offset:4608
	s_waitcnt lgkmcnt(2)
	v_mfma_f32_32x32x16_bf16 v[48:63], v[98:101], v[108:111], v[48:63]
	s_waitcnt vmcnt(7)
	ds_write_b128 v105, v[68:71] offset:18432
	s_waitcnt lgkmcnt(2)
	v_mfma_f32_32x32x16_bf16 v[32:47], v[98:101], v[112:115], v[32:47]
	ds_read_b128 v[196:199], v103 offset:32
	ds_read_b128 v[200:203], v104 offset:36896
	s_waitcnt lgkmcnt(3)
	v_mfma_f32_32x32x16_bf16 v[16:31], v[192:195], v[108:111], v[16:31]
	ds_read_b128 v[204:207], v104 offset:41504
	s_waitcnt vmcnt(6)
	ds_write_b128 v105, v[84:87] offset:23040
	v_mfma_f32_32x32x16_bf16 v[0:15], v[192:195], v[112:115], v[0:15]
	ds_read_b128 v[208:211], v103 offset:4640
	s_waitcnt lgkmcnt(3)
	v_mfma_f32_32x32x16_bf16 v[48:63], v[196:199], v[200:203], v[48:63]
	s_waitcnt vmcnt(5)
	ds_write_b128 v105, v[88:91] offset:27648
	s_waitcnt lgkmcnt(3)
	v_mfma_f32_32x32x16_bf16 v[32:47], v[196:199], v[204:207], v[32:47]
	ds_read_b128 v[212:215], v103 offset:64
	ds_read_b128 v[216:219], v104 offset:36928
	s_waitcnt lgkmcnt(3)
	v_mfma_f32_32x32x16_bf16 v[16:31], v[208:211], v[200:203], v[16:31]
	ds_read_b128 v[220:223], v104 offset:41536
	s_waitcnt vmcnt(4)
	ds_write_b128 v105, v[92:95] offset:32256
	v_mfma_f32_32x32x16_bf16 v[0:15], v[208:211], v[204:207], v[0:15]
	ds_read_b128 v[224:227], v103 offset:4672
	s_waitcnt lgkmcnt(3)
	v_mfma_f32_32x32x16_bf16 v[48:63], v[212:215], v[216:219], v[48:63]
	s_waitcnt vmcnt(3)
	ds_write_b128 v105, v[64:67] offset:55296
	s_waitcnt lgkmcnt(3)
	v_mfma_f32_32x32x16_bf16 v[32:47], v[212:215], v[220:223], v[32:47]
	ds_read_b128 v[228:231], v103 offset:96
	ds_read_b128 v[98:101], v104 offset:36960
	s_waitcnt lgkmcnt(3)
	v_mfma_f32_32x32x16_bf16 v[16:31], v[224:227], v[216:219], v[16:31]
	ds_read_b128 v[108:111], v104 offset:41568
	s_waitcnt vmcnt(2)
	ds_write_b128 v105, v[72:75] offset:59904
	v_mfma_f32_32x32x16_bf16 v[0:15], v[224:227], v[220:223], v[0:15]
	ds_read_b128 v[112:115], v103 offset:4704
	s_waitcnt lgkmcnt(3)
	v_mfma_f32_32x32x16_bf16 v[48:63], v[228:231], v[98:101], v[48:63]
	s_waitcnt vmcnt(1)
	ds_write_b128 v105, v[76:79] offset:64512
	s_waitcnt lgkmcnt(3)
	v_mfma_f32_32x32x16_bf16 v[32:47], v[228:231], v[108:111], v[32:47]
	s_waitcnt lgkmcnt(1)
	v_mfma_f32_32x32x16_bf16 v[16:31], v[112:115], v[98:101], v[16:31]
	s_waitcnt vmcnt(0)
	ds_write_b128 v106, v[80:83] offset:13824
	v_mfma_f32_32x32x16_bf16 v[0:15], v[112:115], v[108:111], v[0:15]
	s_setprio 0
	s_waitcnt lgkmcnt(0)
	s_barrier
	s_setprio 1
	ds_read_b128 v[64:67], v103 offset:18432
	ds_read_b128 v[68:71], v104 offset:55296
	ds_read_b128 v[72:75], v104 offset:59904
	ds_read_b128 v[192:195], v103 offset:23040
	s_waitcnt lgkmcnt(2)
	v_mfma_f32_32x32x16_bf16 v[48:63], v[64:67], v[68:71], v[48:63]
	s_waitcnt lgkmcnt(1)
	v_mfma_f32_32x32x16_bf16 v[32:47], v[64:67], v[72:75], v[32:47]
	ds_read_b128 v[196:199], v103 offset:18464
	ds_read_b128 v[200:203], v104 offset:55328
	s_waitcnt lgkmcnt(2)
	v_mfma_f32_32x32x16_bf16 v[16:31], v[192:195], v[68:71], v[16:31]
	ds_read_b128 v[204:207], v104 offset:59936
	v_mfma_f32_32x32x16_bf16 v[0:15], v[192:195], v[72:75], v[0:15]
	ds_read_b128 v[208:211], v103 offset:23072
	s_waitcnt lgkmcnt(2)
	v_mfma_f32_32x32x16_bf16 v[48:63], v[196:199], v[200:203], v[48:63]
	s_waitcnt lgkmcnt(1)
	v_mfma_f32_32x32x16_bf16 v[32:47], v[196:199], v[204:207], v[32:47]
	ds_read_b128 v[212:215], v103 offset:18496
	ds_read_b128 v[216:219], v104 offset:55360
	s_waitcnt lgkmcnt(2)
	v_mfma_f32_32x32x16_bf16 v[16:31], v[208:211], v[200:203], v[16:31]
	ds_read_b128 v[220:223], v104 offset:59968
	v_mfma_f32_32x32x16_bf16 v[0:15], v[208:211], v[204:207], v[0:15]
	ds_read_b128 v[224:227], v103 offset:23104
	s_waitcnt lgkmcnt(2)
	v_mfma_f32_32x32x16_bf16 v[48:63], v[212:215], v[216:219], v[48:63]
	s_waitcnt lgkmcnt(1)
	v_mfma_f32_32x32x16_bf16 v[32:47], v[212:215], v[220:223], v[32:47]
	ds_read_b128 v[228:231], v103 offset:18528
	ds_read_b128 v[64:67], v104 offset:55392
	s_waitcnt lgkmcnt(2)
	v_mfma_f32_32x32x16_bf16 v[16:31], v[224:227], v[216:219], v[16:31]
	ds_read_b128 v[68:71], v104 offset:60000
	v_mfma_f32_32x32x16_bf16 v[0:15], v[224:227], v[220:223], v[0:15]
	ds_read_b128 v[72:75], v103 offset:23136
	s_waitcnt lgkmcnt(2)
	v_mfma_f32_32x32x16_bf16 v[48:63], v[228:231], v[64:67], v[48:63]
	s_waitcnt lgkmcnt(1)
	v_mfma_f32_32x32x16_bf16 v[32:47], v[228:231], v[68:71], v[32:47]
	s_waitcnt lgkmcnt(0)
	v_mfma_f32_32x32x16_bf16 v[16:31], v[72:75], v[64:67], v[16:31]
	v_mfma_f32_32x32x16_bf16 v[0:15], v[72:75], v[68:71], v[0:15]
	s_setprio 0
	s_cmpk_gt_u32 s22, 0xfff
	s_cselect_b64 s[10:11], -1, 0
	s_cmpk_lt_u32 s22, 0x1000
	s_cselect_b64 s[40:41], -1, 0
	s_ashr_i32 s61, s2, 2
	s_cmp_lt_i32 s61, 7
	s_barrier
	s_cbranch_scc1 .LBB0_2189
	s_cmp_lg_u32 s61, 7
	s_cselect_b64 s[4:5], -1, 0
	s_cbranch_execz .LBB0_2190
	s_branch .LBB0_2191

.LBB0_3734:
	s_setprio 1
	ds_read_b128 v[148:151], v112
	ds_read_b128 v[152:155], v113 offset:36864
	ds_read_b128 v[156:159], v113 offset:41472
	ds_read_b128 v[192:195], v112 offset:4608
	s_waitcnt lgkmcnt(2)
	v_mfma_f32_32x32x16_bf16 v[48:63], v[148:151], v[152:155], v[48:63]
	global_load_dwordx4 v[116:119], v176, s[98:99] offset:256
	global_load_dwordx4 v[120:123], v180, s[98:99] offset:256
	s_waitcnt vmcnt(9)
	ds_write_b128 v114, v[64:67] offset:18432
	s_waitcnt lgkmcnt(2)
	v_mfma_f32_32x32x16_bf16 v[32:47], v[148:151], v[156:159], v[32:47]
	ds_read_b128 v[196:199], v112 offset:32
	ds_read_b128 v[200:203], v113 offset:36896
	global_load_dwordx4 v[124:127], v182, s[98:99] offset:256
	global_load_dwordx4 v[128:131], v184, s[98:99] offset:256
	s_waitcnt lgkmcnt(3)
	v_mfma_f32_32x32x16_bf16 v[16:31], v[192:195], v[152:155], v[16:31]
	ds_read_b128 v[204:207], v113 offset:41504
	global_load_dwordx4 v[132:135], v178, s[98:99]
	global_load_dwordx4 v[136:139], v98, s[98:99]
	s_waitcnt vmcnt(12)
	ds_write_b128 v114, v[68:71] offset:23040
	v_mfma_f32_32x32x16_bf16 v[0:15], v[192:195], v[156:159], v[0:15]
	ds_read_b128 v[208:211], v112 offset:4640
	global_load_dwordx4 v[140:143], v186, s[98:99]
	global_load_dwordx4 v[144:147], v188, s[98:99] offset:-128
	s_waitcnt lgkmcnt(3)
	v_mfma_f32_32x32x16_bf16 v[48:63], v[196:199], v[200:203], v[48:63]
	s_waitcnt vmcnt(13)
	ds_write_b128 v114, v[72:75] offset:27648
	s_waitcnt lgkmcnt(3)
	v_mfma_f32_32x32x16_bf16 v[32:47], v[196:199], v[204:207], v[32:47]
	ds_read_b128 v[212:215], v112 offset:64
	ds_read_b128 v[216:219], v113 offset:36928
	s_waitcnt lgkmcnt(3)
	v_mfma_f32_32x32x16_bf16 v[16:31], v[208:211], v[200:203], v[16:31]
	ds_read_b128 v[220:223], v113 offset:41536
	s_waitcnt vmcnt(12)
	ds_write_b128 v114, v[76:79] offset:32256
	v_mfma_f32_32x32x16_bf16 v[0:15], v[208:211], v[204:207], v[0:15]
	ds_read_b128 v[224:227], v112 offset:4672
	s_waitcnt lgkmcnt(3)
	v_mfma_f32_32x32x16_bf16 v[48:63], v[212:215], v[216:219], v[48:63]
	s_waitcnt vmcnt(11)
	ds_write_b128 v114, v[80:83] offset:55296
	s_waitcnt lgkmcnt(3)
	v_mfma_f32_32x32x16_bf16 v[32:47], v[212:215], v[220:223], v[32:47]
	ds_read_b128 v[228:231], v112 offset:96
	ds_read_b128 v[148:151], v113 offset:36960
	s_waitcnt lgkmcnt(3)
	v_mfma_f32_32x32x16_bf16 v[16:31], v[224:227], v[216:219], v[16:31]
	ds_read_b128 v[152:155], v113 offset:41568
	s_waitcnt vmcnt(10)
	ds_write_b128 v114, v[84:87] offset:59904
	v_mfma_f32_32x32x16_bf16 v[0:15], v[224:227], v[220:223], v[0:15]
	ds_read_b128 v[156:159], v112 offset:4704
	s_waitcnt lgkmcnt(3)
	v_mfma_f32_32x32x16_bf16 v[48:63], v[228:231], v[148:151], v[48:63]
	s_waitcnt vmcnt(9)
	ds_write_b128 v114, v[88:91] offset:64512
	s_waitcnt lgkmcnt(3)
	v_mfma_f32_32x32x16_bf16 v[32:47], v[228:231], v[152:155], v[32:47]
	s_waitcnt lgkmcnt(1)
	v_mfma_f32_32x32x16_bf16 v[16:31], v[156:159], v[148:151], v[16:31]
	s_waitcnt vmcnt(8)
	ds_write_b128 v115, v[92:95] offset:13824
	v_mfma_f32_32x32x16_bf16 v[0:15], v[156:159], v[152:155], v[0:15]
	s_setprio 0
	s_waitcnt lgkmcnt(0)
	s_barrier
	s_setprio 1
	ds_read_b128 v[148:151], v112 offset:18432
	ds_read_b128 v[152:155], v113 offset:55296
	ds_read_b128 v[156:159], v113 offset:59904
	ds_read_b128 v[192:195], v112 offset:23040
	s_waitcnt lgkmcnt(2)
	v_mfma_f32_32x32x16_bf16 v[48:63], v[148:151], v[152:155], v[48:63]
	global_load_dwordx4 v[64:67], v176, s[98:99] offset:384
	global_load_dwordx4 v[68:71], v180, s[98:99] offset:384
	s_waitcnt vmcnt(9)
	ds_write_b128 v114, v[116:119]
	s_waitcnt lgkmcnt(2)
	v_mfma_f32_32x32x16_bf16 v[32:47], v[148:151], v[156:159], v[32:47]
	ds_read_b128 v[196:199], v112 offset:18464
	ds_read_b128 v[200:203], v113 offset:55328
	global_load_dwordx4 v[72:75], v182, s[98:99] offset:384
	global_load_dwordx4 v[76:79], v184, s[98:99] offset:384
	s_waitcnt lgkmcnt(3)
	v_mfma_f32_32x32x16_bf16 v[16:31], v[192:195], v[152:155], v[16:31]
	ds_read_b128 v[204:207], v113 offset:59936
	global_load_dwordx4 v[80:83], v178, s[98:99] offset:128
	global_load_dwordx4 v[84:87], v99, s[98:99]
	s_waitcnt vmcnt(12)
	ds_write_b128 v114, v[120:123] offset:4608
	v_mfma_f32_32x32x16_bf16 v[0:15], v[192:195], v[156:159], v[0:15]
	ds_read_b128 v[208:211], v112 offset:23072
	global_load_dwordx4 v[88:91], v186, s[98:99] offset:128
	global_load_dwordx4 v[92:95], v188, s[98:99]
	s_waitcnt lgkmcnt(3)
	v_mfma_f32_32x32x16_bf16 v[48:63], v[196:199], v[200:203], v[48:63]
	s_add_u32 s98, s98, 0x100
	s_addc_u32 s99, s99, 0
	s_add_i32 s0, s0, 2
	s_cmp_lt_u32 s0, 3
	s_waitcnt vmcnt(13)
	ds_write_b128 v114, v[124:127] offset:9216
	s_waitcnt lgkmcnt(3)
	v_mfma_f32_32x32x16_bf16 v[32:47], v[196:199], v[204:207], v[32:47]
	ds_read_b128 v[212:215], v112 offset:18496
	ds_read_b128 v[216:219], v113 offset:55360
	s_waitcnt lgkmcnt(3)
	v_mfma_f32_32x32x16_bf16 v[16:31], v[208:211], v[200:203], v[16:31]
	ds_read_b128 v[220:223], v113 offset:59968
	s_waitcnt vmcnt(12)
	ds_write_b128 v114, v[128:131] offset:13824
	v_mfma_f32_32x32x16_bf16 v[0:15], v[208:211], v[204:207], v[0:15]
	ds_read_b128 v[224:227], v112 offset:23104
	s_waitcnt lgkmcnt(3)
	v_mfma_f32_32x32x16_bf16 v[48:63], v[212:215], v[216:219], v[48:63]
	s_waitcnt vmcnt(11)
	ds_write_b128 v114, v[132:135] offset:36864
	s_waitcnt lgkmcnt(3)
	v_mfma_f32_32x32x16_bf16 v[32:47], v[212:215], v[220:223], v[32:47]
	ds_read_b128 v[228:231], v112 offset:18528
	ds_read_b128 v[148:151], v113 offset:55392
	s_waitcnt lgkmcnt(3)
	v_mfma_f32_32x32x16_bf16 v[16:31], v[224:227], v[216:219], v[16:31]
	ds_read_b128 v[152:155], v113 offset:60000
	s_waitcnt vmcnt(10)
	ds_write_b128 v114, v[136:139] offset:41472
	v_mfma_f32_32x32x16_bf16 v[0:15], v[224:227], v[220:223], v[0:15]
	ds_read_b128 v[156:159], v112 offset:23136
	s_waitcnt lgkmcnt(3)
	v_mfma_f32_32x32x16_bf16 v[48:63], v[228:231], v[148:151], v[48:63]
	s_waitcnt vmcnt(9)
	ds_write_b128 v114, v[140:143] offset:46080
	s_waitcnt lgkmcnt(3)
	v_mfma_f32_32x32x16_bf16 v[32:47], v[228:231], v[152:155], v[32:47]
	s_waitcnt lgkmcnt(1)
	v_mfma_f32_32x32x16_bf16 v[16:31], v[156:159], v[148:151], v[16:31]
	s_waitcnt vmcnt(8)
	ds_write_b128 v114, v[144:147] offset:50688
	v_mfma_f32_32x32x16_bf16 v[0:15], v[156:159], v[152:155], v[0:15]
	s_setprio 0
	s_waitcnt lgkmcnt(0)
	s_barrier
	s_cbranch_scc1 .LBB0_3734
	s_setprio 1
	ds_read_b128 v[98:101], v112
	ds_read_b128 v[102:105], v113 offset:36864
	ds_read_b128 v[106:109], v113 offset:41472
	ds_read_b128 v[192:195], v112 offset:4608
	s_waitcnt lgkmcnt(2)
	v_mfma_f32_32x32x16_bf16 v[48:63], v[98:101], v[102:105], v[48:63]
	s_waitcnt vmcnt(7)
	ds_write_b128 v114, v[64:67] offset:18432
	s_waitcnt lgkmcnt(2)
	v_mfma_f32_32x32x16_bf16 v[32:47], v[98:101], v[106:109], v[32:47]
	ds_read_b128 v[196:199], v112 offset:32
	ds_read_b128 v[200:203], v113 offset:36896
	s_waitcnt lgkmcnt(3)
	v_mfma_f32_32x32x16_bf16 v[16:31], v[192:195], v[102:105], v[16:31]
	ds_read_b128 v[204:207], v113 offset:41504
	s_waitcnt vmcnt(6)
	ds_write_b128 v114, v[68:71] offset:23040
	v_mfma_f32_32x32x16_bf16 v[0:15], v[192:195], v[106:109], v[0:15]
	ds_read_b128 v[208:211], v112 offset:4640
	s_waitcnt lgkmcnt(3)
	v_mfma_f32_32x32x16_bf16 v[48:63], v[196:199], v[200:203], v[48:63]
	s_waitcnt vmcnt(5)
	ds_write_b128 v114, v[72:75] offset:27648
	s_waitcnt lgkmcnt(3)
	v_mfma_f32_32x32x16_bf16 v[32:47], v[196:199], v[204:207], v[32:47]
	ds_read_b128 v[212:215], v112 offset:64
	ds_read_b128 v[216:219], v113 offset:36928
	s_waitcnt lgkmcnt(3)
	v_mfma_f32_32x32x16_bf16 v[16:31], v[208:211], v[200:203], v[16:31]
	ds_read_b128 v[220:223], v113 offset:41536
	s_waitcnt vmcnt(4)
	ds_write_b128 v114, v[76:79] offset:32256
	v_mfma_f32_32x32x16_bf16 v[0:15], v[208:211], v[204:207], v[0:15]
	ds_read_b128 v[224:227], v112 offset:4672
	s_waitcnt lgkmcnt(3)
	v_mfma_f32_32x32x16_bf16 v[48:63], v[212:215], v[216:219], v[48:63]
	s_waitcnt vmcnt(3)
	ds_write_b128 v114, v[80:83] offset:55296
	s_waitcnt lgkmcnt(3)
	v_mfma_f32_32x32x16_bf16 v[32:47], v[212:215], v[220:223], v[32:47]
	ds_read_b128 v[228:231], v113 offset:36960
	ds_read_b128 v[98:101], v112 offset:4704
	s_waitcnt lgkmcnt(3)
	v_mfma_f32_32x32x16_bf16 v[16:31], v[224:227], v[216:219], v[16:31]
	ds_read_b128 v[102:105], v113 offset:41568
	s_waitcnt vmcnt(2)
	ds_write_b128 v114, v[84:87] offset:59904
	v_mfma_f32_32x32x16_bf16 v[0:15], v[224:227], v[220:223], v[0:15]
	ds_read_b128 v[106:109], v112 offset:96
	s_waitcnt lgkmcnt(3)
	v_mfma_f32_32x32x16_bf16 v[16:31], v[98:101], v[228:231], v[16:31]
	s_waitcnt vmcnt(1)
	ds_write_b128 v114, v[88:91] offset:64512
	s_waitcnt lgkmcnt(3)
	v_mfma_f32_32x32x16_bf16 v[0:15], v[98:101], v[102:105], v[0:15]
	s_waitcnt lgkmcnt(1)
	v_mfma_f32_32x32x16_bf16 v[48:63], v[106:109], v[228:231], v[48:63]
	s_waitcnt vmcnt(0)
	ds_write_b128 v115, v[92:95] offset:13824
	v_mfma_f32_32x32x16_bf16 v[32:47], v[106:109], v[102:105], v[32:47]
	s_setprio 0
	s_waitcnt lgkmcnt(0)
	s_barrier
	s_setprio 1
	ds_read_b128 v[64:67], v112 offset:18432
	ds_read_b128 v[68:71], v113 offset:55296
	ds_read_b128 v[72:75], v113 offset:59904
	ds_read_b128 v[192:195], v112 offset:23040
	s_waitcnt lgkmcnt(2)
	v_mfma_f32_32x32x16_bf16 v[48:63], v[64:67], v[68:71], v[48:63]
	s_waitcnt lgkmcnt(1)
	v_mfma_f32_32x32x16_bf16 v[32:47], v[64:67], v[72:75], v[32:47]
	ds_read_b128 v[196:199], v112 offset:18464
	ds_read_b128 v[200:203], v113 offset:55328
	s_waitcnt lgkmcnt(2)
	v_mfma_f32_32x32x16_bf16 v[16:31], v[192:195], v[68:71], v[16:31]
	ds_read_b128 v[204:207], v113 offset:59936
	v_mfma_f32_32x32x16_bf16 v[0:15], v[192:195], v[72:75], v[0:15]
	ds_read_b128 v[208:211], v112 offset:23072
	s_waitcnt lgkmcnt(2)
	v_mfma_f32_32x32x16_bf16 v[48:63], v[196:199], v[200:203], v[48:63]
	s_waitcnt lgkmcnt(1)
	v_mfma_f32_32x32x16_bf16 v[32:47], v[196:199], v[204:207], v[32:47]
	ds_read_b128 v[212:215], v112 offset:18496
	ds_read_b128 v[216:219], v113 offset:55360
	s_waitcnt lgkmcnt(2)
	v_mfma_f32_32x32x16_bf16 v[16:31], v[208:211], v[200:203], v[16:31]
	ds_read_b128 v[220:223], v113 offset:59968
	v_mfma_f32_32x32x16_bf16 v[0:15], v[208:211], v[204:207], v[0:15]
	ds_read_b128 v[224:227], v112 offset:23104
	s_waitcnt lgkmcnt(2)
	v_mfma_f32_32x32x16_bf16 v[48:63], v[212:215], v[216:219], v[48:63]
	s_waitcnt lgkmcnt(1)
	v_mfma_f32_32x32x16_bf16 v[32:47], v[212:215], v[220:223], v[32:47]
	ds_read_b128 v[228:231], v113 offset:55392
	ds_read_b128 v[64:67], v112 offset:23136
	s_waitcnt lgkmcnt(2)
	v_mfma_f32_32x32x16_bf16 v[16:31], v[224:227], v[216:219], v[16:31]
	ds_read_b128 v[68:71], v113 offset:60000
	v_mfma_f32_32x32x16_bf16 v[0:15], v[224:227], v[220:223], v[0:15]
	ds_read_b128 v[72:75], v112 offset:18528
	s_waitcnt lgkmcnt(2)
	v_mfma_f32_32x32x16_bf16 v[16:31], v[64:67], v[228:231], v[16:31]
	s_waitcnt lgkmcnt(1)
	v_mfma_f32_32x32x16_bf16 v[0:15], v[64:67], v[68:71], v[0:15]
	s_waitcnt lgkmcnt(0)
	v_mfma_f32_32x32x16_bf16 v[48:63], v[72:75], v[228:231], v[48:63]
	v_mfma_f32_32x32x16_bf16 v[32:47], v[72:75], v[68:71], v[32:47]
	s_setprio 0
	s_nop 10
	v_cvt_pk_bf16_f32 v32, v32, s0
	v_cvt_pk_bf16_f32 v0, v0, s0
	s_barrier
	ds_write_b16 v111, v32 offset:64
	v_cvt_pk_bf16_f32 v32, v49, s0
	ds_write_b16 v111, v0 offset:8768
	v_cvt_pk_bf16_f32 v0, v17, s0
	ds_write_b16 v111, v32 offset:272
	v_cvt_pk_bf16_f32 v32, v33, s0
	ds_write_b16 v111, v0 offset:8976
	v_cvt_pk_bf16_f32 v0, v1, s0
	ds_write_b16 v111, v32 offset:336
	v_cvt_pk_bf16_f32 v32, v50, s0
	ds_write_b16 v111, v0 offset:9040
	v_cvt_pk_bf16_f32 v0, v18, s0
	ds_write_b16 v111, v32 offset:544
	v_cvt_pk_bf16_f32 v32, v34, s0
	ds_write_b16 v111, v0 offset:9248
	v_cvt_pk_bf16_f32 v0, v2, s0
	ds_write_b16 v111, v32 offset:608
	v_cvt_pk_bf16_f32 v32, v51, s0
	ds_write_b16 v111, v0 offset:9312
	v_cvt_pk_bf16_f32 v0, v19, s0
	ds_write_b16 v111, v32 offset:816
	v_cvt_pk_bf16_f32 v32, v35, s0
	ds_write_b16 v111, v0 offset:9520
	v_cvt_pk_bf16_f32 v0, v3, s0
	ds_write_b16 v111, v32 offset:880
	v_cvt_pk_bf16_f32 v32, v52, s0
	ds_write_b16 v111, v0 offset:9584
	v_cvt_pk_bf16_f32 v0, v20, s0
	ds_write_b16 v111, v32 offset:2176
	v_cvt_pk_bf16_f32 v32, v36, s0
	ds_write_b16 v111, v0 offset:10880
	v_cvt_pk_bf16_f32 v0, v4, s0
	ds_write_b16 v111, v32 offset:2240
	v_cvt_pk_bf16_f32 v32, v53, s0
	ds_write_b16 v111, v0 offset:10944
	v_cvt_pk_bf16_f32 v0, v21, s0
	ds_write_b16 v111, v32 offset:2448
	v_cvt_pk_bf16_f32 v32, v37, s0
	ds_write_b16 v111, v0 offset:11152
	v_cvt_pk_bf16_f32 v0, v5, s0
	ds_write_b16 v111, v32 offset:2512
	v_cvt_pk_bf16_f32 v32, v54, s0
	ds_write_b16 v111, v0 offset:11216
	v_cvt_pk_bf16_f32 v0, v22, s0
	ds_write_b16 v111, v32 offset:2720
	v_cvt_pk_bf16_f32 v32, v38, s0
	ds_write_b16 v111, v0 offset:11424
	v_cvt_pk_bf16_f32 v0, v6, s0
	ds_write_b16 v111, v32 offset:2784
	v_cvt_pk_bf16_f32 v32, v55, s0
	ds_write_b16 v111, v0 offset:11488
	v_cvt_pk_bf16_f32 v0, v23, s0
	ds_write_b16 v111, v32 offset:2992
	v_cvt_pk_bf16_f32 v32, v39, s0
	ds_write_b16 v111, v0 offset:11696
	v_cvt_pk_bf16_f32 v0, v7, s0
	ds_write_b16 v111, v32 offset:3056
	v_cvt_pk_bf16_f32 v32, v56, s0
	ds_write_b16 v111, v0 offset:11760
	v_cvt_pk_bf16_f32 v0, v24, s0
	ds_write_b16 v111, v32 offset:4352
	v_cvt_pk_bf16_f32 v32, v40, s0
	ds_write_b16 v111, v0 offset:13056
	v_cvt_pk_bf16_f32 v0, v8, s0
	ds_write_b16 v111, v32 offset:4416
	v_cvt_pk_bf16_f32 v32, v57, s0
	ds_write_b16 v111, v0 offset:13120
	v_cvt_pk_bf16_f32 v0, v25, s0
	ds_write_b16 v111, v32 offset:4624
	v_cvt_pk_bf16_f32 v32, v41, s0
	ds_write_b16 v111, v0 offset:13328
	v_cvt_pk_bf16_f32 v0, v9, s0
	ds_write_b16 v111, v32 offset:4688
	v_cvt_pk_bf16_f32 v32, v58, s0
	ds_write_b16 v111, v0 offset:13392
	v_cvt_pk_bf16_f32 v0, v26, s0
	ds_write_b16 v111, v32 offset:4896
	v_cvt_pk_bf16_f32 v32, v42, s0
	ds_write_b16 v111, v0 offset:13600
	v_cvt_pk_bf16_f32 v0, v10, s0
	ds_write_b16 v111, v32 offset:4960
	v_cvt_pk_bf16_f32 v32, v59, s0
	ds_write_b16 v111, v0 offset:13664
	v_cvt_pk_bf16_f32 v0, v27, s0
	ds_write_b16 v111, v32 offset:5168
	v_cvt_pk_bf16_f32 v32, v43, s0
	ds_write_b16 v111, v0 offset:13872
	v_cvt_pk_bf16_f32 v0, v11, s0
	ds_write_b16 v111, v32 offset:5232
	v_cvt_pk_bf16_f32 v32, v60, s0
	ds_write_b16 v111, v0 offset:13936
	v_cvt_pk_bf16_f32 v0, v28, s0
	ds_write_b16 v111, v32 offset:6528
	v_cvt_pk_bf16_f32 v32, v44, s0
	ds_write_b16 v111, v0 offset:15232
	v_cvt_pk_bf16_f32 v0, v12, s0
	ds_write_b16 v111, v32 offset:6592
	v_cvt_pk_bf16_f32 v32, v61, s0
	ds_write_b16 v111, v0 offset:15296
	v_cvt_pk_bf16_f32 v0, v29, s0
	ds_write_b16 v111, v32 offset:6800
	v_cvt_pk_bf16_f32 v32, v45, s0
	ds_write_b16 v111, v0 offset:15504
	v_cvt_pk_bf16_f32 v0, v13, s0
	ds_write_b16 v111, v32 offset:6864
	v_cvt_pk_bf16_f32 v32, v62, s0
	ds_write_b16 v111, v0 offset:15568
	v_cvt_pk_bf16_f32 v0, v30, s0
	ds_write_b16 v111, v32 offset:7072
	v_cvt_pk_bf16_f32 v32, v46, s0
	ds_write_b16 v111, v0 offset:15776
	v_cvt_pk_bf16_f32 v0, v14, s0
	ds_write_b16 v111, v32 offset:7136
	v_cvt_pk_bf16_f32 v32, v63, s0
	ds_write_b16 v111, v0 offset:15840
	v_cvt_pk_bf16_f32 v0, v31, s0
	v_cvt_pk_bf16_f32 v48, v48, s0
	ds_write_b16 v111, v32 offset:7344
	v_cvt_pk_bf16_f32 v32, v47, s0
	v_cvt_pk_bf16_f32 v16, v16, s0
	ds_write_b16 v111, v0 offset:16048
	v_cvt_pk_bf16_f32 v0, v15, s0
	v_mov_b32_e32 v15, v110
	ds_write_b16 v111, v48
	ds_write_b16 v111, v32 offset:7408
	ds_write_b16 v111, v16 offset:8704
	ds_write_b16 v111, v0 offset:16112
	s_waitcnt lgkmcnt(0)
	s_barrier
	v_mov_b64_e32 v[2:3], s[4:5]
	v_lshlrev_b32_e32 v0, 3, v15
	v_and_b32_e32 v0, 0x78, v0
	v_ashrrev_i32_e32 v1, 4, v15
	v_lshlrev_b32_e32 v96, 1, v0
	v_add_u32_e32 v0, s63, v1
	s_lshl_b32 s16, s26, 10
	v_mad_i64_i32 v[2:3], s[0:1], v0, s60, v[2:3]
	v_lshl_add_u64 v[2:3], s[16:17], 1, v[2:3]
	v_lshl_add_u64 v[2:3], s[22:23], 1, v[2:3]
	v_lshl_add_u64 v[2:3], v[2:3], 0, v[96:97]
	global_load_dwordx4 v[6:9], v[2:3], off
	v_add_co_u32_e32 v80, vcc, 0x18000, v2
	s_nop 1
	v_addc_co_u32_e32 v81, vcc, 0, v3, vcc
	global_load_dwordx4 v[24:27], v[80:81], off
	v_add_co_u32_e32 v80, vcc, 0x30000, v2
	s_nop 1
	v_addc_co_u32_e32 v81, vcc, 0, v3, vcc
	global_load_dwordx4 v[28:31], v[80:81], off
	v_add_co_u32_e32 v80, vcc, 0x48000, v2
	s_nop 1
	v_addc_co_u32_e32 v81, vcc, 0, v3, vcc
	global_load_dwordx4 v[32:35], v[80:81], off
	v_add_co_u32_e32 v80, vcc, 0x60000, v2
	s_nop 1
	v_addc_co_u32_e32 v81, vcc, 0, v3, vcc
	global_load_dwordx4 v[36:39], v[80:81], off
	v_add_co_u32_e32 v80, vcc, 0x78000, v2
	s_nop 1
	v_addc_co_u32_e32 v81, vcc, 0, v3, vcc
	global_load_dwordx4 v[40:43], v[80:81], off
	v_add_co_u32_e32 v80, vcc, 0x90000, v2
	s_nop 1
	v_addc_co_u32_e32 v81, vcc, 0, v3, vcc
	global_load_dwordx4 v[44:47], v[80:81], off
	v_add_co_u32_e32 v80, vcc, 0xa8000, v2
	s_nop 1
	v_addc_co_u32_e32 v81, vcc, 0, v3, vcc
	global_load_dwordx4 v[48:51], v[80:81], off
	v_add_u32_e32 v14, 32, v96
	v_mad_u64_u32 v[2:3], s[0:1], v1, s54, v[14:15]
	ds_read_b128 v[2:5], v2
	v_ashrrev_i32_e32 v1, 31, v0
	v_lshlrev_b64 v[0:1], 11, v[0:1]
	v_lshl_add_u64 v[0:1], s[24:25], 0, v[0:1]
	v_lshl_add_u64 v[16:17], v[0:1], 0, v[96:97]
	v_cndmask_b32_e64 v1, 0, 1, s[44:45]
	v_mov_b32_e32 v0, 0
	v_cmp_ne_u32_e64 s[0:1], 1, v1
	s_andn2_b64 vcc, exec, s[44:45]
	v_mov_b32_e32 v10, 0
	v_mov_b32_e32 v11, 0
	v_mov_b32_e32 v12, 0
	v_mov_b32_e32 v13, 0
	s_cbranch_vccnz .LBB0_3737
	global_load_dwordx4 v[10:13], v[16:17], off
	v_add_co_u32_e32 v80, vcc, 0x8000, v16
	s_nop 1
	v_addc_co_u32_e32 v81, vcc, 0, v17, vcc
	global_load_dwordx4 v[52:55], v[80:81], off
	v_add_co_u32_e32 v80, vcc, 0x10000, v16
	s_nop 1
	v_addc_co_u32_e32 v81, vcc, 0, v17, vcc
	global_load_dwordx4 v[56:59], v[80:81], off
	v_add_co_u32_e32 v80, vcc, 0x18000, v16
	s_nop 1
	v_addc_co_u32_e32 v81, vcc, 0, v17, vcc
	global_load_dwordx4 v[60:63], v[80:81], off
	v_add_co_u32_e32 v80, vcc, 0x20000, v16
	s_nop 1
	v_addc_co_u32_e32 v81, vcc, 0, v17, vcc
	global_load_dwordx4 v[64:67], v[80:81], off
	v_add_co_u32_e32 v80, vcc, 0x28000, v16
	s_nop 1
	v_addc_co_u32_e32 v81, vcc, 0, v17, vcc
	global_load_dwordx4 v[68:71], v[80:81], off
	v_add_co_u32_e32 v80, vcc, 0x30000, v16
	s_nop 1
	v_addc_co_u32_e32 v81, vcc, 0, v17, vcc
	global_load_dwordx4 v[72:75], v[80:81], off
	v_add_co_u32_e32 v80, vcc, 0x38000, v16
	s_nop 1
	v_addc_co_u32_e32 v81, vcc, 0, v17, vcc
	global_load_dwordx4 v[76:79], v[80:81], off

.LBB0_3806:
	s_setprio 1
	ds_read_b128 v[140:143], v103
	ds_read_b128 v[144:147], v104 offset:36864
	ds_read_b128 v[148:151], v104 offset:41472
	ds_read_b128 v[192:195], v103 offset:4608
	s_waitcnt lgkmcnt(2)
	v_mfma_f32_32x32x16_bf16 v[48:63], v[140:143], v[144:147], v[48:63]
	global_load_dwordx4 v[108:111], v168, s[98:99] offset:3840
	global_load_dwordx4 v[112:115], v170, s[98:99] offset:3840
	s_waitcnt vmcnt(9)
	ds_write_b128 v105, v[68:71] offset:18432
	s_waitcnt lgkmcnt(2)
	v_mfma_f32_32x32x16_bf16 v[32:47], v[140:143], v[148:151], v[32:47]
	ds_read_b128 v[196:199], v103 offset:32
	ds_read_b128 v[200:203], v104 offset:36896
	global_load_dwordx4 v[116:119], v172, s[98:99] offset:3840
	global_load_dwordx4 v[120:123], v174, s[98:99] offset:3840
	s_waitcnt lgkmcnt(3)
	v_mfma_f32_32x32x16_bf16 v[16:31], v[192:195], v[144:147], v[16:31]
	ds_read_b128 v[204:207], v104 offset:41504
	global_load_dwordx4 v[124:127], v176, s[98:99] offset:3840
	global_load_dwordx4 v[128:131], v178, s[98:99] offset:3840
	s_waitcnt vmcnt(11)
	ds_write_b128 v105, v[84:87] offset:23040
	v_mfma_f32_32x32x16_bf16 v[0:15], v[192:195], v[148:151], v[0:15]
	ds_read_b128 v[208:211], v103 offset:4640
	global_load_dwordx4 v[132:135], v180, s[98:99] offset:3840
	global_load_dwordx4 v[136:139], v182, s[98:99] offset:3840
	s_waitcnt lgkmcnt(3)
	v_mfma_f32_32x32x16_bf16 v[48:63], v[196:199], v[200:203], v[48:63]
	s_waitcnt vmcnt(12)
	ds_write_b128 v105, v[88:91] offset:27648
	s_waitcnt lgkmcnt(3)
	v_mfma_f32_32x32x16_bf16 v[32:47], v[196:199], v[204:207], v[32:47]
	ds_read_b128 v[212:215], v103 offset:64
	ds_read_b128 v[216:219], v104 offset:36928
	s_waitcnt lgkmcnt(3)
	v_mfma_f32_32x32x16_bf16 v[16:31], v[208:211], v[200:203], v[16:31]
	ds_read_b128 v[220:223], v104 offset:41536
	s_waitcnt vmcnt(11)
	ds_write_b128 v105, v[92:95] offset:32256
	v_mfma_f32_32x32x16_bf16 v[0:15], v[208:211], v[204:207], v[0:15]
	ds_read_b128 v[224:227], v103 offset:4672
	s_waitcnt lgkmcnt(3)
	v_mfma_f32_32x32x16_bf16 v[48:63], v[212:215], v[216:219], v[48:63]
	ds_write_b128 v105, v[64:67] offset:55296
	s_waitcnt lgkmcnt(3)
	v_mfma_f32_32x32x16_bf16 v[32:47], v[212:215], v[220:223], v[32:47]
	ds_read_b128 v[228:231], v103 offset:96
	ds_read_b128 v[140:143], v104 offset:36960
	s_waitcnt lgkmcnt(3)
	v_mfma_f32_32x32x16_bf16 v[16:31], v[224:227], v[216:219], v[16:31]
	ds_read_b128 v[144:147], v104 offset:41568
	s_waitcnt vmcnt(10)
	ds_write_b128 v105, v[72:75] offset:59904
	v_mfma_f32_32x32x16_bf16 v[0:15], v[224:227], v[220:223], v[0:15]
	ds_read_b128 v[148:151], v103 offset:4704
	s_waitcnt lgkmcnt(3)
	v_mfma_f32_32x32x16_bf16 v[48:63], v[228:231], v[140:143], v[48:63]
	s_waitcnt vmcnt(9)
	ds_write_b128 v105, v[76:79] offset:64512
	s_waitcnt lgkmcnt(3)
	v_mfma_f32_32x32x16_bf16 v[32:47], v[228:231], v[144:147], v[32:47]
	s_waitcnt lgkmcnt(1)
	v_mfma_f32_32x32x16_bf16 v[16:31], v[148:151], v[140:143], v[16:31]
	s_waitcnt vmcnt(8)
	ds_write_b128 v106, v[80:83] offset:13824
	v_mfma_f32_32x32x16_bf16 v[0:15], v[148:151], v[144:147], v[0:15]
	s_setprio 0
	s_waitcnt lgkmcnt(0)
	s_barrier
	s_setprio 1
	ds_read_b128 v[140:143], v103 offset:18432
	ds_read_b128 v[144:147], v104 offset:55296
	ds_read_b128 v[148:151], v104 offset:59904
	ds_read_b128 v[192:195], v103 offset:23040
	s_waitcnt lgkmcnt(2)
	v_mfma_f32_32x32x16_bf16 v[48:63], v[140:143], v[144:147], v[48:63]
	global_load_dwordx4 v[68:71], v168, s[98:99] offset:3968
	global_load_dwordx4 v[84:87], v170, s[98:99] offset:3968
	s_waitcnt vmcnt(9)
	ds_write_b128 v105, v[108:111]
	s_waitcnt lgkmcnt(2)
	v_mfma_f32_32x32x16_bf16 v[32:47], v[140:143], v[148:151], v[32:47]
	ds_read_b128 v[196:199], v103 offset:18464
	ds_read_b128 v[200:203], v104 offset:55328
	global_load_dwordx4 v[88:91], v172, s[98:99] offset:3968
	global_load_dwordx4 v[92:95], v174, s[98:99] offset:3968
	s_waitcnt lgkmcnt(3)
	v_mfma_f32_32x32x16_bf16 v[16:31], v[192:195], v[144:147], v[16:31]
	ds_read_b128 v[204:207], v104 offset:59936
	global_load_dwordx4 v[64:67], v176, s[98:99] offset:3968
	global_load_dwordx4 v[72:75], v178, s[98:99] offset:3968
	s_waitcnt vmcnt(12)
	ds_write_b128 v105, v[112:115] offset:4608
	v_mfma_f32_32x32x16_bf16 v[0:15], v[192:195], v[148:151], v[0:15]
	ds_read_b128 v[208:211], v103 offset:23072
	global_load_dwordx4 v[76:79], v180, s[98:99] offset:3968
	global_load_dwordx4 v[80:83], v182, s[98:99] offset:3968
	s_waitcnt lgkmcnt(3)
	v_mfma_f32_32x32x16_bf16 v[48:63], v[196:199], v[200:203], v[48:63]
	s_add_u32 s98, s98, 0x100
	s_addc_u32 s99, s99, 0
	s_add_i32 s10, s10, 2
	s_cmp_lt_u32 s10, 11
	s_waitcnt vmcnt(13)
	ds_write_b128 v105, v[116:119] offset:9216
	s_waitcnt lgkmcnt(3)
	v_mfma_f32_32x32x16_bf16 v[32:47], v[196:199], v[204:207], v[32:47]
	ds_read_b128 v[212:215], v103 offset:18496
	ds_read_b128 v[216:219], v104 offset:55360
	s_waitcnt lgkmcnt(3)
	v_mfma_f32_32x32x16_bf16 v[16:31], v[208:211], v[200:203], v[16:31]
	ds_read_b128 v[220:223], v104 offset:59968
	s_waitcnt vmcnt(12)
	ds_write_b128 v105, v[120:123] offset:13824
	v_mfma_f32_32x32x16_bf16 v[0:15], v[208:211], v[204:207], v[0:15]
	ds_read_b128 v[224:227], v103 offset:23104
	s_waitcnt lgkmcnt(3)
	v_mfma_f32_32x32x16_bf16 v[48:63], v[212:215], v[216:219], v[48:63]
	s_waitcnt vmcnt(11)
	ds_write_b128 v105, v[124:127] offset:36864
	s_waitcnt lgkmcnt(3)
	v_mfma_f32_32x32x16_bf16 v[32:47], v[212:215], v[220:223], v[32:47]
	ds_read_b128 v[228:231], v103 offset:18528
	ds_read_b128 v[140:143], v104 offset:55392
	s_waitcnt lgkmcnt(3)
	v_mfma_f32_32x32x16_bf16 v[16:31], v[224:227], v[216:219], v[16:31]
	ds_read_b128 v[144:147], v104 offset:60000
	s_waitcnt vmcnt(10)
	ds_write_b128 v105, v[128:131] offset:41472
	v_mfma_f32_32x32x16_bf16 v[0:15], v[224:227], v[220:223], v[0:15]
	ds_read_b128 v[148:151], v103 offset:23136
	s_waitcnt lgkmcnt(3)
	v_mfma_f32_32x32x16_bf16 v[48:63], v[228:231], v[140:143], v[48:63]
	s_waitcnt vmcnt(9)
	ds_write_b128 v105, v[132:135] offset:46080
	s_waitcnt lgkmcnt(3)
	v_mfma_f32_32x32x16_bf16 v[32:47], v[228:231], v[144:147], v[32:47]
	s_waitcnt lgkmcnt(1)
	v_mfma_f32_32x32x16_bf16 v[16:31], v[148:151], v[140:143], v[16:31]
	s_waitcnt vmcnt(8)
	ds_write_b128 v105, v[136:139] offset:50688
	v_mfma_f32_32x32x16_bf16 v[0:15], v[148:151], v[144:147], v[0:15]
	s_setprio 0
	s_waitcnt lgkmcnt(0)
	s_barrier
	s_cbranch_scc1 .LBB0_3806
	s_setprio 1
	ds_read_b128 v[98:101], v103
	ds_read_b128 v[108:111], v104 offset:36864
	ds_read_b128 v[112:115], v104 offset:41472
	ds_read_b128 v[192:195], v103 offset:4608
	s_waitcnt lgkmcnt(2)
	v_mfma_f32_32x32x16_bf16 v[48:63], v[98:101], v[108:111], v[48:63]
	s_waitcnt vmcnt(7)
	ds_write_b128 v105, v[68:71] offset:18432
	s_waitcnt lgkmcnt(2)
	v_mfma_f32_32x32x16_bf16 v[32:47], v[98:101], v[112:115], v[32:47]
	ds_read_b128 v[196:199], v103 offset:32
	ds_read_b128 v[200:203], v104 offset:36896
	s_waitcnt lgkmcnt(3)
	v_mfma_f32_32x32x16_bf16 v[16:31], v[192:195], v[108:111], v[16:31]
	ds_read_b128 v[204:207], v104 offset:41504
	s_waitcnt vmcnt(6)
	ds_write_b128 v105, v[84:87] offset:23040
	v_mfma_f32_32x32x16_bf16 v[0:15], v[192:195], v[112:115], v[0:15]
	ds_read_b128 v[208:211], v103 offset:4640
	s_waitcnt lgkmcnt(3)
	v_mfma_f32_32x32x16_bf16 v[48:63], v[196:199], v[200:203], v[48:63]
	s_waitcnt vmcnt(5)
	ds_write_b128 v105, v[88:91] offset:27648
	s_waitcnt lgkmcnt(3)
	v_mfma_f32_32x32x16_bf16 v[32:47], v[196:199], v[204:207], v[32:47]
	ds_read_b128 v[212:215], v103 offset:64
	ds_read_b128 v[216:219], v104 offset:36928
	s_waitcnt lgkmcnt(3)
	v_mfma_f32_32x32x16_bf16 v[16:31], v[208:211], v[200:203], v[16:31]
	ds_read_b128 v[220:223], v104 offset:41536
	s_waitcnt vmcnt(4)
	ds_write_b128 v105, v[92:95] offset:32256
	v_mfma_f32_32x32x16_bf16 v[0:15], v[208:211], v[204:207], v[0:15]
	ds_read_b128 v[224:227], v103 offset:4672
	s_waitcnt lgkmcnt(3)
	v_mfma_f32_32x32x16_bf16 v[48:63], v[212:215], v[216:219], v[48:63]
	s_waitcnt vmcnt(3)
	ds_write_b128 v105, v[64:67] offset:55296
	s_waitcnt lgkmcnt(3)
	v_mfma_f32_32x32x16_bf16 v[32:47], v[212:215], v[220:223], v[32:47]
	ds_read_b128 v[228:231], v103 offset:96
	ds_read_b128 v[98:101], v104 offset:41568
	s_waitcnt lgkmcnt(3)
	v_mfma_f32_32x32x16_bf16 v[16:31], v[224:227], v[216:219], v[16:31]
	ds_read_b128 v[108:111], v104 offset:36960
	ds_read_b128 v[112:115], v103 offset:4704
	s_waitcnt vmcnt(2)
	ds_write_b128 v105, v[72:75] offset:59904
	v_mfma_f32_32x32x16_bf16 v[0:15], v[224:227], v[220:223], v[0:15]
	s_waitcnt lgkmcnt(3)
	v_mfma_f32_32x32x16_bf16 v[32:47], v[228:231], v[98:101], v[32:47]
	s_waitcnt vmcnt(1)
	ds_write_b128 v105, v[76:79] offset:64512
	s_waitcnt lgkmcnt(2)
	v_mfma_f32_32x32x16_bf16 v[16:31], v[112:115], v[108:111], v[16:31]
	v_mfma_f32_32x32x16_bf16 v[0:15], v[112:115], v[98:101], v[0:15]
	s_waitcnt vmcnt(0)
	ds_write_b128 v106, v[80:83] offset:13824
	v_mfma_f32_32x32x16_bf16 v[48:63], v[228:231], v[108:111], v[48:63]
	s_setprio 0
	s_waitcnt lgkmcnt(0)
	s_barrier
	s_setprio 1
	ds_read_b128 v[64:67], v103 offset:18432
	ds_read_b128 v[68:71], v104 offset:55296
	ds_read_b128 v[72:75], v104 offset:59904
	ds_read_b128 v[192:195], v103 offset:23040
	s_waitcnt lgkmcnt(2)
	v_mfma_f32_32x32x16_bf16 v[48:63], v[64:67], v[68:71], v[48:63]
	s_waitcnt lgkmcnt(1)
	v_mfma_f32_32x32x16_bf16 v[32:47], v[64:67], v[72:75], v[32:47]
	ds_read_b128 v[196:199], v103 offset:18464
	ds_read_b128 v[200:203], v104 offset:55328
	s_waitcnt lgkmcnt(2)
	v_mfma_f32_32x32x16_bf16 v[16:31], v[192:195], v[68:71], v[16:31]
	ds_read_b128 v[204:207], v104 offset:59936
	v_mfma_f32_32x32x16_bf16 v[0:15], v[192:195], v[72:75], v[0:15]
	ds_read_b128 v[208:211], v103 offset:23072
	s_waitcnt lgkmcnt(2)
	v_mfma_f32_32x32x16_bf16 v[48:63], v[196:199], v[200:203], v[48:63]
	s_waitcnt lgkmcnt(1)
	v_mfma_f32_32x32x16_bf16 v[32:47], v[196:199], v[204:207], v[32:47]
	ds_read_b128 v[212:215], v103 offset:18496
	ds_read_b128 v[216:219], v104 offset:55360
	s_waitcnt lgkmcnt(2)
	v_mfma_f32_32x32x16_bf16 v[16:31], v[208:211], v[200:203], v[16:31]
	ds_read_b128 v[220:223], v104 offset:59968
	v_mfma_f32_32x32x16_bf16 v[0:15], v[208:211], v[204:207], v[0:15]
	ds_read_b128 v[224:227], v103 offset:23104
	s_waitcnt lgkmcnt(2)
	v_mfma_f32_32x32x16_bf16 v[48:63], v[212:215], v[216:219], v[48:63]
	s_waitcnt lgkmcnt(1)
	v_mfma_f32_32x32x16_bf16 v[32:47], v[212:215], v[220:223], v[32:47]
	ds_read_b128 v[228:231], v103 offset:18528
	ds_read_b128 v[64:67], v104 offset:60000
	s_waitcnt lgkmcnt(2)
	v_mfma_f32_32x32x16_bf16 v[16:31], v[224:227], v[216:219], v[16:31]
	ds_read_b128 v[68:71], v104 offset:55392
	ds_read_b128 v[72:75], v103 offset:23136
	v_mfma_f32_32x32x16_bf16 v[0:15], v[224:227], v[220:223], v[0:15]
	s_waitcnt lgkmcnt(2)
	v_mfma_f32_32x32x16_bf16 v[32:47], v[228:231], v[64:67], v[32:47]
	s_waitcnt lgkmcnt(0)
	v_mfma_f32_32x32x16_bf16 v[16:31], v[72:75], v[68:71], v[16:31]
	v_mfma_f32_32x32x16_bf16 v[0:15], v[72:75], v[64:67], v[0:15]
	v_mfma_f32_32x32x16_bf16 v[48:63], v[228:231], v[68:71], v[48:63]
	s_setprio 0
	s_addk_i32 s0, 0xf000
	s_lshr_b32 s10, s0, 10
	s_mulk_i32 s10, 0x1800
	s_add_i32 s10, s10, 0x9000
	s_and_b64 s[58:59], s[8:9], exec
	s_cselect_b32 s10, 0x7800, s10
	v_mov_b32_e32 v68, v234
	s_barrier
	s_lshl_b64 s[58:59], s[10:11], 2
	s_add_u32 s58, s30, s58
	v_and_b32_e32 v69, 0x5f, v68
	v_or_b32_e32 v64, s25, v69
	s_addc_u32 s59, s31, s59
	v_ashrrev_i32_e32 v65, 31, v64
	v_lshl_add_u64 v[64:65], v[64:65], 2, s[58:59]
	v_lshl_add_u64 v[66:67], v[64:65], 0, s[14:15]
	v_add_co_u32_e32 v64, vcc, s51, v64
	v_lshlrev_b32_e32 v69, 2, v69
	s_nop 0
	v_addc_co_u32_e32 v65, vcc, 0, v65, vcc
	global_load_dword v64, v[64:65], off
	s_nop 0
	global_load_dword v65, v[66:67], off offset:128
	v_lshrrev_b32_e32 v67, 3, v68
	v_lshrrev_b32_e32 v66, 1, v68
	v_and_b32_e32 v67, 4, v67
	v_and_or_b32 v66, v66, s42, v67
	v_mul_lo_u32 v66, v66, s52
	v_add3_u32 v66, 32, v69, v66
	v_add_u32_e32 v67, 0x400, v66
	v_add_u32_e32 v69, 0x1000, v66
	v_add_u32_e32 v70, 0x1400, v66
	v_add_u32_e32 v71, 0x2000, v66
	v_add_u32_e32 v72, 0x2400, v66
	v_add_u32_e32 v73, 0x3000, v66
	v_add_u32_e32 v74, 0x3200, v66
	v_add_u32_e32 v75, 0x3400, v66
	v_add_u32_e32 v76, 0x3600, v66
	v_add_u32_e32 v77, 0x4000, v66
	v_readlane_b32 s80, v250, 6
	v_readlane_b32 s81, v250, 7
	v_readlane_b32 s82, v250, 8
	v_readlane_b32 s83, v250, 9
	v_readlane_b32 s92, v250, 18
	v_readlane_b32 s93, v250, 19
	v_readlane_b32 s94, v250, 20
	v_readlane_b32 s95, v250, 21
	s_mov_b64 s[80:81], s[92:93]
	s_mov_b64 s[82:83], s[94:95]
	s_lshl_b32 s1, s1, 19
	s_add_u32 s10, s28, s1
	s_mov_b32 s1, s11
	v_readlane_b32 s84, v250, 10
	v_readlane_b32 s85, v250, 11
	v_readlane_b32 s86, v250, 12
	v_readlane_b32 s87, v250, 13
	v_readlane_b32 s88, v250, 14
	v_readlane_b32 s89, v250, 15
	v_readlane_b32 s90, v250, 16
	v_readlane_b32 s91, v250, 17
	s_waitcnt vmcnt(1)
	v_mul_f32_e32 v48, v48, v64
	s_waitcnt vmcnt(0)
	v_mul_f32_e32 v32, v32, v65
	v_mul_f32_e32 v16, v16, v64
	v_mul_f32_e32 v0, v0, v65
	v_mul_f32_e32 v49, v49, v64
	v_mul_f32_e32 v33, v33, v65
	v_mul_f32_e32 v50, v50, v64
	v_mul_f32_e32 v34, v34, v65
	v_mul_f32_e32 v51, v51, v64
	v_mul_f32_e32 v35, v35, v65
	v_mul_f32_e32 v52, v52, v64
	v_mul_f32_e32 v36, v36, v65
	v_mul_f32_e32 v53, v53, v64
	v_mul_f32_e32 v37, v37, v65
	v_mul_f32_e32 v54, v54, v64
	v_mul_f32_e32 v38, v38, v65
	v_mul_f32_e32 v55, v55, v64
	v_mul_f32_e32 v39, v39, v65
	v_mul_f32_e32 v56, v56, v64
	v_mul_f32_e32 v40, v40, v65
	v_mul_f32_e32 v57, v57, v64
	v_mul_f32_e32 v41, v41, v65
	v_mul_f32_e32 v58, v58, v64
	v_mul_f32_e32 v42, v42, v65
	v_mul_f32_e32 v59, v59, v64
	v_mul_f32_e32 v43, v43, v65
	v_mul_f32_e32 v60, v60, v64
	v_mul_f32_e32 v44, v44, v65
	v_mul_f32_e32 v61, v61, v64
	v_mul_f32_e32 v45, v45, v65
	v_mul_f32_e32 v62, v62, v64
	v_mul_f32_e32 v46, v46, v65
	v_mul_f32_e32 v63, v63, v64
	v_mul_f32_e32 v47, v47, v65
	ds_write2_b32 v66, v48, v32 offset1:32
	ds_write2_b32 v66, v49, v33 offset0:132 offset1:164
	ds_write2_b32 v67, v50, v34 offset0:8 offset1:40
	ds_write2_b32 v67, v51, v35 offset0:140 offset1:172
	ds_write2_b32 v69, v52, v36 offset0:32 offset1:64
	ds_write2_b32 v69, v53, v37 offset0:164 offset1:196
	ds_write2_b32 v70, v54, v38 offset0:40 offset1:72
	ds_write2_b32 v70, v55, v39 offset0:172 offset1:204
	ds_write2_b32 v71, v56, v40 offset0:64 offset1:96
	ds_write2_b32 v71, v57, v41 offset0:196 offset1:228
	ds_write2_b32 v72, v58, v42 offset0:72 offset1:104
	ds_write2_b32 v72, v59, v43 offset0:204 offset1:236
	ds_write2_b32 v73, v60, v44 offset0:96 offset1:128
	ds_write2_b32 v74, v61, v45 offset0:100 offset1:132
	ds_write2_b32 v75, v62, v46 offset0:104 offset1:136
	ds_write2_b32 v76, v63, v47 offset0:108 offset1:140
	ds_write2_b32 v77, v16, v0 offset0:128 offset1:160
	v_mul_f32_e32 v0, v17, v64
	v_mul_f32_e32 v1, v1, v65
	v_add_u32_e32 v16, 0x4400, v66
	ds_write2_b32 v16, v0, v1 offset0:4 offset1:36
	v_mul_f32_e32 v0, v18, v64
	v_mul_f32_e32 v1, v2, v65
	ds_write2_b32 v16, v0, v1 offset0:136 offset1:168
	v_mul_f32_e32 v0, v19, v64
	v_mul_f32_e32 v1, v3, v65
	v_add_u32_e32 v2, 0x4800, v66
	ds_write2_b32 v2, v0, v1 offset0:12 offset1:44
	v_mul_f32_e32 v0, v20, v64
	v_mul_f32_e32 v1, v4, v65
	v_add_u32_e32 v2, 0x5000, v66
	ds_write2_b32 v2, v0, v1 offset0:160 offset1:192
	v_mul_f32_e32 v0, v21, v64
	v_mul_f32_e32 v1, v5, v65
	v_add_u32_e32 v2, 0x5400, v66
	ds_write2_b32 v2, v0, v1 offset0:36 offset1:68
	v_mul_f32_e32 v0, v22, v64
	v_mul_f32_e32 v1, v6, v65
	ds_write2_b32 v2, v0, v1 offset0:168 offset1:200
	v_mul_f32_e32 v0, v23, v64
	v_mul_f32_e32 v1, v7, v65
	v_add_u32_e32 v2, 0x5800, v66
	ds_write2_b32 v2, v0, v1 offset0:44 offset1:76
	v_mul_f32_e32 v0, v24, v64
	v_mul_f32_e32 v1, v8, v65
	v_add_u32_e32 v2, 0x6000, v66
	ds_write2_b32 v2, v0, v1 offset0:192 offset1:224
	v_mul_f32_e32 v0, v25, v64
	v_mul_f32_e32 v1, v9, v65
	v_add_u32_e32 v2, 0x6400, v66
	ds_write2_b32 v2, v0, v1 offset0:68 offset1:100
	v_mul_f32_e32 v0, v26, v64
	v_mul_f32_e32 v1, v10, v65
	ds_write2_b32 v2, v0, v1 offset0:200 offset1:232
	v_mul_f32_e32 v0, v27, v64
	v_mul_f32_e32 v1, v11, v65
	v_add_u32_e32 v2, 0x6800, v66
	ds_write2_b32 v2, v0, v1 offset0:76 offset1:108
	v_mul_f32_e32 v0, v28, v64
	v_mul_f32_e32 v1, v12, v65
	v_add_u32_e32 v2, 0x7200, v66
	ds_write2_b32 v2, v0, v1 offset0:96 offset1:128
	v_mul_f32_e32 v0, v29, v64
	v_mul_f32_e32 v1, v13, v65
	v_add_u32_e32 v2, 0x7400, v66
	ds_write2_b32 v2, v0, v1 offset0:100 offset1:132
	v_mul_f32_e32 v0, v30, v64
	v_mul_f32_e32 v1, v14, v65
	v_add_u32_e32 v2, 0x7600, v66
	v_and_b32_e32 v12, 31, v68
	ds_write2_b32 v2, v0, v1 offset0:104 offset1:136
	v_mul_f32_e32 v0, v31, v64
	v_mul_f32_e32 v1, v15, v65
	v_add_u32_e32 v2, 0x7800, v66
	v_lshlrev_b32_e32 v10, 2, v12
	ds_write2_b32 v2, v0, v1 offset0:108 offset1:140
	v_or_b32_e32 v0, s25, v10
	v_ashrrev_i32_e32 v1, 31, v0
	v_lshlrev_b64 v[0:1], 2, v[0:1]
	v_lshl_add_u64 v[2:3], s[80:81], 0, v[0:1]
	v_lshl_add_u64 v[4:5], s[82:83], 0, v[0:1]
	s_waitcnt lgkmcnt(0)
	s_barrier
	global_load_dwordx4 v[0:3], v[2:3], off
	s_nop 0
	global_load_dwordx4 v[4:7], v[4:5], off
	v_and_b32_e32 v8, 64, v102
	v_add_u32_e32 v8, 64, v8
	v_xor_b32_e32 v9, 1, v102
	v_cmp_lt_i32_e32 vcc, v9, v8
	s_addc_u32 s25, s29, 0
	s_lshl_b64 s[0:1], s[0:1], 12
	v_cndmask_b32_e32 v9, v102, v9, vcc
	v_lshlrev_b32_e32 v30, 2, v9
	v_xor_b32_e32 v9, 2, v102
	v_cmp_lt_i32_e32 vcc, v9, v8
	s_add_u32 s58, s17, s0
	s_addc_u32 s59, s19, s1
	v_cndmask_b32_e32 v9, v102, v9, vcc
	v_lshlrev_b32_e32 v31, 2, v9
	v_xor_b32_e32 v9, 4, v102
	v_cmp_lt_i32_e32 vcc, v9, v8
	s_and_b64 s[0:1], s[8:9], exec
	v_add_u32_e32 v10, s22, v10
	v_cndmask_b32_e32 v9, v102, v9, vcc
	v_lshlrev_b32_e32 v32, 2, v9
	v_xor_b32_e32 v9, 8, v102
	v_cmp_lt_i32_e32 vcc, v9, v8
	v_ashrrev_i32_e32 v22, 5, v68
	s_cselect_b32 s59, s25, s59
	s_cselect_b32 s58, s10, s58
	v_cndmask_b32_e32 v9, v102, v9, vcc
	v_ashrrev_i32_e32 v11, 31, v10
	s_add_i32 s10, s24, s35
	v_cmp_eq_u32_e64 s[0:1], 0, v12
	v_lshlrev_b32_e32 v33, 2, v9
	v_xor_b32_e32 v9, 16, v102
	v_lshlrev_b64 v[24:25], 2, v[10:11]
	v_lshlrev_b32_e32 v11, 4, v12
	v_add_u32_e32 v12, s10, v22
	s_add_i32 s10, s24, s36
	s_add_i32 s24, s24, s37
	v_cmp_lt_i32_e32 vcc, v9, v8
	v_add_u32_e32 v16, s10, v22
	v_add_u32_e32 v20, s24, v22
	v_cndmask_b32_e32 v8, v102, v9, vcc
	v_ashrrev_i32_e32 v23, 31, v22
	v_mul_lo_u32 v10, v22, s52
	v_ashrrev_i32_e32 v13, 31, v12
	v_ashrrev_i32_e32 v17, 31, v16
	v_ashrrev_i32_e32 v21, 31, v20
	v_add_u32_e32 v26, s23, v22
	v_lshlrev_b32_e32 v34, 2, v8
	v_lshlrev_b64 v[8:9], 12, v[22:23]
	v_add3_u32 v35, v10, v11, 32
	v_lshlrev_b64 v[10:11], 12, v[12:13]
	v_lshlrev_b32_e32 v12, 1, v12
	v_lshlrev_b64 v[14:15], 12, v[16:17]
	v_lshlrev_b32_e32 v16, 1, v16
	v_lshlrev_b64 v[18:19], 12, v[20:21]
	v_lshlrev_b32_e32 v20, 1, v20
	v_lshlrev_b32_e32 v22, 1, v26
	v_ashrrev_i32_e32 v27, 31, v26
	v_lshl_add_u64 v[8:9], v[8:9], 0, v[24:25]
	v_ashrrev_i32_e32 v13, 31, v12
	v_ashrrev_i32_e32 v17, 31, v16
	v_ashrrev_i32_e32 v21, 31, v20
	v_ashrrev_i32_e32 v23, 31, v22
	v_lshlrev_b64 v[26:27], 12, v[26:27]
	v_lshl_add_u64 v[8:9], s[58:59], 0, v[8:9]
	v_lshl_add_u64 v[10:11], v[10:11], 0, v[24:25]
	v_lshlrev_b64 v[12:13], 2, v[12:13]
	v_lshl_add_u64 v[14:15], v[14:15], 0, v[24:25]
	v_lshlrev_b64 v[16:17], 2, v[16:17]
	v_lshl_add_u64 v[18:19], v[18:19], 0, v[24:25]
	v_lshlrev_b64 v[20:21], 2, v[20:21]
	v_lshlrev_b64 v[22:23], 2, v[22:23]
	v_lshl_add_u64 v[24:25], v[26:27], 0, v[24:25]
	s_mov_b64 s[22:23], 0
	s_branch .LBB0_3809

.LBB0_3929:
	s_setprio 1
	ds_read_b128 v[140:143], v103
	ds_read_b128 v[144:147], v104 offset:36864
	ds_read_b128 v[148:151], v104 offset:41472
	ds_read_b128 v[192:195], v103 offset:4608
	s_waitcnt lgkmcnt(2)
	v_mfma_f32_32x32x16_bf16 v[48:63], v[140:143], v[144:147], v[48:63]
	global_load_dwordx4 v[108:111], v168, s[98:99] offset:3840
	global_load_dwordx4 v[112:115], v170, s[98:99] offset:3840
	s_waitcnt vmcnt(9)
	ds_write_b128 v105, v[68:71] offset:18432
	s_waitcnt lgkmcnt(2)
	v_mfma_f32_32x32x16_bf16 v[32:47], v[140:143], v[148:151], v[32:47]
	ds_read_b128 v[196:199], v103 offset:32
	ds_read_b128 v[200:203], v104 offset:36896
	global_load_dwordx4 v[116:119], v172, s[98:99] offset:3840
	global_load_dwordx4 v[120:123], v174, s[98:99] offset:3840
	s_waitcnt lgkmcnt(3)
	v_mfma_f32_32x32x16_bf16 v[16:31], v[192:195], v[144:147], v[16:31]
	ds_read_b128 v[204:207], v104 offset:41504
	global_load_dwordx4 v[124:127], v176, s[98:99] offset:3840
	global_load_dwordx4 v[128:131], v178, s[98:99] offset:3840
	s_waitcnt vmcnt(11)
	ds_write_b128 v105, v[84:87] offset:23040
	v_mfma_f32_32x32x16_bf16 v[0:15], v[192:195], v[148:151], v[0:15]
	ds_read_b128 v[208:211], v103 offset:4640
	global_load_dwordx4 v[132:135], v180, s[98:99] offset:3840
	global_load_dwordx4 v[136:139], v182, s[98:99] offset:3840
	s_waitcnt lgkmcnt(3)
	v_mfma_f32_32x32x16_bf16 v[48:63], v[196:199], v[200:203], v[48:63]
	s_waitcnt vmcnt(12)
	ds_write_b128 v105, v[88:91] offset:27648
	s_waitcnt lgkmcnt(3)
	v_mfma_f32_32x32x16_bf16 v[32:47], v[196:199], v[204:207], v[32:47]
	ds_read_b128 v[212:215], v103 offset:64
	ds_read_b128 v[216:219], v104 offset:36928
	s_waitcnt lgkmcnt(3)
	v_mfma_f32_32x32x16_bf16 v[16:31], v[208:211], v[200:203], v[16:31]
	ds_read_b128 v[220:223], v104 offset:41536
	s_waitcnt vmcnt(11)
	ds_write_b128 v105, v[92:95] offset:32256
	v_mfma_f32_32x32x16_bf16 v[0:15], v[208:211], v[204:207], v[0:15]
	ds_read_b128 v[224:227], v103 offset:4672
	s_waitcnt lgkmcnt(3)
	v_mfma_f32_32x32x16_bf16 v[48:63], v[212:215], v[216:219], v[48:63]
	ds_write_b128 v105, v[64:67] offset:55296
	s_waitcnt lgkmcnt(3)
	v_mfma_f32_32x32x16_bf16 v[32:47], v[212:215], v[220:223], v[32:47]
	ds_read_b128 v[228:231], v103 offset:96
	ds_read_b128 v[140:143], v104 offset:36960
	s_waitcnt lgkmcnt(3)
	v_mfma_f32_32x32x16_bf16 v[16:31], v[224:227], v[216:219], v[16:31]
	ds_read_b128 v[144:147], v104 offset:41568
	s_waitcnt vmcnt(10)
	ds_write_b128 v105, v[72:75] offset:59904
	v_mfma_f32_32x32x16_bf16 v[0:15], v[224:227], v[220:223], v[0:15]
	ds_read_b128 v[148:151], v103 offset:4704
	s_waitcnt lgkmcnt(3)
	v_mfma_f32_32x32x16_bf16 v[48:63], v[228:231], v[140:143], v[48:63]
	s_waitcnt vmcnt(9)
	ds_write_b128 v105, v[76:79] offset:64512
	s_waitcnt lgkmcnt(3)
	v_mfma_f32_32x32x16_bf16 v[32:47], v[228:231], v[144:147], v[32:47]
	s_waitcnt lgkmcnt(1)
	v_mfma_f32_32x32x16_bf16 v[16:31], v[148:151], v[140:143], v[16:31]
	s_waitcnt vmcnt(8)
	ds_write_b128 v106, v[80:83] offset:13824
	v_mfma_f32_32x32x16_bf16 v[0:15], v[148:151], v[144:147], v[0:15]
	s_setprio 0
	s_waitcnt lgkmcnt(0)
	s_barrier
	s_setprio 1
	ds_read_b128 v[140:143], v103 offset:18432
	ds_read_b128 v[144:147], v104 offset:55296
	ds_read_b128 v[148:151], v104 offset:59904
	ds_read_b128 v[192:195], v103 offset:23040
	s_waitcnt lgkmcnt(2)
	v_mfma_f32_32x32x16_bf16 v[48:63], v[140:143], v[144:147], v[48:63]
	global_load_dwordx4 v[68:71], v168, s[98:99] offset:3968
	global_load_dwordx4 v[84:87], v170, s[98:99] offset:3968
	s_waitcnt vmcnt(9)
	ds_write_b128 v105, v[108:111]
	s_waitcnt lgkmcnt(2)
	v_mfma_f32_32x32x16_bf16 v[32:47], v[140:143], v[148:151], v[32:47]
	ds_read_b128 v[196:199], v103 offset:18464
	ds_read_b128 v[200:203], v104 offset:55328
	global_load_dwordx4 v[88:91], v172, s[98:99] offset:3968
	global_load_dwordx4 v[92:95], v174, s[98:99] offset:3968
	s_waitcnt lgkmcnt(3)
	v_mfma_f32_32x32x16_bf16 v[16:31], v[192:195], v[144:147], v[16:31]
	ds_read_b128 v[204:207], v104 offset:59936
	global_load_dwordx4 v[64:67], v176, s[98:99] offset:3968
	global_load_dwordx4 v[72:75], v178, s[98:99] offset:3968
	s_waitcnt vmcnt(12)
	ds_write_b128 v105, v[112:115] offset:4608
	v_mfma_f32_32x32x16_bf16 v[0:15], v[192:195], v[148:151], v[0:15]
	ds_read_b128 v[208:211], v103 offset:23072
	global_load_dwordx4 v[76:79], v180, s[98:99] offset:3968
	global_load_dwordx4 v[80:83], v182, s[98:99] offset:3968
	s_waitcnt lgkmcnt(3)
	v_mfma_f32_32x32x16_bf16 v[48:63], v[196:199], v[200:203], v[48:63]
	s_add_u32 s98, s98, 0x100
	s_addc_u32 s99, s99, 0
	s_add_i32 s41, s41, 2
	s_cmp_lt_u32 s41, 11
	s_waitcnt vmcnt(13)
	ds_write_b128 v105, v[116:119] offset:9216
	s_waitcnt lgkmcnt(3)
	v_mfma_f32_32x32x16_bf16 v[32:47], v[196:199], v[204:207], v[32:47]
	ds_read_b128 v[212:215], v103 offset:18496
	ds_read_b128 v[216:219], v104 offset:55360
	s_waitcnt lgkmcnt(3)
	v_mfma_f32_32x32x16_bf16 v[16:31], v[208:211], v[200:203], v[16:31]
	ds_read_b128 v[220:223], v104 offset:59968
	s_waitcnt vmcnt(12)
	ds_write_b128 v105, v[120:123] offset:13824
	v_mfma_f32_32x32x16_bf16 v[0:15], v[208:211], v[204:207], v[0:15]
	ds_read_b128 v[224:227], v103 offset:23104
	s_waitcnt lgkmcnt(3)
	v_mfma_f32_32x32x16_bf16 v[48:63], v[212:215], v[216:219], v[48:63]
	s_waitcnt vmcnt(11)
	ds_write_b128 v105, v[124:127] offset:36864
	s_waitcnt lgkmcnt(3)
	v_mfma_f32_32x32x16_bf16 v[32:47], v[212:215], v[220:223], v[32:47]
	ds_read_b128 v[228:231], v103 offset:18528
	ds_read_b128 v[140:143], v104 offset:55392
	s_waitcnt lgkmcnt(3)
	v_mfma_f32_32x32x16_bf16 v[16:31], v[224:227], v[216:219], v[16:31]
	ds_read_b128 v[144:147], v104 offset:60000
	s_waitcnt vmcnt(10)
	ds_write_b128 v105, v[128:131] offset:41472
	v_mfma_f32_32x32x16_bf16 v[0:15], v[224:227], v[220:223], v[0:15]
	ds_read_b128 v[148:151], v103 offset:23136
	s_waitcnt lgkmcnt(3)
	v_mfma_f32_32x32x16_bf16 v[48:63], v[228:231], v[140:143], v[48:63]
	s_waitcnt vmcnt(9)
	ds_write_b128 v105, v[132:135] offset:46080
	s_waitcnt lgkmcnt(3)
	v_mfma_f32_32x32x16_bf16 v[32:47], v[228:231], v[144:147], v[32:47]
	s_waitcnt lgkmcnt(1)
	v_mfma_f32_32x32x16_bf16 v[16:31], v[148:151], v[140:143], v[16:31]
	s_waitcnt vmcnt(8)
	ds_write_b128 v105, v[136:139] offset:50688
	v_mfma_f32_32x32x16_bf16 v[0:15], v[148:151], v[144:147], v[0:15]
	s_setprio 0
	s_waitcnt lgkmcnt(0)
	s_barrier
	s_cbranch_scc1 .LBB0_3929
	s_setprio 1
	ds_read_b128 v[98:101], v103
	ds_read_b128 v[108:111], v104 offset:36864
	ds_read_b128 v[112:115], v104 offset:41472
	ds_read_b128 v[192:195], v103 offset:4608
	s_waitcnt lgkmcnt(2)
	v_mfma_f32_32x32x16_bf16 v[48:63], v[98:101], v[108:111], v[48:63]
	s_waitcnt vmcnt(7)
	ds_write_b128 v105, v[68:71] offset:18432
	s_waitcnt lgkmcnt(2)
	v_mfma_f32_32x32x16_bf16 v[32:47], v[98:101], v[112:115], v[32:47]
	ds_read_b128 v[196:199], v103 offset:32
	ds_read_b128 v[200:203], v104 offset:36896
	s_waitcnt lgkmcnt(3)
	v_mfma_f32_32x32x16_bf16 v[16:31], v[192:195], v[108:111], v[16:31]
	ds_read_b128 v[204:207], v104 offset:41504
	s_waitcnt vmcnt(6)
	ds_write_b128 v105, v[84:87] offset:23040
	v_mfma_f32_32x32x16_bf16 v[0:15], v[192:195], v[112:115], v[0:15]
	ds_read_b128 v[208:211], v103 offset:4640
	s_waitcnt lgkmcnt(3)
	v_mfma_f32_32x32x16_bf16 v[48:63], v[196:199], v[200:203], v[48:63]
	s_waitcnt vmcnt(5)
	ds_write_b128 v105, v[88:91] offset:27648
	s_waitcnt lgkmcnt(3)
	v_mfma_f32_32x32x16_bf16 v[32:47], v[196:199], v[204:207], v[32:47]
	ds_read_b128 v[212:215], v103 offset:64
	ds_read_b128 v[216:219], v104 offset:36928
	s_waitcnt lgkmcnt(3)
	v_mfma_f32_32x32x16_bf16 v[16:31], v[208:211], v[200:203], v[16:31]
	ds_read_b128 v[220:223], v104 offset:41536
	s_waitcnt vmcnt(4)
	ds_write_b128 v105, v[92:95] offset:32256
	v_mfma_f32_32x32x16_bf16 v[0:15], v[208:211], v[204:207], v[0:15]
	ds_read_b128 v[224:227], v103 offset:4672
	s_waitcnt lgkmcnt(3)
	v_mfma_f32_32x32x16_bf16 v[48:63], v[212:215], v[216:219], v[48:63]
	s_waitcnt vmcnt(3)
	ds_write_b128 v105, v[64:67] offset:55296
	s_waitcnt lgkmcnt(3)
	v_mfma_f32_32x32x16_bf16 v[32:47], v[212:215], v[220:223], v[32:47]
	ds_read_b128 v[228:231], v103 offset:96
	ds_read_b128 v[98:101], v104 offset:36960
	s_waitcnt lgkmcnt(3)
	v_mfma_f32_32x32x16_bf16 v[16:31], v[224:227], v[216:219], v[16:31]
	ds_read_b128 v[108:111], v104 offset:41568
	s_waitcnt vmcnt(2)
	ds_write_b128 v105, v[72:75] offset:59904
	v_mfma_f32_32x32x16_bf16 v[0:15], v[224:227], v[220:223], v[0:15]
	ds_read_b128 v[112:115], v103 offset:4704
	s_waitcnt lgkmcnt(3)
	v_mfma_f32_32x32x16_bf16 v[48:63], v[228:231], v[98:101], v[48:63]
	s_waitcnt vmcnt(1)
	ds_write_b128 v105, v[76:79] offset:64512
	s_waitcnt lgkmcnt(3)
	v_mfma_f32_32x32x16_bf16 v[32:47], v[228:231], v[108:111], v[32:47]
	s_waitcnt lgkmcnt(1)
	v_mfma_f32_32x32x16_bf16 v[16:31], v[112:115], v[98:101], v[16:31]
	s_waitcnt vmcnt(0)
	ds_write_b128 v106, v[80:83] offset:13824
	v_mfma_f32_32x32x16_bf16 v[0:15], v[112:115], v[108:111], v[0:15]
	s_setprio 0
	s_waitcnt lgkmcnt(0)
	s_barrier
	s_setprio 1
	ds_read_b128 v[64:67], v103 offset:18432
	ds_read_b128 v[68:71], v104 offset:55296
	ds_read_b128 v[72:75], v104 offset:59904
	ds_read_b128 v[192:195], v103 offset:23040
	s_waitcnt lgkmcnt(2)
	v_mfma_f32_32x32x16_bf16 v[48:63], v[64:67], v[68:71], v[48:63]
	s_waitcnt lgkmcnt(1)
	v_mfma_f32_32x32x16_bf16 v[32:47], v[64:67], v[72:75], v[32:47]
	ds_read_b128 v[196:199], v103 offset:18464
	ds_read_b128 v[200:203], v104 offset:55328
	s_waitcnt lgkmcnt(2)
	v_mfma_f32_32x32x16_bf16 v[16:31], v[192:195], v[68:71], v[16:31]
	ds_read_b128 v[204:207], v104 offset:59936
	v_mfma_f32_32x32x16_bf16 v[0:15], v[192:195], v[72:75], v[0:15]
	ds_read_b128 v[208:211], v103 offset:23072
	s_waitcnt lgkmcnt(2)
	v_mfma_f32_32x32x16_bf16 v[48:63], v[196:199], v[200:203], v[48:63]
	s_waitcnt lgkmcnt(1)
	v_mfma_f32_32x32x16_bf16 v[32:47], v[196:199], v[204:207], v[32:47]
	ds_read_b128 v[212:215], v103 offset:18496
	ds_read_b128 v[216:219], v104 offset:55360
	s_waitcnt lgkmcnt(2)
	v_mfma_f32_32x32x16_bf16 v[16:31], v[208:211], v[200:203], v[16:31]
	ds_read_b128 v[220:223], v104 offset:59968
	v_mfma_f32_32x32x16_bf16 v[0:15], v[208:211], v[204:207], v[0:15]
	ds_read_b128 v[224:227], v103 offset:23104
	s_waitcnt lgkmcnt(2)
	v_mfma_f32_32x32x16_bf16 v[48:63], v[212:215], v[216:219], v[48:63]
	s_waitcnt lgkmcnt(1)
	v_mfma_f32_32x32x16_bf16 v[32:47], v[212:215], v[220:223], v[32:47]
	ds_read_b128 v[228:231], v103 offset:18528
	ds_read_b128 v[64:67], v104 offset:55392
	s_waitcnt lgkmcnt(2)
	v_mfma_f32_32x32x16_bf16 v[16:31], v[224:227], v[216:219], v[16:31]
	ds_read_b128 v[68:71], v104 offset:60000
	v_mfma_f32_32x32x16_bf16 v[0:15], v[224:227], v[220:223], v[0:15]
	ds_read_b128 v[72:75], v103 offset:23136
	s_waitcnt lgkmcnt(2)
	v_mfma_f32_32x32x16_bf16 v[48:63], v[228:231], v[64:67], v[48:63]
	s_waitcnt lgkmcnt(1)
	v_mfma_f32_32x32x16_bf16 v[32:47], v[228:231], v[68:71], v[32:47]
	s_waitcnt lgkmcnt(0)
	v_mfma_f32_32x32x16_bf16 v[16:31], v[72:75], v[64:67], v[16:31]
	v_mfma_f32_32x32x16_bf16 v[0:15], v[72:75], v[68:71], v[0:15]
	s_setprio 0
	v_lshrrev_b32_e32 v65, 3, v102
	v_lshrrev_b32_e32 v64, 1, v102
	v_and_b32_e32 v65, 4, v65
	v_and_or_b32 v64, v64, s22, v65
	v_and_b32_e32 v65, 0x5f, v102
	v_lshlrev_b32_e32 v65, 1, v65
	v_mul_lo_u32 v64, v64, s36
	v_add3_u32 v64, 32, v65, v64
	s_nop 2
	v_cvt_pk_bf16_f32 v0, v0, s0
	s_barrier
	ds_write_b16 v64, v0 offset:8768
	v_cvt_pk_bf16_f32 v0, v17, s0
	ds_write_b16 v64, v0 offset:8976
	v_cvt_pk_bf16_f32 v0, v1, s0
	ds_write_b16 v64, v0 offset:9040
	v_cvt_pk_bf16_f32 v0, v18, s0
	v_cvt_pk_bf16_f32 v32, v32, s0
	ds_write_b16 v64, v0 offset:9248
	v_cvt_pk_bf16_f32 v0, v2, s0
	ds_write_b16 v64, v32 offset:64
	v_cvt_pk_bf16_f32 v32, v49, s0
	ds_write_b16 v64, v0 offset:9312
	v_cvt_pk_bf16_f32 v0, v19, s0
	ds_write_b16 v64, v32 offset:272
	v_cvt_pk_bf16_f32 v32, v33, s0
	ds_write_b16 v64, v0 offset:9520
	v_cvt_pk_bf16_f32 v0, v3, s0
	ds_write_b16 v64, v32 offset:336
	v_cvt_pk_bf16_f32 v32, v50, s0
	ds_write_b16 v64, v0 offset:9584
	v_cvt_pk_bf16_f32 v0, v20, s0
	ds_write_b16 v64, v32 offset:544
	v_cvt_pk_bf16_f32 v32, v34, s0
	ds_write_b16 v64, v0 offset:10880
	v_cvt_pk_bf16_f32 v0, v4, s0
	ds_write_b16 v64, v32 offset:608
	v_cvt_pk_bf16_f32 v32, v51, s0
	ds_write_b16 v64, v0 offset:10944
	v_cvt_pk_bf16_f32 v0, v21, s0
	ds_write_b16 v64, v32 offset:816
	v_cvt_pk_bf16_f32 v32, v35, s0
	ds_write_b16 v64, v0 offset:11152
	v_cvt_pk_bf16_f32 v0, v5, s0
	ds_write_b16 v64, v32 offset:880
	v_cvt_pk_bf16_f32 v32, v52, s0
	ds_write_b16 v64, v0 offset:11216
	v_cvt_pk_bf16_f32 v0, v22, s0
	ds_write_b16 v64, v32 offset:2176
	v_cvt_pk_bf16_f32 v32, v36, s0
	ds_write_b16 v64, v0 offset:11424
	v_cvt_pk_bf16_f32 v0, v6, s0
	ds_write_b16 v64, v32 offset:2240
	v_cvt_pk_bf16_f32 v32, v53, s0
	ds_write_b16 v64, v0 offset:11488
	v_cvt_pk_bf16_f32 v0, v23, s0
	ds_write_b16 v64, v32 offset:2448
	v_cvt_pk_bf16_f32 v32, v37, s0
	ds_write_b16 v64, v0 offset:11696
	v_cvt_pk_bf16_f32 v0, v7, s0
	ds_write_b16 v64, v32 offset:2512
	v_cvt_pk_bf16_f32 v32, v54, s0
	ds_write_b16 v64, v0 offset:11760
	v_cvt_pk_bf16_f32 v0, v24, s0
	ds_write_b16 v64, v32 offset:2720
	v_cvt_pk_bf16_f32 v32, v38, s0
	ds_write_b16 v64, v0 offset:13056
	v_cvt_pk_bf16_f32 v0, v8, s0
	ds_write_b16 v64, v32 offset:2784
	v_cvt_pk_bf16_f32 v32, v55, s0
	ds_write_b16 v64, v0 offset:13120
	v_cvt_pk_bf16_f32 v0, v25, s0
	ds_write_b16 v64, v32 offset:2992
	v_cvt_pk_bf16_f32 v32, v39, s0
	ds_write_b16 v64, v0 offset:13328
	v_cvt_pk_bf16_f32 v0, v9, s0
	ds_write_b16 v64, v32 offset:3056
	v_cvt_pk_bf16_f32 v32, v56, s0
	ds_write_b16 v64, v0 offset:13392
	v_cvt_pk_bf16_f32 v0, v26, s0
	ds_write_b16 v64, v32 offset:4352
	v_cvt_pk_bf16_f32 v32, v40, s0
	ds_write_b16 v64, v0 offset:13600
	v_cvt_pk_bf16_f32 v0, v10, s0
	ds_write_b16 v64, v32 offset:4416
	v_cvt_pk_bf16_f32 v32, v57, s0
	ds_write_b16 v64, v0 offset:13664
	v_cvt_pk_bf16_f32 v0, v27, s0
	ds_write_b16 v64, v32 offset:4624
	v_cvt_pk_bf16_f32 v32, v41, s0
	ds_write_b16 v64, v0 offset:13872
	v_cvt_pk_bf16_f32 v0, v11, s0
	ds_write_b16 v64, v32 offset:4688
	v_cvt_pk_bf16_f32 v32, v58, s0
	ds_write_b16 v64, v0 offset:13936
	v_cvt_pk_bf16_f32 v0, v28, s0
	ds_write_b16 v64, v32 offset:4896
	v_cvt_pk_bf16_f32 v32, v42, s0
	ds_write_b16 v64, v0 offset:15232
	v_cvt_pk_bf16_f32 v0, v12, s0
	ds_write_b16 v64, v32 offset:4960
	v_cvt_pk_bf16_f32 v32, v59, s0
	ds_write_b16 v64, v0 offset:15296
	v_cvt_pk_bf16_f32 v0, v29, s0
	ds_write_b16 v64, v32 offset:5168
	v_cvt_pk_bf16_f32 v32, v43, s0
	ds_write_b16 v64, v0 offset:15504
	v_cvt_pk_bf16_f32 v0, v13, s0
	ds_write_b16 v64, v32 offset:5232
	v_cvt_pk_bf16_f32 v32, v60, s0
	ds_write_b16 v64, v0 offset:15568
	v_cvt_pk_bf16_f32 v0, v30, s0
	ds_write_b16 v64, v32 offset:6528
	v_cvt_pk_bf16_f32 v32, v44, s0
	ds_write_b16 v64, v0 offset:15776
	v_cvt_pk_bf16_f32 v0, v14, s0
	s_mul_i32 s11, s11, 0x160000
	ds_write_b16 v64, v32 offset:6592
	v_cvt_pk_bf16_f32 v32, v61, s0
	ds_write_b16 v64, v0 offset:15840
	v_cvt_pk_bf16_f32 v0, v31, s0
	s_add_u32 s41, s13, s11
	ds_write_b16 v64, v32 offset:6800
	v_cvt_pk_bf16_f32 v32, v45, s0
	ds_write_b16 v64, v0 offset:16048
	v_cvt_pk_bf16_f32 v0, v15, s0
	s_addc_u32 s42, s14, 0
	s_ashr_i32 s11, s10, 31
	ds_write_b16 v64, v32 offset:6864
	v_cvt_pk_bf16_f32 v32, v62, s0
	ds_write_b16 v64, v0 offset:16112
	s_lshl_b64 s[10:11], s[10:11], 1
	v_lshlrev_b32_e32 v0, 4, v102
	ds_write_b16 v64, v32 offset:7072
	v_cvt_pk_bf16_f32 v32, v46, s0
	s_add_u32 s10, s41, s10
	v_and_b32_e32 v96, 0xf0, v0
	ds_write_b16 v64, v32 offset:7136
	v_cvt_pk_bf16_f32 v32, v63, s0
	s_addc_u32 s11, s42, s11
	v_add_u32_e32 v8, 32, v96
	v_ashrrev_i32_e32 v9, 4, v102
	v_add_u32_e32 v4, 0x100, v102
	v_cvt_pk_bf16_f32 v48, v48, s0
	ds_write_b16 v64, v32 offset:7344
	v_cvt_pk_bf16_f32 v32, v47, s0
	v_cvt_pk_bf16_f32 v16, v16, s0
	v_lshl_add_u64 v[10:11], s[10:11], 0, v[96:97]
	v_mad_u64_u32 v[0:1], s[10:11], v9, s36, v[8:9]
	v_ashrrev_i32_e32 v14, 4, v4
	ds_write_b16 v64, v48
	ds_write_b16 v64, v32 offset:7408
	ds_write_b16 v64, v16 offset:8704
	s_waitcnt lgkmcnt(0)
	s_barrier
	ds_read_b128 v[0:3], v0
	v_mad_u64_u32 v[4:5], s[10:11], v14, s36, v[8:9]
	ds_read_b128 v[4:7], v4
	v_mad_i64_i32 v[12:13], s[10:11], v9, s37, v[10:11]
	s_waitcnt lgkmcnt(1)
	global_store_dwordx4 v[12:13], v[0:3], off
	s_nop 1
	v_mad_i64_i32 v[0:1], s[10:11], v14, s37, v[10:11]
	s_waitcnt lgkmcnt(0)
	global_store_dwordx4 v[0:1], v[4:7], off
	v_add_u32_e32 v0, 0x200, v102
	v_ashrrev_i32_e32 v9, 4, v0
	v_add_u32_e32 v4, 0x300, v102
	v_mad_u64_u32 v[0:1], s[10:11], v9, s36, v[8:9]
	v_ashrrev_i32_e32 v14, 4, v4
	ds_read_b128 v[0:3], v0
	v_mad_u64_u32 v[4:5], s[10:11], v14, s36, v[8:9]
	ds_read_b128 v[4:7], v4
	v_mad_i64_i32 v[12:13], s[10:11], v9, s37, v[10:11]
	s_waitcnt lgkmcnt(1)
	global_store_dwordx4 v[12:13], v[0:3], off
	s_nop 1
	v_mad_i64_i32 v[0:1], s[10:11], v14, s37, v[10:11]
	s_waitcnt lgkmcnt(0)
	global_store_dwordx4 v[0:1], v[4:7], off
	v_add_u32_e32 v0, 0x400, v102
	v_ashrrev_i32_e32 v9, 4, v0
	v_add_u32_e32 v4, 0x500, v102
	v_mad_u64_u32 v[0:1], s[10:11], v9, s36, v[8:9]
	v_ashrrev_i32_e32 v14, 4, v4
	ds_read_b128 v[0:3], v0
	v_mad_u64_u32 v[4:5], s[10:11], v14, s36, v[8:9]
	ds_read_b128 v[4:7], v4
	v_mad_i64_i32 v[12:13], s[10:11], v9, s37, v[10:11]
	s_waitcnt lgkmcnt(1)
	global_store_dwordx4 v[12:13], v[0:3], off
	s_nop 1
	v_mad_i64_i32 v[0:1], s[10:11], v14, s37, v[10:11]
	s_waitcnt lgkmcnt(0)
	global_store_dwordx4 v[0:1], v[4:7], off
	v_add_u32_e32 v0, 0x600, v102
	v_ashrrev_i32_e32 v9, 4, v0
	v_add_u32_e32 v4, 0x700, v102
	v_mad_u64_u32 v[0:1], s[10:11], v9, s36, v[8:9]
	v_ashrrev_i32_e32 v12, 4, v4
	ds_read_b128 v[0:3], v0
	v_mad_u64_u32 v[4:5], s[10:11], v12, s36, v[8:9]
	ds_read_b128 v[4:7], v4
	v_mad_i64_i32 v[8:9], s[10:11], v9, s37, v[10:11]
	s_waitcnt lgkmcnt(1)
	global_store_dwordx4 v[8:9], v[0:3], off
	s_nop 1
	v_mad_i64_i32 v[0:1], s[10:11], v12, s37, v[10:11]
	s_waitcnt lgkmcnt(0)
	global_store_dwordx4 v[0:1], v[4:7], off
	s_branch .LBB0_3926

.LBB0_4051:
	s_setprio 1
	ds_read_b128 v[146:149], v109
	ds_read_b128 v[150:153], v110 offset:36864
	ds_read_b128 v[154:157], v110 offset:41472
	ds_read_b128 v[192:195], v109 offset:4608
	s_waitcnt lgkmcnt(2)
	v_mfma_f32_32x32x16_bf16 v[48:63], v[146:149], v[150:153], v[48:63]
	global_load_dwordx4 v[114:117], v174, s[98:99] offset:3840
	global_load_dwordx4 v[118:121], v176, s[98:99] offset:3840
	s_waitcnt vmcnt(9)
	ds_write_b128 v111, v[68:71] offset:18432
	s_waitcnt lgkmcnt(2)
	v_mfma_f32_32x32x16_bf16 v[32:47], v[146:149], v[154:157], v[32:47]
	ds_read_b128 v[196:199], v109 offset:32
	ds_read_b128 v[200:203], v110 offset:36896
	global_load_dwordx4 v[122:125], v178, s[98:99] offset:3840
	global_load_dwordx4 v[126:129], v180, s[98:99] offset:3840
	s_waitcnt lgkmcnt(3)
	v_mfma_f32_32x32x16_bf16 v[16:31], v[192:195], v[150:153], v[16:31]
	ds_read_b128 v[204:207], v110 offset:41504
	global_load_dwordx4 v[130:133], v182, s[98:99] offset:3840
	global_load_dwordx4 v[134:137], v184, s[98:99] offset:3840
	s_waitcnt vmcnt(11)
	ds_write_b128 v111, v[84:87] offset:23040
	v_mfma_f32_32x32x16_bf16 v[0:15], v[192:195], v[154:157], v[0:15]
	ds_read_b128 v[208:211], v109 offset:4640
	global_load_dwordx4 v[138:141], v186, s[98:99] offset:3840
	global_load_dwordx4 v[142:145], v188, s[98:99] offset:3840
	s_waitcnt lgkmcnt(3)
	v_mfma_f32_32x32x16_bf16 v[48:63], v[196:199], v[200:203], v[48:63]
	s_waitcnt vmcnt(12)
	ds_write_b128 v111, v[88:91] offset:27648
	s_waitcnt lgkmcnt(3)
	v_mfma_f32_32x32x16_bf16 v[32:47], v[196:199], v[204:207], v[32:47]
	ds_read_b128 v[212:215], v109 offset:64
	ds_read_b128 v[216:219], v110 offset:36928
	s_waitcnt lgkmcnt(3)
	v_mfma_f32_32x32x16_bf16 v[16:31], v[208:211], v[200:203], v[16:31]
	ds_read_b128 v[220:223], v110 offset:41536
	s_waitcnt vmcnt(11)
	ds_write_b128 v111, v[92:95] offset:32256
	v_mfma_f32_32x32x16_bf16 v[0:15], v[208:211], v[204:207], v[0:15]
	ds_read_b128 v[224:227], v109 offset:4672
	s_waitcnt lgkmcnt(3)
	v_mfma_f32_32x32x16_bf16 v[48:63], v[212:215], v[216:219], v[48:63]
	ds_write_b128 v111, v[64:67] offset:55296
	s_waitcnt lgkmcnt(3)
	v_mfma_f32_32x32x16_bf16 v[32:47], v[212:215], v[220:223], v[32:47]
	ds_read_b128 v[228:231], v109 offset:96
	ds_read_b128 v[146:149], v110 offset:36960
	s_waitcnt lgkmcnt(3)
	v_mfma_f32_32x32x16_bf16 v[16:31], v[224:227], v[216:219], v[16:31]
	ds_read_b128 v[150:153], v110 offset:41568
	s_waitcnt vmcnt(10)
	ds_write_b128 v111, v[72:75] offset:59904
	v_mfma_f32_32x32x16_bf16 v[0:15], v[224:227], v[220:223], v[0:15]
	ds_read_b128 v[154:157], v109 offset:4704
	s_waitcnt lgkmcnt(3)
	v_mfma_f32_32x32x16_bf16 v[48:63], v[228:231], v[146:149], v[48:63]
	s_waitcnt vmcnt(9)
	ds_write_b128 v111, v[76:79] offset:64512
	s_waitcnt lgkmcnt(3)
	v_mfma_f32_32x32x16_bf16 v[32:47], v[228:231], v[150:153], v[32:47]
	s_waitcnt lgkmcnt(1)
	v_mfma_f32_32x32x16_bf16 v[16:31], v[154:157], v[146:149], v[16:31]
	s_waitcnt vmcnt(8)
	ds_write_b128 v112, v[80:83] offset:13824
	v_mfma_f32_32x32x16_bf16 v[0:15], v[154:157], v[150:153], v[0:15]
	s_setprio 0
	s_waitcnt lgkmcnt(0)
	s_barrier
	s_setprio 1
	ds_read_b128 v[146:149], v109 offset:18432
	ds_read_b128 v[150:153], v110 offset:55296
	ds_read_b128 v[154:157], v110 offset:59904
	ds_read_b128 v[192:195], v109 offset:23040
	s_waitcnt lgkmcnt(2)
	v_mfma_f32_32x32x16_bf16 v[48:63], v[146:149], v[150:153], v[48:63]
	global_load_dwordx4 v[68:71], v174, s[98:99] offset:3968
	global_load_dwordx4 v[84:87], v176, s[98:99] offset:3968
	s_waitcnt vmcnt(9)
	ds_write_b128 v111, v[114:117]
	s_waitcnt lgkmcnt(2)
	v_mfma_f32_32x32x16_bf16 v[32:47], v[146:149], v[154:157], v[32:47]
	ds_read_b128 v[196:199], v109 offset:18464
	ds_read_b128 v[200:203], v110 offset:55328
	global_load_dwordx4 v[88:91], v178, s[98:99] offset:3968
	global_load_dwordx4 v[92:95], v180, s[98:99] offset:3968
	s_waitcnt lgkmcnt(3)
	v_mfma_f32_32x32x16_bf16 v[16:31], v[192:195], v[150:153], v[16:31]
	ds_read_b128 v[204:207], v110 offset:59936
	global_load_dwordx4 v[64:67], v182, s[98:99] offset:3968
	global_load_dwordx4 v[72:75], v184, s[98:99] offset:3968
	s_waitcnt vmcnt(12)
	ds_write_b128 v111, v[118:121] offset:4608
	v_mfma_f32_32x32x16_bf16 v[0:15], v[192:195], v[154:157], v[0:15]
	ds_read_b128 v[208:211], v109 offset:23072
	global_load_dwordx4 v[76:79], v186, s[98:99] offset:3968
	global_load_dwordx4 v[80:83], v188, s[98:99] offset:3968
	s_waitcnt lgkmcnt(3)
	v_mfma_f32_32x32x16_bf16 v[48:63], v[196:199], v[200:203], v[48:63]
	s_add_u32 s98, s98, 0x100
	s_addc_u32 s99, s99, 0
	s_add_i32 s12, s12, 2
	s_cmp_lt_u32 s12, 39
	s_waitcnt vmcnt(13)
	ds_write_b128 v111, v[122:125] offset:9216
	s_waitcnt lgkmcnt(3)
	v_mfma_f32_32x32x16_bf16 v[32:47], v[196:199], v[204:207], v[32:47]
	ds_read_b128 v[212:215], v109 offset:18496
	ds_read_b128 v[216:219], v110 offset:55360
	s_waitcnt lgkmcnt(3)
	v_mfma_f32_32x32x16_bf16 v[16:31], v[208:211], v[200:203], v[16:31]
	ds_read_b128 v[220:223], v110 offset:59968
	s_waitcnt vmcnt(12)
	ds_write_b128 v111, v[126:129] offset:13824
	v_mfma_f32_32x32x16_bf16 v[0:15], v[208:211], v[204:207], v[0:15]
	ds_read_b128 v[224:227], v109 offset:23104
	s_waitcnt lgkmcnt(3)
	v_mfma_f32_32x32x16_bf16 v[48:63], v[212:215], v[216:219], v[48:63]
	s_waitcnt vmcnt(11)
	ds_write_b128 v111, v[130:133] offset:36864
	s_waitcnt lgkmcnt(3)
	v_mfma_f32_32x32x16_bf16 v[32:47], v[212:215], v[220:223], v[32:47]
	ds_read_b128 v[228:231], v109 offset:18528
	ds_read_b128 v[146:149], v110 offset:55392
	s_waitcnt lgkmcnt(3)
	v_mfma_f32_32x32x16_bf16 v[16:31], v[224:227], v[216:219], v[16:31]
	ds_read_b128 v[150:153], v110 offset:60000
	s_waitcnt vmcnt(10)
	ds_write_b128 v111, v[134:137] offset:41472
	v_mfma_f32_32x32x16_bf16 v[0:15], v[224:227], v[220:223], v[0:15]
	ds_read_b128 v[154:157], v109 offset:23136
	s_waitcnt lgkmcnt(3)
	v_mfma_f32_32x32x16_bf16 v[48:63], v[228:231], v[146:149], v[48:63]
	s_waitcnt vmcnt(9)
	ds_write_b128 v111, v[138:141] offset:46080
	s_waitcnt lgkmcnt(3)
	v_mfma_f32_32x32x16_bf16 v[32:47], v[228:231], v[150:153], v[32:47]
	s_waitcnt lgkmcnt(1)
	v_mfma_f32_32x32x16_bf16 v[16:31], v[154:157], v[146:149], v[16:31]
	s_waitcnt vmcnt(8)
	ds_write_b128 v111, v[142:145] offset:50688
	v_mfma_f32_32x32x16_bf16 v[0:15], v[154:157], v[150:153], v[0:15]
	s_setprio 0
	s_waitcnt lgkmcnt(0)
	s_barrier
	s_cbranch_scc1 .LBB0_4051
	s_setprio 1
	ds_read_b128 v[104:107], v109
	ds_read_b128 v[114:117], v110 offset:36864
	ds_read_b128 v[118:121], v110 offset:41472
	ds_read_b128 v[192:195], v109 offset:4608
	s_waitcnt lgkmcnt(2)
	v_mfma_f32_32x32x16_bf16 v[48:63], v[104:107], v[114:117], v[48:63]
	s_waitcnt vmcnt(7)
	ds_write_b128 v111, v[68:71] offset:18432
	s_waitcnt lgkmcnt(2)
	v_mfma_f32_32x32x16_bf16 v[32:47], v[104:107], v[118:121], v[32:47]
	ds_read_b128 v[196:199], v109 offset:32
	ds_read_b128 v[200:203], v110 offset:36896
	s_waitcnt lgkmcnt(3)
	v_mfma_f32_32x32x16_bf16 v[16:31], v[192:195], v[114:117], v[16:31]
	ds_read_b128 v[204:207], v110 offset:41504
	s_waitcnt vmcnt(6)
	ds_write_b128 v111, v[84:87] offset:23040
	v_mfma_f32_32x32x16_bf16 v[0:15], v[192:195], v[118:121], v[0:15]
	ds_read_b128 v[208:211], v109 offset:4640
	s_waitcnt lgkmcnt(3)
	v_mfma_f32_32x32x16_bf16 v[48:63], v[196:199], v[200:203], v[48:63]
	s_waitcnt vmcnt(5)
	ds_write_b128 v111, v[88:91] offset:27648
	s_waitcnt lgkmcnt(3)
	v_mfma_f32_32x32x16_bf16 v[32:47], v[196:199], v[204:207], v[32:47]
	ds_read_b128 v[212:215], v109 offset:64
	ds_read_b128 v[216:219], v110 offset:36928
	s_waitcnt lgkmcnt(3)
	v_mfma_f32_32x32x16_bf16 v[16:31], v[208:211], v[200:203], v[16:31]
	ds_read_b128 v[220:223], v110 offset:41536
	s_waitcnt vmcnt(4)
	ds_write_b128 v111, v[92:95] offset:32256
	v_mfma_f32_32x32x16_bf16 v[0:15], v[208:211], v[204:207], v[0:15]
	ds_read_b128 v[224:227], v109 offset:4672
	s_waitcnt lgkmcnt(3)
	v_mfma_f32_32x32x16_bf16 v[48:63], v[212:215], v[216:219], v[48:63]
	s_waitcnt vmcnt(3)
	ds_write_b128 v111, v[64:67] offset:55296
	s_waitcnt lgkmcnt(3)
	v_mfma_f32_32x32x16_bf16 v[32:47], v[212:215], v[220:223], v[32:47]
	ds_read_b128 v[228:231], v109 offset:96
	ds_read_b128 v[104:107], v110 offset:41568
	s_waitcnt lgkmcnt(3)
	v_mfma_f32_32x32x16_bf16 v[16:31], v[224:227], v[216:219], v[16:31]
	ds_read_b128 v[114:117], v110 offset:36960
	ds_read_b128 v[118:121], v109 offset:4704
	s_waitcnt vmcnt(2)
	ds_write_b128 v111, v[72:75] offset:59904
	v_mfma_f32_32x32x16_bf16 v[0:15], v[224:227], v[220:223], v[0:15]
	s_waitcnt lgkmcnt(3)
	v_mfma_f32_32x32x16_bf16 v[32:47], v[228:231], v[104:107], v[32:47]
	s_waitcnt vmcnt(1)
	ds_write_b128 v111, v[76:79] offset:64512
	s_waitcnt lgkmcnt(2)
	v_mfma_f32_32x32x16_bf16 v[16:31], v[118:121], v[114:117], v[16:31]
	v_mfma_f32_32x32x16_bf16 v[0:15], v[118:121], v[104:107], v[0:15]
	s_waitcnt vmcnt(0)
	ds_write_b128 v112, v[80:83] offset:13824
	v_mfma_f32_32x32x16_bf16 v[48:63], v[228:231], v[114:117], v[48:63]
	s_setprio 0
	s_waitcnt lgkmcnt(0)
	s_barrier
	s_setprio 1
	ds_read_b128 v[64:67], v109 offset:18432
	ds_read_b128 v[68:71], v110 offset:55296
	ds_read_b128 v[72:75], v110 offset:59904
	ds_read_b128 v[192:195], v109 offset:23040
	s_waitcnt lgkmcnt(2)
	v_mfma_f32_32x32x16_bf16 v[48:63], v[64:67], v[68:71], v[48:63]
	s_waitcnt lgkmcnt(1)
	v_mfma_f32_32x32x16_bf16 v[32:47], v[64:67], v[72:75], v[32:47]
	ds_read_b128 v[196:199], v109 offset:18464
	ds_read_b128 v[200:203], v110 offset:55328
	s_waitcnt lgkmcnt(2)
	v_mfma_f32_32x32x16_bf16 v[16:31], v[192:195], v[68:71], v[16:31]
	ds_read_b128 v[204:207], v110 offset:59936
	v_mfma_f32_32x32x16_bf16 v[0:15], v[192:195], v[72:75], v[0:15]
	ds_read_b128 v[208:211], v109 offset:23072
	s_waitcnt lgkmcnt(2)
	v_mfma_f32_32x32x16_bf16 v[48:63], v[196:199], v[200:203], v[48:63]
	s_waitcnt lgkmcnt(1)
	v_mfma_f32_32x32x16_bf16 v[32:47], v[196:199], v[204:207], v[32:47]
	ds_read_b128 v[212:215], v109 offset:18496
	ds_read_b128 v[216:219], v110 offset:55360
	s_waitcnt lgkmcnt(2)
	v_mfma_f32_32x32x16_bf16 v[16:31], v[208:211], v[200:203], v[16:31]
	ds_read_b128 v[220:223], v110 offset:59968
	v_mfma_f32_32x32x16_bf16 v[0:15], v[208:211], v[204:207], v[0:15]
	ds_read_b128 v[224:227], v109 offset:23104
	s_waitcnt lgkmcnt(2)
	v_mfma_f32_32x32x16_bf16 v[48:63], v[212:215], v[216:219], v[48:63]
	s_waitcnt lgkmcnt(1)
	v_mfma_f32_32x32x16_bf16 v[32:47], v[212:215], v[220:223], v[32:47]
	ds_read_b128 v[228:231], v109 offset:18528
	ds_read_b128 v[64:67], v110 offset:60000
	s_waitcnt lgkmcnt(2)
	v_mfma_f32_32x32x16_bf16 v[16:31], v[224:227], v[216:219], v[16:31]
	ds_read_b128 v[68:71], v110 offset:55392
	ds_read_b128 v[72:75], v109 offset:23136
	v_mfma_f32_32x32x16_bf16 v[0:15], v[224:227], v[220:223], v[0:15]
	s_waitcnt lgkmcnt(2)
	v_mfma_f32_32x32x16_bf16 v[32:47], v[228:231], v[64:67], v[32:47]
	s_waitcnt lgkmcnt(0)
	v_mfma_f32_32x32x16_bf16 v[16:31], v[72:75], v[68:71], v[16:31]
	v_mfma_f32_32x32x16_bf16 v[0:15], v[72:75], v[64:67], v[0:15]
	v_mfma_f32_32x32x16_bf16 v[48:63], v[228:231], v[68:71], v[48:63]
	s_setprio 0
	s_addk_i32 s0, 0xf000
	s_lshr_b32 s12, s0, 10
	s_mulk_i32 s12, 0x1800
	s_add_i32 s12, s12, 0x9000
	s_and_b64 s[66:67], s[4:5], exec
	s_cselect_b32 s12, 0x7800, s12
	v_mov_b32_e32 v68, v234
	s_barrier
	s_lshl_b64 s[66:67], s[12:13], 2
	s_add_u32 s66, s30, s66
	v_and_b32_e32 v69, 0x5f, v68
	v_or_b32_e32 v64, s27, v69
	s_addc_u32 s67, s31, s67
	v_ashrrev_i32_e32 v65, 31, v64
	v_lshl_add_u64 v[64:65], v[64:65], 2, s[66:67]
	v_lshl_add_u64 v[66:67], v[64:65], 0, s[16:17]
	v_add_co_u32_e32 v64, vcc, s56, v64
	v_lshlrev_b32_e32 v69, 2, v69
	s_nop 0
	v_addc_co_u32_e32 v65, vcc, 0, v65, vcc
	global_load_dword v64, v[64:65], off
	s_nop 0
	global_load_dword v65, v[66:67], off offset:128
	v_lshrrev_b32_e32 v67, 3, v68
	v_lshrrev_b32_e32 v66, 1, v68
	v_and_b32_e32 v67, 4, v67
	v_and_or_b32 v66, v66, s47, v67
	v_mul_lo_u32 v66, v66, s57
	v_add3_u32 v66, 32, v69, v66
	v_add_u32_e32 v67, 0x400, v66
	v_add_u32_e32 v69, 0x1000, v66
	v_add_u32_e32 v70, 0x1400, v66
	v_add_u32_e32 v71, 0x2000, v66
	v_add_u32_e32 v72, 0x2400, v66
	v_add_u32_e32 v73, 0x3000, v66
	v_add_u32_e32 v74, 0x3200, v66
	v_add_u32_e32 v75, 0x3400, v66
	v_add_u32_e32 v76, 0x3600, v66
	v_add_u32_e32 v77, 0x4000, v66
	s_lshl_b32 s1, s1, 19
	s_add_u32 s12, s19, s1
	s_mov_b32 s1, s13
	s_waitcnt vmcnt(1)
	v_mul_f32_e32 v48, v48, v64
	s_waitcnt vmcnt(0)
	v_mul_f32_e32 v32, v32, v65
	v_mul_f32_e32 v16, v16, v64
	v_mul_f32_e32 v0, v0, v65
	v_mul_f32_e32 v49, v49, v64
	v_mul_f32_e32 v33, v33, v65
	v_mul_f32_e32 v50, v50, v64
	v_mul_f32_e32 v34, v34, v65
	v_mul_f32_e32 v51, v51, v64
	v_mul_f32_e32 v35, v35, v65
	v_mul_f32_e32 v52, v52, v64
	v_mul_f32_e32 v36, v36, v65
	v_mul_f32_e32 v53, v53, v64
	v_mul_f32_e32 v37, v37, v65
	v_mul_f32_e32 v54, v54, v64
	v_mul_f32_e32 v38, v38, v65
	v_mul_f32_e32 v55, v55, v64
	v_mul_f32_e32 v39, v39, v65
	v_mul_f32_e32 v56, v56, v64
	v_mul_f32_e32 v40, v40, v65
	v_mul_f32_e32 v57, v57, v64
	v_mul_f32_e32 v41, v41, v65
	v_mul_f32_e32 v58, v58, v64
	v_mul_f32_e32 v42, v42, v65
	v_mul_f32_e32 v59, v59, v64
	v_mul_f32_e32 v43, v43, v65
	v_mul_f32_e32 v60, v60, v64
	v_mul_f32_e32 v44, v44, v65
	v_mul_f32_e32 v61, v61, v64
	v_mul_f32_e32 v45, v45, v65
	v_mul_f32_e32 v62, v62, v64
	v_mul_f32_e32 v46, v46, v65
	v_mul_f32_e32 v63, v63, v64
	v_mul_f32_e32 v47, v47, v65
	ds_write2_b32 v66, v48, v32 offset1:32
	ds_write2_b32 v66, v49, v33 offset0:132 offset1:164
	ds_write2_b32 v67, v50, v34 offset0:8 offset1:40
	ds_write2_b32 v67, v51, v35 offset0:140 offset1:172
	ds_write2_b32 v69, v52, v36 offset0:32 offset1:64
	ds_write2_b32 v69, v53, v37 offset0:164 offset1:196
	ds_write2_b32 v70, v54, v38 offset0:40 offset1:72
	ds_write2_b32 v70, v55, v39 offset0:172 offset1:204
	ds_write2_b32 v71, v56, v40 offset0:64 offset1:96
	ds_write2_b32 v71, v57, v41 offset0:196 offset1:228
	ds_write2_b32 v72, v58, v42 offset0:72 offset1:104
	ds_write2_b32 v72, v59, v43 offset0:204 offset1:236
	ds_write2_b32 v73, v60, v44 offset0:96 offset1:128
	ds_write2_b32 v74, v61, v45 offset0:100 offset1:132
	ds_write2_b32 v75, v62, v46 offset0:104 offset1:136
	ds_write2_b32 v76, v63, v47 offset0:108 offset1:140
	ds_write2_b32 v77, v16, v0 offset0:128 offset1:160
	v_mul_f32_e32 v0, v17, v64
	v_mul_f32_e32 v1, v1, v65
	v_add_u32_e32 v16, 0x4400, v66
	ds_write2_b32 v16, v0, v1 offset0:4 offset1:36
	v_mul_f32_e32 v0, v18, v64
	v_mul_f32_e32 v1, v2, v65
	ds_write2_b32 v16, v0, v1 offset0:136 offset1:168
	v_mul_f32_e32 v0, v19, v64
	v_mul_f32_e32 v1, v3, v65
	v_add_u32_e32 v2, 0x4800, v66
	ds_write2_b32 v2, v0, v1 offset0:12 offset1:44
	v_mul_f32_e32 v0, v20, v64
	v_mul_f32_e32 v1, v4, v65
	v_add_u32_e32 v2, 0x5000, v66
	ds_write2_b32 v2, v0, v1 offset0:160 offset1:192
	v_mul_f32_e32 v0, v21, v64
	v_mul_f32_e32 v1, v5, v65
	v_add_u32_e32 v2, 0x5400, v66
	ds_write2_b32 v2, v0, v1 offset0:36 offset1:68
	v_mul_f32_e32 v0, v22, v64
	v_mul_f32_e32 v1, v6, v65
	ds_write2_b32 v2, v0, v1 offset0:168 offset1:200
	v_mul_f32_e32 v0, v23, v64
	v_mul_f32_e32 v1, v7, v65
	v_add_u32_e32 v2, 0x5800, v66
	ds_write2_b32 v2, v0, v1 offset0:44 offset1:76
	v_mul_f32_e32 v0, v24, v64
	v_mul_f32_e32 v1, v8, v65
	v_add_u32_e32 v2, 0x6000, v66
	ds_write2_b32 v2, v0, v1 offset0:192 offset1:224
	v_mul_f32_e32 v0, v25, v64
	v_mul_f32_e32 v1, v9, v65
	v_add_u32_e32 v2, 0x6400, v66
	ds_write2_b32 v2, v0, v1 offset0:68 offset1:100
	v_mul_f32_e32 v0, v26, v64
	v_mul_f32_e32 v1, v10, v65
	ds_write2_b32 v2, v0, v1 offset0:200 offset1:232
	v_mul_f32_e32 v0, v27, v64
	v_mul_f32_e32 v1, v11, v65
	v_add_u32_e32 v2, 0x6800, v66
	ds_write2_b32 v2, v0, v1 offset0:76 offset1:108
	v_mul_f32_e32 v0, v28, v64
	v_mul_f32_e32 v1, v12, v65
	v_add_u32_e32 v2, 0x7200, v66
	ds_write2_b32 v2, v0, v1 offset0:96 offset1:128
	v_mul_f32_e32 v0, v29, v64
	v_mul_f32_e32 v1, v13, v65
	v_add_u32_e32 v2, 0x7400, v66
	ds_write2_b32 v2, v0, v1 offset0:100 offset1:132
	v_mul_f32_e32 v0, v30, v64
	v_mul_f32_e32 v1, v14, v65
	v_add_u32_e32 v2, 0x7600, v66
	v_and_b32_e32 v12, 31, v68
	ds_write2_b32 v2, v0, v1 offset0:104 offset1:136
	v_mul_f32_e32 v0, v31, v64
	v_mul_f32_e32 v1, v15, v65
	v_add_u32_e32 v2, 0x7800, v66
	v_lshlrev_b32_e32 v8, 2, v12
	ds_write2_b32 v2, v0, v1 offset0:108 offset1:140
	v_or_b32_e32 v0, s27, v8
	v_ashrrev_i32_e32 v1, 31, v0
	v_lshlrev_b64 v[0:1], 2, v[0:1]
	v_lshl_add_u64 v[2:3], s[6:7], 0, v[0:1]
	v_lshl_add_u64 v[4:5], s[8:9], 0, v[0:1]
	s_waitcnt lgkmcnt(0)
	s_barrier
	global_load_dwordx4 v[0:3], v[2:3], off
	s_nop 0
	global_load_dwordx4 v[4:7], v[4:5], off
	v_and_b32_e32 v9, 64, v108
	v_add_u32_e32 v9, 64, v9
	v_xor_b32_e32 v10, 1, v108
	v_cmp_lt_i32_e32 vcc, v10, v9
	s_addc_u32 s27, s21, 0
	s_lshl_b64 s[0:1], s[0:1], 12
	v_cndmask_b32_e32 v10, v108, v10, vcc
	v_lshlrev_b32_e32 v32, 2, v10
	v_xor_b32_e32 v10, 2, v108
	v_cmp_lt_i32_e32 vcc, v10, v9
	s_add_u32 s63, s33, s0
	s_addc_u32 s65, s34, s1
	v_cndmask_b32_e32 v10, v108, v10, vcc
	v_lshlrev_b32_e32 v33, 2, v10
	v_xor_b32_e32 v10, 4, v108
	v_cmp_lt_i32_e32 vcc, v10, v9
	s_and_b64 s[0:1], s[4:5], exec
	v_ashrrev_i32_e32 v22, 5, v68
	v_cndmask_b32_e32 v10, v108, v10, vcc
	v_lshlrev_b32_e32 v34, 2, v10
	v_xor_b32_e32 v10, 8, v108
	s_cselect_b32 s67, s27, s65
	s_cselect_b32 s66, s12, s63
	v_cmp_lt_i32_e32 vcc, v10, v9
	s_add_i32 s12, s26, s39
	v_add_u32_e32 v16, s12, v22
	v_cndmask_b32_e32 v10, v108, v10, vcc
	s_add_i32 s12, s26, s40
	s_add_i32 s26, s26, s41
	v_lshlrev_b32_e32 v35, 2, v10
	v_xor_b32_e32 v10, 16, v108
	v_add_u32_e32 v20, s12, v22
	v_add_u32_e32 v24, s26, v22
	v_cmp_eq_u32_e64 s[0:1], 0, v12
	v_cmp_lt_i32_e32 vcc, v10, v9
	v_ashrrev_i32_e32 v23, 31, v22
	v_mul_lo_u32 v13, v22, s57
	v_lshlrev_b32_e32 v12, 4, v12
	v_add_u32_e32 v26, s25, v22
	v_ashrrev_i32_e32 v17, 31, v16
	v_ashrrev_i32_e32 v21, 31, v20
	v_ashrrev_i32_e32 v25, 31, v24
	v_cndmask_b32_e32 v9, v108, v10, vcc
	v_add_u32_e32 v8, s24, v8
	v_lshlrev_b64 v[10:11], 12, v[22:23]
	v_add3_u32 v37, v13, v12, 32
	v_lshlrev_b32_e32 v12, 1, v26
	v_lshlrev_b64 v[14:15], 12, v[16:17]
	v_lshlrev_b32_e32 v16, 1, v16
	v_lshlrev_b64 v[18:19], 12, v[20:21]
	v_lshlrev_b32_e32 v20, 1, v20
	v_lshlrev_b64 v[22:23], 12, v[24:25]
	v_lshlrev_b32_e32 v24, 1, v24
	v_ashrrev_i32_e32 v27, 31, v26
	v_lshlrev_b32_e32 v36, 2, v9
	v_ashrrev_i32_e32 v9, 31, v8
	v_ashrrev_i32_e32 v13, 31, v12
	v_ashrrev_i32_e32 v17, 31, v16
	v_ashrrev_i32_e32 v21, 31, v20
	v_ashrrev_i32_e32 v25, 31, v24
	v_lshlrev_b64 v[26:27], 12, v[26:27]
	v_lshlrev_b64 v[8:9], 2, v[8:9]
	v_lshl_add_u64 v[10:11], s[66:67], 0, v[10:11]
	v_lshl_add_u64 v[12:13], v[12:13], 2, s[30:31]
	v_lshl_add_u64 v[14:15], s[28:29], 0, v[14:15]
	v_lshl_add_u64 v[16:17], v[16:17], 2, s[30:31]
	v_lshl_add_u64 v[18:19], s[28:29], 0, v[18:19]
	v_lshl_add_u64 v[20:21], v[20:21], 2, s[30:31]
	v_lshl_add_u64 v[22:23], s[28:29], 0, v[22:23]
	v_lshl_add_u64 v[24:25], v[24:25], 2, s[30:31]
	v_lshl_add_u64 v[26:27], s[10:11], 0, v[26:27]
	s_mov_b64 s[24:25], 0
	s_branch .LBB0_4054
